# ABI and SGI epilogues: UG / Z tile stores issued with nt (consumers are cross-XCD, read once), test on top of v59
# speedup vs baseline: 1.0362x; 1.0362x over previous
; __device__ __forceinline__ f32x2 gelu_pk(f32x2 v) {
;     const f32x2 av = __builtin_elementwise_abs(v), d = av * 0.2316418882f + 1.0f;
;     f32x2 t; t.x = __builtin_amdgcn_rcpf(d.x); t.y = __builtin_amdgcn_rcpf(d.y);
;     f32x2 q = t * 0.5307027145f + (-0.7265760135f); q = q * t + 0.7107068705f; q = q * t + (-0.142248368f); q = q * t + 0.127414796f; q = q * t;
;     const f32x2 s = (v * v) * (-0.72134752044f);
;     f32x2 e; e.x = __builtin_amdgcn_exp2f(s.x); e.y = __builtin_amdgcn_exp2f(s.y);
;     const f32x2 m = v * (q * e), r = v - m;
;     f32x2 o; o.x = v.x < 0.f ? m.x : r.x; o.y = v.y < 0.f ? m.y : r.y; return o;
;     __device__ __forceinline__ void operator()(const f32x4 (&acc)[2][2][4][2], const Unit& u, int ui, int wr, int wc, int fr, int fq) const {
;     ...
;         const int row0 = u.pm * BM + wr * 64 + fr, col0 = u.pn * BM + wc * 32 + 8 * fq;
;         float rs[2][4];
; #pragma unroll
;         for (int ai = 0; ai < 2; ++ai)
; #pragma unroll
;             for (int m = 0; m < 4; ++m) rs[ai][m] = row_rstd(lds, ui, ai * HALF + wr * 64 + m * 16 + fr);
; #pragma unroll
;         for (int ai = 0; ai < 2; ++ai)
; #pragma unroll
;             for (int m = 0; m < 4; ++m) { const float r = rs[ai][m]; const int row = row0 + ai * HALF + m * 16; bf16_t* rowp = Z + (size_t)row * 2048 + col0; float s1 = 0.f, s2 = 0.f;
; #pragma unroll
;                 for (int bj = 0; bj < 2; ++bj) { const f32x4 v0 = acc[ai][bj][m][0] * r, v1 = acc[ai][bj][m][1] * r;
;                     const f32x2 a = gelu_pk((f32x2){v0[0], v0[1]}), b = gelu_pk((f32x2){v0[2], v0[3]}), c = gelu_pk((f32x2){v1[0], v1[1]}), d = gelu_pk((f32x2){v1[2], v1[3]});
.LBB0_752:
	v_mov_b32_e32 v140, v176
	v_mov_b32_e32 v141, v177
	s_lshl_b32 s0, s10, 8
	v_add_u32_e32 v142, s45, v140
	v_lshl_add_u32 v140, s11, 8, v142
	v_lshlrev_b32_e32 v142, 2, v142
	v_lshl_add_u32 v142, s12, 10, v142
	v_add_u32_e32 v142, 0x20400, v142
	ds_read2_b32 v[168:169], v142 offset1:16
	ds_read2_b32 v[166:167], v142 offset0:32 offset1:48
	ds_read2_b32 v[164:165], v142 offset0:128 offset1:144
	ds_read2_b32 v[142:143], v142 offset0:160 offset1:176
	s_mov_b32 s56, 0x3e6d3388
	s_waitcnt lgkmcnt(0)
	v_pk_mul_f32 v[172:173], v[124:125], v[168:169] op_sel_hi:[1,0]
	s_or_b32 s0, s0, s47
	v_and_b32_e32 v125, 0x7fffffff, v173
	v_and_b32_e32 v124, 0x7fffffff, v172
	v_pk_fma_f32 v[124:125], v[124:125], s[56:57], 1.0 op_sel_hi:[1,0,0]
	s_cmp_gt_i32 s10, 3
	v_rcp_f32_e32 v174, v124
	v_rcp_f32_e32 v175, v125
	v_lshl_add_u32 v162, v141, 3, s0
	s_cselect_b64 s[0:1], -1, 0
	s_lshl_b32 s2, s10, 2
	s_add_i32 s38, s2, -16
	s_mov_b32 s2, 0xbf3a00e3
	v_mov_b64_e32 v[124:125], s[2:3]
	s_mov_b32 s2, 0x3f07dc22
	v_pk_mul_f32 v[182:183], v[120:121], v[168:169] op_sel_hi:[1,0]
	v_pk_fma_f32 v[120:121], v[174:175], s[2:3], v[124:125] op_sel_hi:[1,0,0]
	s_mov_b32 s4, 0x3f35f0e3
	v_pk_fma_f32 v[120:121], v[174:175], v[120:121], s[4:5] op_sel_hi:[1,1,0]
	s_mov_b32 s12, 0xbe11a98e
	v_pk_fma_f32 v[120:121], v[174:175], v[120:121], s[12:13] op_sel_hi:[1,1,0]
	s_mov_b32 s88, 0x3e027906
	v_pk_fma_f32 v[120:121], v[174:175], v[120:121], s[88:89] op_sel_hi:[1,1,0]
	v_pk_mul_f32 v[126:127], v[126:127], v[168:169] op_sel_hi:[1,0]
	v_pk_mul_f32 v[120:121], v[174:175], v[120:121]
	v_pk_mul_f32 v[174:175], v[172:173], v[172:173]
	s_mov_b32 s86, 0xbf38aa3b
	v_pk_mul_f32 v[174:175], v[174:175], s[86:87] op_sel_hi:[1,0]
	v_and_b32_e32 v181, 0x7fffffff, v127
	v_and_b32_e32 v180, 0x7fffffff, v126
	v_exp_f32_e32 v174, v174
	v_exp_f32_e32 v175, v175
	v_pk_fma_f32 v[180:181], v[180:181], s[56:57], 1.0 op_sel_hi:[1,0,0]
	v_pk_mul_f32 v[184:185], v[122:123], v[168:169] op_sel_hi:[1,0]
	v_rcp_f32_e32 v180, v180
	v_rcp_f32_e32 v181, v181
	v_pk_mul_f32 v[122:123], v[126:127], v[126:127]
	v_pk_mul_f32 v[120:121], v[174:175], v[120:121]
	v_pk_mul_f32 v[122:123], v[122:123], s[86:87] op_sel_hi:[1,0]
	v_pk_mul_f32 v[174:175], v[172:173], v[120:121]
	v_pk_fma_f32 v[186:187], v[172:173], v[120:121], v[172:173] neg_lo:[1,0,0] neg_hi:[1,0,0]
	v_pk_fma_f32 v[120:121], v[180:181], s[2:3], v[124:125] op_sel_hi:[1,0,0]
	v_exp_f32_e32 v122, v122
	v_pk_fma_f32 v[120:121], v[180:181], v[120:121], s[4:5] op_sel_hi:[1,1,0]
	v_exp_f32_e32 v123, v123
	v_pk_fma_f32 v[120:121], v[180:181], v[120:121], s[12:13] op_sel_hi:[1,1,0]
	v_and_b32_e32 v189, 0x7fffffff, v183
	v_pk_fma_f32 v[120:121], v[180:181], v[120:121], s[88:89] op_sel_hi:[1,1,0]
	v_and_b32_e32 v188, 0x7fffffff, v182
	v_pk_mul_f32 v[120:121], v[180:181], v[120:121]
	v_cmp_gt_f32_e32 vcc, 0, v126
	v_pk_mul_f32 v[120:121], v[122:123], v[120:121]
	v_pk_fma_f32 v[188:189], v[188:189], s[56:57], 1.0 op_sel_hi:[1,0,0]
	v_pk_mul_f32 v[122:123], v[126:127], v[120:121]
	v_pk_fma_f32 v[180:181], v[126:127], v[120:121], v[126:127] neg_lo:[1,0,0] neg_hi:[1,0,0]
	v_rcp_f32_e32 v188, v188
	v_cndmask_b32_e32 v121, v180, v122, vcc
	v_cmp_gt_f32_e32 vcc, 0, v172
	v_rcp_f32_e32 v189, v189
	v_and_b32_e32 v180, 0x7fffffff, v184
	v_cndmask_b32_e32 v120, v186, v174, vcc
	v_cmp_gt_f32_e32 vcc, 0, v127
	v_pk_fma_f32 v[126:127], v[188:189], s[2:3], v[124:125] op_sel_hi:[1,0,0]
	v_pk_mul_f32 v[116:117], v[116:117], v[168:169] op_sel_hi:[1,0]
	v_cndmask_b32_e32 v123, v181, v123, vcc
	v_cmp_gt_f32_e32 vcc, 0, v173
	v_and_b32_e32 v181, 0x7fffffff, v185
	v_pk_fma_f32 v[126:127], v[188:189], v[126:127], s[4:5] op_sel_hi:[1,1,0]
	v_cndmask_b32_e32 v122, v187, v175, vcc
	v_pk_mul_f32 v[174:175], v[182:183], v[182:183]
	v_pk_fma_f32 v[180:181], v[180:181], s[56:57], 1.0 op_sel_hi:[1,0,0]
	v_pk_mul_f32 v[174:175], v[174:175], s[86:87] op_sel_hi:[1,0]
	v_pk_fma_f32 v[126:127], v[188:189], v[126:127], s[12:13] op_sel_hi:[1,1,0]
	v_exp_f32_e32 v174, v174
	v_exp_f32_e32 v175, v175
	v_rcp_f32_e32 v180, v180
	v_rcp_f32_e32 v181, v181
	v_pk_fma_f32 v[126:127], v[188:189], v[126:127], s[88:89] op_sel_hi:[1,1,0]
	v_pk_mul_f32 v[172:173], v[184:185], v[184:185]
	v_pk_mul_f32 v[126:127], v[188:189], v[126:127]
	v_pk_mul_f32 v[172:173], v[172:173], s[86:87] op_sel_hi:[1,0]
	v_pk_mul_f32 v[126:127], v[174:175], v[126:127]
	v_exp_f32_e32 v172, v172
	v_pk_mul_f32 v[174:175], v[182:183], v[126:127]
	v_pk_fma_f32 v[186:187], v[182:183], v[126:127], v[182:183] neg_lo:[1,0,0] neg_hi:[1,0,0]
	v_pk_fma_f32 v[126:127], v[180:181], s[2:3], v[124:125] op_sel_hi:[1,0,0]
	v_exp_f32_e32 v173, v173
	v_pk_fma_f32 v[126:127], v[180:181], v[126:127], s[4:5] op_sel_hi:[1,1,0]
	v_pk_mul_f32 v[210:211], v[112:113], v[168:169] op_sel_hi:[1,0]
	v_pk_fma_f32 v[126:127], v[180:181], v[126:127], s[12:13] op_sel_hi:[1,1,0]
	v_pk_mul_f32 v[118:119], v[118:119], v[168:169] op_sel_hi:[1,0]
	v_pk_fma_f32 v[126:127], v[180:181], v[126:127], s[88:89] op_sel_hi:[1,1,0]
	v_and_b32_e32 v213, 0x7fffffff, v119
	v_pk_mul_f32 v[126:127], v[180:181], v[126:127]
	v_and_b32_e32 v212, 0x7fffffff, v118
	v_pk_mul_f32 v[126:127], v[172:173], v[126:127]
	v_and_b32_e32 v173, 0x7fffffff, v117
	v_and_b32_e32 v172, 0x7fffffff, v116
	v_pk_fma_f32 v[172:173], v[172:173], s[56:57], 1.0 op_sel_hi:[1,0,0]
	v_pk_fma_f32 v[212:213], v[212:213], s[56:57], 1.0 op_sel_hi:[1,0,0]
	v_rcp_f32_e32 v172, v172
	v_rcp_f32_e32 v173, v173
	v_rcp_f32_e32 v212, v212
	v_rcp_f32_e32 v213, v213
	v_pk_mul_f32 v[208:209], v[114:115], v[168:169] op_sel_hi:[1,0]
	v_pk_fma_f32 v[112:113], v[172:173], s[2:3], v[124:125] op_sel_hi:[1,0,0]
	v_pk_mul_f32 v[114:115], v[118:119], v[118:119]
; __device__ __forceinline__ u32x4 pack8(const f32x4& a, const f32x4& b) { u32x4 w; w.x = cvt_pk_bf16(a[0], a[1]); w.y = cvt_pk_bf16(a[2], a[3]); w.z = cvt_pk_bf16(b[0], b[1]); w.w = cvt_pk_bf16(b[2], b[3]); return w; }
; __device__ __forceinline__ f32x2 gelu_pk(f32x2 v) {
;     const f32x2 av = __builtin_elementwise_abs(v), d = av * 0.2316418882f + 1.0f;
;     f32x2 t; t.x = __builtin_amdgcn_rcpf(d.x); t.y = __builtin_amdgcn_rcpf(d.y);
;     f32x2 q = t * 0.5307027145f + (-0.7265760135f); q = q * t + 0.7107068705f; q = q * t + (-0.142248368f); q = q * t + 0.127414796f; q = q * t;
;     const f32x2 s = (v * v) * (-0.72134752044f);
;     f32x2 e; e.x = __builtin_amdgcn_exp2f(s.x); e.y = __builtin_amdgcn_exp2f(s.y);
;     const f32x2 m = v * (q * e), r = v - m;
;     f32x2 o; o.x = v.x < 0.f ? m.x : r.x; o.y = v.y < 0.f ? m.y : r.y; return o;
;     __device__ __forceinline__ void operator()(const f32x4 (&acc)[2][2][4][2], const Unit& u, int ui, int wr, int wc, int fr, int fq) const {
;     ...
;             for (int m = 0; m < 4; ++m) { const float r = rs[ai][m]; const int row = row0 + ai * HALF + m * 16; bf16_t* rowp = Z + (size_t)row * 2048 + col0; float s1 = 0.f, s2 = 0.f;
; #pragma unroll
;                 for (int bj = 0; bj < 2; ++bj) { const f32x4 v0 = acc[ai][bj][m][0] * r, v1 = acc[ai][bj][m][1] * r;
;                     const f32x2 a = gelu_pk((f32x2){v0[0], v0[1]}), b = gelu_pk((f32x2){v0[2], v0[3]}), c = gelu_pk((f32x2){v1[0], v1[1]}), d = gelu_pk((f32x2){v1[2], v1[3]});
;                     const f32x4 z0 = (f32x4){a.x, a.y, b.x, b.y}, z1 = (f32x4){c.x, c.y, d.x, d.y};
;                     *(u32x4*)(rowp + bj * HALF) = pack8(z0, z1);
	v_pk_fma_f32 v[112:113], v[172:173], v[112:113], s[4:5] op_sel_hi:[1,1,0]
	v_pk_mul_f32 v[114:115], v[114:115], s[86:87] op_sel_hi:[1,0]
	v_pk_fma_f32 v[112:113], v[172:173], v[112:113], s[12:13] op_sel_hi:[1,1,0]
	v_exp_f32_e32 v114, v114
	v_pk_fma_f32 v[112:113], v[172:173], v[112:113], s[88:89] op_sel_hi:[1,1,0]
	v_exp_f32_e32 v115, v115
	v_pk_mul_f32 v[112:113], v[172:173], v[112:113]
	v_pk_mul_f32 v[172:173], v[116:117], v[116:117]
	v_and_b32_e32 v217, 0x7fffffff, v211
	v_pk_mul_f32 v[172:173], v[172:173], s[86:87] op_sel_hi:[1,0]
	v_and_b32_e32 v216, 0x7fffffff, v210
	v_exp_f32_e32 v172, v172
	v_exp_f32_e32 v173, v173
	v_pk_fma_f32 v[216:217], v[216:217], s[56:57], 1.0 op_sel_hi:[1,0,0]
	v_pk_mul_f32 v[188:189], v[184:185], v[126:127]
	v_pk_fma_f32 v[190:191], v[184:185], v[126:127], v[184:185] neg_lo:[1,0,0] neg_hi:[1,0,0]
	v_pk_mul_f32 v[112:113], v[172:173], v[112:113]
	v_cmp_gt_f32_e32 vcc, 0, v185
	v_pk_mul_f32 v[172:173], v[116:117], v[112:113]
	v_pk_fma_f32 v[214:215], v[116:117], v[112:113], v[116:117] neg_lo:[1,0,0] neg_hi:[1,0,0]
	v_pk_fma_f32 v[112:113], v[212:213], s[2:3], v[124:125] op_sel_hi:[1,0,0]
	v_rcp_f32_e32 v216, v216
	v_pk_fma_f32 v[112:113], v[212:213], v[112:113], s[4:5] op_sel_hi:[1,1,0]
	v_rcp_f32_e32 v217, v217
	v_pk_fma_f32 v[112:113], v[212:213], v[112:113], s[12:13] op_sel_hi:[1,1,0]
	v_cndmask_b32_e32 v126, v191, v189, vcc
	v_pk_fma_f32 v[112:113], v[212:213], v[112:113], s[88:89] op_sel_hi:[1,1,0]
	v_cmp_gt_f32_e32 vcc, 0, v118
	v_pk_mul_f32 v[112:113], v[212:213], v[112:113]
	s_ashr_i32 s39, s38, 31
	v_pk_mul_f32 v[112:113], v[114:115], v[112:113]
	s_cmp_lt_i32 s10, 4
	v_pk_mul_f32 v[114:115], v[118:119], v[112:113]
	v_pk_fma_f32 v[212:213], v[118:119], v[112:113], v[118:119] neg_lo:[1,0,0] neg_hi:[1,0,0]
	v_cmp_eq_u32_e64 s[10:11], 0, v141
	v_cndmask_b32_e32 v113, v212, v114, vcc
	v_cmp_gt_f32_e32 vcc, 0, v116
	v_ashrrev_i32_e32 v141, 31, v140
	v_lshlrev_b64 v[170:171], 12, v[140:141]
	v_cndmask_b32_e32 v112, v214, v172, vcc
	v_cmp_gt_f32_e32 vcc, 0, v119
	v_pk_mul_f32 v[118:119], v[210:211], v[210:211]
	v_ashrrev_i32_e32 v163, 31, v162
	v_cndmask_b32_e32 v115, v213, v115, vcc
	v_cmp_gt_f32_e32 vcc, 0, v117
	v_pk_fma_f32 v[116:117], v[216:217], s[2:3], v[124:125] op_sel_hi:[1,0,0]
	v_pk_mul_f32 v[118:119], v[118:119], s[86:87] op_sel_hi:[1,0]
	v_pk_fma_f32 v[116:117], v[216:217], v[116:117], s[4:5] op_sel_hi:[1,1,0]
	v_exp_f32_e32 v118, v118
	v_exp_f32_e32 v119, v119
	v_pk_fma_f32 v[116:117], v[216:217], v[116:117], s[12:13] op_sel_hi:[1,1,0]
	v_cndmask_b32_e32 v114, v215, v173, vcc
	v_pk_fma_f32 v[116:117], v[216:217], v[116:117], s[88:89] op_sel_hi:[1,1,0]
	v_cmp_gt_f32_e32 vcc, 0, v182
	v_pk_mul_f32 v[116:117], v[216:217], v[116:117]
	v_lshl_add_u64 v[170:171], s[20:21], 0, v[170:171]
	v_pk_mul_f32 v[116:117], v[118:119], v[116:117]
	v_cndmask_b32_e32 v118, v186, v174, vcc
	v_pk_mul_f32 v[172:173], v[210:211], v[116:117]
	v_pk_fma_f32 v[214:215], v[210:211], v[116:117], v[210:211] neg_lo:[1,0,0] neg_hi:[1,0,0]
	v_cmp_gt_f32_e32 vcc, 0, v210
	v_and_b32_e32 v174, 0x7fffffff, v208
	v_lshl_add_u64 v[170:171], v[162:163], 1, v[170:171]
	v_cndmask_b32_e32 v119, v214, v172, vcc
	v_cmp_gt_f32_e32 vcc, 0, v183
	v_cvt_pk_bf16_f32 v180, v120, v122
	v_cvt_pk_bf16_f32 v181, v121, v123
	v_pk_mul_f32 v[212:213], v[208:209], v[208:209]
	s_nop 0
	v_cndmask_b32_e32 v172, v187, v175, vcc
	v_and_b32_e32 v175, 0x7fffffff, v209
	v_pk_fma_f32 v[174:175], v[174:175], s[56:57], 1.0 op_sel_hi:[1,0,0]
	v_cmp_gt_f32_e32 vcc, 0, v184
	v_rcp_f32_e32 v184, v174
	v_rcp_f32_e32 v185, v175
	v_cvt_pk_bf16_f32 v182, v118, v172
	v_cndmask_b32_e32 v117, v190, v188, vcc
	v_cvt_pk_bf16_f32 v183, v117, v126
	global_store_dwordx4 v[170:171], v[180:183], off nt
	v_pk_fma_f32 v[124:125], v[184:185], s[2:3], v[124:125] op_sel_hi:[1,0,0]
	v_cmp_gt_f32_e32 vcc, 0, v211
	v_pk_mul_f32 v[180:181], v[212:213], s[86:87] op_sel_hi:[1,0]
	v_pk_fma_f32 v[124:125], v[184:185], v[124:125], s[4:5] op_sel_hi:[1,1,0]
	v_exp_f32_e32 v180, v180
	v_exp_f32_e32 v181, v181
	v_pk_fma_f32 v[124:125], v[184:185], v[124:125], s[12:13] op_sel_hi:[1,1,0]
	v_cndmask_b32_e32 v174, v215, v173, vcc
	v_pk_fma_f32 v[124:125], v[184:185], v[124:125], s[88:89] op_sel_hi:[1,1,0]
	v_cmp_gt_f32_e32 vcc, 0, v209
	v_pk_mul_f32 v[124:125], v[184:185], v[124:125]
	s_nop 0
	v_pk_mul_f32 v[124:125], v[180:181], v[124:125]
	s_nop 0
	v_pk_mul_f32 v[180:181], v[208:209], v[124:125]
	v_pk_fma_f32 v[124:125], v[208:209], v[124:125], v[208:209] neg_lo:[1,0,0] neg_hi:[1,0,0]
	s_nop 0
	v_cndmask_b32_e32 v125, v125, v181, vcc
	v_cmp_gt_f32_e32 vcc, 0, v208
	s_nop 1
	v_cndmask_b32_e32 v124, v124, v180, vcc
	v_cvt_pk_bf16_f32 v180, v112, v114
	v_cvt_pk_bf16_f32 v181, v113, v115
	v_cvt_pk_bf16_f32 v182, v119, v174
	v_cvt_pk_bf16_f32 v183, v124, v125
	global_store_dwordx4 v[170:171], v[180:183], off offset:256 nt
	s_cbranch_scc1 .LBB0_756
;     __device__ __forceinline__ void operator()(const f32x4 (&acc)[2][2][4][2], const Unit& u, int ui, int wr, int wc, int fr, int fq) const {
;     ...
;                     s1 += (z0[0] + z0[1]) + (z0[2] + z0[3]) + (z1[0] + z1[1]) + (z1[2] + z1[3]);
;                     s2 += (z0[0] * z0[0] + z0[1] * z0[1]) + (z0[2] * z0[2] + z0[3] * z0[3]) + (z1[0] * z1[0] + z1[1] * z1[1]) + (z1[2] * z1[2] + z1[3] * z1[3]); }
;                 if (u.pn >= 4) { s1 += __shfl_xor(s1, 16); s1 += __shfl_xor(s1, 32); s2 += __shfl_xor(s2, 16); s2 += __shfl_xor(s2, 32);
;                     if (fq == 0) vst[(size_t)row * 16 + (u.pn - 4) * 4 + wc] = (f32x2){s1, s2}; } }
	v_mov_b32_e32 v116, v119
	v_mov_b32_e32 v175, v117
	v_pk_add_f32 v[170:171], v[116:117], v[174:175]
	v_pk_mul_f32 v[180:181], v[116:117], v[174:175]
	v_mov_b32_e32 v182, v118
	v_mov_b32_e32 v183, v172
	v_mul_f32_e32 v116, v118, v118
	v_mov_b32_e32 v173, v119
	v_pk_fma_f32 v[182:183], v[182:183], v[182:183], v[116:117] op_sel_hi:[1,1,0]
	v_mul_f32_e32 v116, v124, v124
	v_pk_fma_f32 v[184:185], v[124:125], v[124:125], v[116:117] op_sel_hi:[1,1,0]
	v_mov_b32_e32 v186, v112
	v_mov_b32_e32 v187, v114
	v_mul_f32_e32 v116, v112, v112
	v_pk_add_f32 v[190:191], v[118:119], v[172:173]
	v_pk_mul_f32 v[118:119], v[118:119], v[172:173]
	v_mov_b32_e32 v171, v181
	v_pk_mul_f32 v[180:181], v[122:123], v[122:123]
	v_pk_fma_f32 v[186:187], v[186:187], v[186:187], v[116:117] op_sel_hi:[1,1,0]
	v_mov_b32_e32 v188, v113
	v_mov_b32_e32 v189, v115
	v_mul_f32_e32 v116, v113, v113
	v_mov_b32_e32 v191, v119
	v_pk_mul_f32 v[118:119], v[174:175], v[174:175]
	v_pk_add_f32 v[112:113], v[112:113], v[114:115]
	v_and_b32_e32 v115, 64, v192
	v_pk_fma_f32 v[180:181], v[120:121], v[120:121], v[180:181]
	v_pk_add_f32 v[120:121], v[120:121], v[122:123]
	v_xor_b32_e32 v114, 16, v192
	v_add_u32_e32 v119, 64, v115
	v_pk_fma_f32 v[188:189], v[188:189], v[188:189], v[116:117] op_sel_hi:[1,1,0]
	v_pk_add_f32 v[120:121], v[120:121], v[120:121] op_sel:[0,1] op_sel_hi:[1,0]
	v_cmp_lt_i32_e32 vcc, v114, v119
	v_mul_f32_e32 v168, v126, v126
	v_pk_add_f32 v[180:181], v[180:181], v[180:181] op_sel_hi:[0,1]
	v_cndmask_b32_e32 v114, v192, v114, vcc
	v_mov_b32_e32 v186, v117
	v_mov_b32_e32 v127, v189
	v_mov_b32_e32 v121, v118
	v_pk_add_f32 v[112:113], v[112:113], v[112:113] op_sel:[0,1] op_sel_hi:[1,0]
	v_lshlrev_b32_e32 v122, 2, v114
	v_pk_add_f32 v[114:115], v[186:187], v[126:127]
	v_pk_add_f32 v[116:117], v[190:191], v[120:121]
	v_mov_b32_e32 v182, v124
	v_mov_b32_e32 v180, v125
	v_mov_b32_e32 v113, v168
	v_pk_add_f32 v[114:115], v[116:117], v[114:115]
	v_mov_b32_e32 v147, v185
	v_pk_add_f32 v[116:117], v[182:183], v[180:181]
	v_pk_add_f32 v[112:113], v[170:171], v[112:113]
	v_pk_add_f32 v[114:115], v[114:115], v[146:147]
	v_pk_add_f32 v[112:113], v[112:113], v[116:117]
	v_xor_b32_e32 v116, 32, v192
	v_pk_add_f32 v[112:113], v[112:113], v[114:115]
	ds_bpermute_b32 v114, v122, v112
	ds_bpermute_b32 v115, v122, v113
	v_cmp_lt_i32_e32 vcc, v116, v119
	s_waitcnt lgkmcnt(0)
	v_pk_add_f32 v[112:113], v[112:113], v[114:115]
	v_cndmask_b32_e32 v116, v192, v116, vcc
	v_lshlrev_b32_e32 v116, 2, v116
	ds_bpermute_b32 v114, v116, v112
	ds_bpermute_b32 v115, v116, v113
	s_and_saveexec_b64 s[2:3], s[10:11]
	s_cbranch_execz .LBB0_755
	s_waitcnt lgkmcnt(0)
	v_pk_add_f32 v[112:113], v[112:113], v[114:115]
	v_lshlrev_b64 v[114:115], 7, v[140:141]
	v_lshl_add_u64 v[114:115], s[16:17], 0, v[114:115]
	v_lshl_add_u64 v[114:115], s[38:39], 3, v[114:115]
	s_lshl_b32 s88, s44, 3
	v_lshl_add_u64 v[114:115], v[114:115], 0, s[88:89]
	global_store_dwordx2 v[114:115], v[112:113], off

; __device__ __forceinline__ f32x2 gelu_pk(f32x2 v) {
;     const f32x2 av = __builtin_elementwise_abs(v), d = av * 0.2316418882f + 1.0f;
;     f32x2 t; t.x = __builtin_amdgcn_rcpf(d.x); t.y = __builtin_amdgcn_rcpf(d.y);
;     f32x2 q = t * 0.5307027145f + (-0.7265760135f); q = q * t + 0.7107068705f; q = q * t + (-0.142248368f); q = q * t + 0.127414796f; q = q * t;
;     const f32x2 s = (v * v) * (-0.72134752044f);
;     f32x2 e; e.x = __builtin_amdgcn_exp2f(s.x); e.y = __builtin_amdgcn_exp2f(s.y);
;     const f32x2 m = v * (q * e), r = v - m;
;     f32x2 o; o.x = v.x < 0.f ? m.x : r.x; o.y = v.y < 0.f ? m.y : r.y; return o;
;     __device__ __forceinline__ void operator()(const f32x4 (&acc)[2][2][4][2], const Unit& u, int ui, int wr, int wc, int fr, int fq) const {
;     ...
;             for (int m = 0; m < 4; ++m) { const float r = rs[ai][m]; const int row = row0 + ai * HALF + m * 16; bf16_t* rowp = Z + (size_t)row * 2048 + col0; float s1 = 0.f, s2 = 0.f;
; #pragma unroll
;                 for (int bj = 0; bj < 2; ++bj) { const f32x4 v0 = acc[ai][bj][m][0] * r, v1 = acc[ai][bj][m][1] * r;
;                     const f32x2 a = gelu_pk((f32x2){v0[0], v0[1]}), b = gelu_pk((f32x2){v0[2], v0[3]}), c = gelu_pk((f32x2){v1[0], v1[1]}), d = gelu_pk((f32x2){v1[2], v1[3]});
.LBB0_756:
	v_mov_b32_e32 v116, v169
	v_pk_mul_f32 v[118:119], v[108:109], v[116:117] op_sel_hi:[1,0]
	s_mov_b32 s2, 0xbf3a00e3
	v_and_b32_e32 v109, 0x7fffffff, v119
	v_and_b32_e32 v108, 0x7fffffff, v118
	v_pk_fma_f32 v[108:109], v[108:109], s[56:57], 1.0 op_sel_hi:[1,0,0]
	v_pk_mul_f32 v[122:123], v[104:105], v[116:117] op_sel_hi:[1,0]
	v_rcp_f32_e32 v120, v108
	v_rcp_f32_e32 v121, v109
	v_mov_b64_e32 v[108:109], s[2:3]
	s_mov_b32 s2, 0x3f07dc22
	s_mov_b32 s88, 0x3e027906
	v_pk_fma_f32 v[104:105], v[120:121], s[2:3], v[108:109] op_sel_hi:[1,0,0]
	v_pk_mul_f32 v[110:111], v[110:111], v[116:117] op_sel_hi:[1,0]
	v_pk_fma_f32 v[104:105], v[120:121], v[104:105], s[4:5] op_sel_hi:[1,1,0]
	v_and_b32_e32 v127, 0x7fffffff, v111
	v_pk_fma_f32 v[104:105], v[120:121], v[104:105], s[12:13] op_sel_hi:[1,1,0]
	v_and_b32_e32 v126, 0x7fffffff, v110
	v_pk_fma_f32 v[104:105], v[120:121], v[104:105], s[88:89] op_sel_hi:[1,1,0]
	v_pk_fma_f32 v[126:127], v[126:127], s[56:57], 1.0 op_sel_hi:[1,0,0]
	v_pk_mul_f32 v[104:105], v[120:121], v[104:105]
	v_pk_mul_f32 v[120:121], v[118:119], v[118:119]
	v_rcp_f32_e32 v126, v126
	v_pk_mul_f32 v[120:121], v[120:121], s[86:87] op_sel_hi:[1,0]
	v_rcp_f32_e32 v127, v127
	v_exp_f32_e32 v120, v120
	v_exp_f32_e32 v121, v121
	v_pk_mul_f32 v[124:125], v[106:107], v[116:117] op_sel_hi:[1,0]
	v_pk_mul_f32 v[106:107], v[110:111], v[110:111]
	v_pk_mul_f32 v[100:101], v[100:101], v[116:117] op_sel_hi:[1,0]
	v_pk_mul_f32 v[104:105], v[120:121], v[104:105]
	v_pk_mul_f32 v[106:107], v[106:107], s[86:87] op_sel_hi:[1,0]
	v_pk_mul_f32 v[120:121], v[118:119], v[104:105]
	v_pk_fma_f32 v[168:169], v[118:119], v[104:105], v[118:119] neg_lo:[1,0,0] neg_hi:[1,0,0]
	v_pk_fma_f32 v[104:105], v[126:127], s[2:3], v[108:109] op_sel_hi:[1,0,0]
	v_exp_f32_e32 v106, v106
	v_pk_fma_f32 v[104:105], v[126:127], v[104:105], s[4:5] op_sel_hi:[1,1,0]
	v_exp_f32_e32 v107, v107
	v_and_b32_e32 v173, 0x7fffffff, v101
	v_and_b32_e32 v172, 0x7fffffff, v100
	v_pk_fma_f32 v[104:105], v[126:127], v[104:105], s[12:13] op_sel_hi:[1,1,0]
	v_pk_fma_f32 v[172:173], v[172:173], s[56:57], 1.0 op_sel_hi:[1,0,0]
	v_pk_fma_f32 v[104:105], v[126:127], v[104:105], s[88:89] op_sel_hi:[1,1,0]
	v_rcp_f32_e32 v172, v172
	v_rcp_f32_e32 v173, v173
	v_pk_mul_f32 v[104:105], v[126:127], v[104:105]
	v_and_b32_e32 v171, 0x7fffffff, v123
	v_pk_mul_f32 v[104:105], v[106:107], v[104:105]
	v_and_b32_e32 v170, 0x7fffffff, v122
	v_pk_mul_f32 v[106:107], v[110:111], v[104:105]
	v_pk_fma_f32 v[126:127], v[110:111], v[104:105], v[110:111] neg_lo:[1,0,0] neg_hi:[1,0,0]
	v_cmp_gt_f32_e32 vcc, 0, v110
	v_pk_fma_f32 v[170:171], v[170:171], s[56:57], 1.0 op_sel_hi:[1,0,0]
	v_pk_mul_f32 v[102:103], v[102:103], v[116:117] op_sel_hi:[1,0]
	v_cndmask_b32_e32 v105, v126, v106, vcc
	v_cmp_gt_f32_e32 vcc, 0, v118
	v_rcp_f32_e32 v170, v170
	v_rcp_f32_e32 v171, v171
	v_pk_mul_f32 v[174:175], v[98:99], v[116:117] op_sel_hi:[1,0]
	v_pk_mul_f32 v[116:117], v[96:97], v[116:117] op_sel_hi:[1,0]
	v_pk_fma_f32 v[96:97], v[172:173], s[2:3], v[108:109] op_sel_hi:[1,0,0]
	v_cndmask_b32_e32 v104, v168, v120, vcc
	v_cmp_gt_f32_e32 vcc, 0, v111
	v_pk_fma_f32 v[96:97], v[172:173], v[96:97], s[4:5] op_sel_hi:[1,1,0]
	v_pk_fma_f32 v[110:111], v[170:171], s[2:3], v[108:109] op_sel_hi:[1,0,0]
	v_cndmask_b32_e32 v107, v127, v107, vcc
	v_cmp_gt_f32_e32 vcc, 0, v119
	v_pk_fma_f32 v[96:97], v[172:173], v[96:97], s[12:13] op_sel_hi:[1,1,0]
	v_and_b32_e32 v127, 0x7fffffff, v125
	v_cndmask_b32_e32 v106, v169, v121, vcc
	v_pk_mul_f32 v[120:121], v[122:123], v[122:123]
	v_pk_fma_f32 v[96:97], v[172:173], v[96:97], s[88:89] op_sel_hi:[1,1,0]
	v_pk_mul_f32 v[120:121], v[120:121], s[86:87] op_sel_hi:[1,0]
	v_and_b32_e32 v126, 0x7fffffff, v124
	v_pk_mul_f32 v[96:97], v[172:173], v[96:97]
	v_pk_mul_f32 v[172:173], v[100:101], v[100:101]
	v_pk_fma_f32 v[110:111], v[170:171], v[110:111], s[4:5] op_sel_hi:[1,1,0]
	v_exp_f32_e32 v120, v120
	v_exp_f32_e32 v121, v121
	v_pk_fma_f32 v[126:127], v[126:127], s[56:57], 1.0 op_sel_hi:[1,0,0]
	v_pk_mul_f32 v[172:173], v[172:173], s[86:87] op_sel_hi:[1,0]
	v_and_b32_e32 v181, 0x7fffffff, v103
	v_and_b32_e32 v180, 0x7fffffff, v102
	v_pk_fma_f32 v[110:111], v[170:171], v[110:111], s[12:13] op_sel_hi:[1,1,0]
	v_rcp_f32_e32 v126, v126
	v_rcp_f32_e32 v127, v127
	v_exp_f32_e32 v172, v172
	v_exp_f32_e32 v173, v173
	v_pk_fma_f32 v[180:181], v[180:181], s[56:57], 1.0 op_sel_hi:[1,0,0]
	v_pk_fma_f32 v[110:111], v[170:171], v[110:111], s[88:89] op_sel_hi:[1,1,0]
	v_rcp_f32_e32 v180, v180
	v_rcp_f32_e32 v181, v181
	v_pk_mul_f32 v[110:111], v[170:171], v[110:111]
	v_pk_mul_f32 v[118:119], v[124:125], v[124:125]
	v_pk_mul_f32 v[110:111], v[120:121], v[110:111]
	v_pk_mul_f32 v[118:119], v[118:119], s[86:87] op_sel_hi:[1,0]
	v_pk_mul_f32 v[168:169], v[122:123], v[110:111]
	v_pk_fma_f32 v[170:171], v[122:123], v[110:111], v[122:123] neg_lo:[1,0,0] neg_hi:[1,0,0]
	v_pk_fma_f32 v[110:111], v[126:127], s[2:3], v[108:109] op_sel_hi:[1,0,0]
	v_pk_mul_f32 v[98:99], v[102:103], v[102:103]
	v_pk_mul_f32 v[96:97], v[172:173], v[96:97]
	v_pk_fma_f32 v[110:111], v[126:127], v[110:111], s[4:5] op_sel_hi:[1,1,0]
	v_exp_f32_e32 v118, v118
	v_exp_f32_e32 v119, v119
	v_pk_mul_f32 v[172:173], v[100:101], v[96:97]
	v_pk_fma_f32 v[182:183], v[100:101], v[96:97], v[100:101] neg_lo:[1,0,0] neg_hi:[1,0,0]
	v_pk_fma_f32 v[96:97], v[180:181], s[2:3], v[108:109] op_sel_hi:[1,0,0]
	v_pk_mul_f32 v[98:99], v[98:99], s[86:87] op_sel_hi:[1,0]
	v_pk_fma_f32 v[110:111], v[126:127], v[110:111], s[12:13] op_sel_hi:[1,1,0]
	v_pk_fma_f32 v[96:97], v[180:181], v[96:97], s[4:5] op_sel_hi:[1,1,0]
	v_exp_f32_e32 v98, v98
	v_exp_f32_e32 v99, v99
	v_pk_fma_f32 v[110:111], v[126:127], v[110:111], s[88:89] op_sel_hi:[1,1,0]
	v_pk_fma_f32 v[96:97], v[180:181], v[96:97], s[12:13] op_sel_hi:[1,1,0]
	v_pk_mul_f32 v[110:111], v[126:127], v[110:111]
	v_pk_fma_f32 v[96:97], v[180:181], v[96:97], s[88:89] op_sel_hi:[1,1,0]
	v_and_b32_e32 v185, 0x7fffffff, v117
	v_and_b32_e32 v184, 0x7fffffff, v116
	v_pk_mul_f32 v[110:111], v[118:119], v[110:111]
	v_pk_mul_f32 v[96:97], v[180:181], v[96:97]
	v_pk_fma_f32 v[184:185], v[184:185], s[56:57], 1.0 op_sel_hi:[1,0,0]
	v_pk_mul_f32 v[118:119], v[124:125], v[110:111]
	v_pk_fma_f32 v[126:127], v[124:125], v[110:111], v[124:125] neg_lo:[1,0,0] neg_hi:[1,0,0]
	v_cmp_gt_f32_e32 vcc, 0, v125
	v_pk_mul_f32 v[96:97], v[98:99], v[96:97]
	v_rcp_f32_e32 v184, v184
	v_rcp_f32_e32 v185, v185
	v_cndmask_b32_e32 v110, v127, v119, vcc
	v_pk_mul_f32 v[98:99], v[102:103], v[96:97]
	v_pk_fma_f32 v[180:181], v[102:103], v[96:97], v[102:103] neg_lo:[1,0,0] neg_hi:[1,0,0]
	v_cmp_gt_f32_e32 vcc, 0, v102
	v_and_b32_e32 v119, 0x7fffffff, v175
	v_add_u32_e32 v112, 16, v140
	v_cndmask_b32_e32 v97, v180, v98, vcc
	v_cmp_gt_f32_e32 vcc, 0, v100
	v_ashrrev_i32_e32 v113, 31, v112
	s_waitcnt lgkmcnt(0)
; __device__ __forceinline__ u32x4 pack8(const f32x4& a, const f32x4& b) { u32x4 w; w.x = cvt_pk_bf16(a[0], a[1]); w.y = cvt_pk_bf16(a[2], a[3]); w.z = cvt_pk_bf16(b[0], b[1]); w.w = cvt_pk_bf16(b[2], b[3]); return w; }
; __device__ __forceinline__ f32x2 gelu_pk(f32x2 v) {
;     const f32x2 av = __builtin_elementwise_abs(v), d = av * 0.2316418882f + 1.0f;
;     f32x2 t; t.x = __builtin_amdgcn_rcpf(d.x); t.y = __builtin_amdgcn_rcpf(d.y);
;     f32x2 q = t * 0.5307027145f + (-0.7265760135f); q = q * t + 0.7107068705f; q = q * t + (-0.142248368f); q = q * t + 0.127414796f; q = q * t;
;     const f32x2 s = (v * v) * (-0.72134752044f);
;     f32x2 e; e.x = __builtin_amdgcn_exp2f(s.x); e.y = __builtin_amdgcn_exp2f(s.y);
;     const f32x2 m = v * (q * e), r = v - m;
;     f32x2 o; o.x = v.x < 0.f ? m.x : r.x; o.y = v.y < 0.f ? m.y : r.y; return o;
;     __device__ __forceinline__ void operator()(const f32x4 (&acc)[2][2][4][2], const Unit& u, int ui, int wr, int wc, int fr, int fq) const {
;     ...
;             for (int m = 0; m < 4; ++m) { const float r = rs[ai][m]; const int row = row0 + ai * HALF + m * 16; bf16_t* rowp = Z + (size_t)row * 2048 + col0; float s1 = 0.f, s2 = 0.f;
; #pragma unroll
;                 for (int bj = 0; bj < 2; ++bj) { const f32x4 v0 = acc[ai][bj][m][0] * r, v1 = acc[ai][bj][m][1] * r;
;                     const f32x2 a = gelu_pk((f32x2){v0[0], v0[1]}), b = gelu_pk((f32x2){v0[2], v0[3]}), c = gelu_pk((f32x2){v1[0], v1[1]}), d = gelu_pk((f32x2){v1[2], v1[3]});
;                     const f32x4 z0 = (f32x4){a.x, a.y, b.x, b.y}, z1 = (f32x4){c.x, c.y, d.x, d.y};
;                     *(u32x4*)(rowp + bj * HALF) = pack8(z0, z1);
;                     s1 += (z0[0] + z0[1]) + (z0[2] + z0[3]) + (z1[0] + z1[1]) + (z1[2] + z1[3]);
;                     s2 += (z0[0] * z0[0] + z0[1] * z0[1]) + (z0[2] * z0[2] + z0[3] * z0[3]) + (z1[0] * z1[0] + z1[1] * z1[1]) + (z1[2] * z1[2] + z1[3] * z1[3]); }
;                 if (u.pn >= 4) { s1 += __shfl_xor(s1, 16); s1 += __shfl_xor(s1, 32); s2 += __shfl_xor(s2, 16); s2 += __shfl_xor(s2, 32);
;                     if (fq == 0) vst[(size_t)row * 16 + (u.pn - 4) * 4 + wc] = (f32x2){s1, s2}; } }
	v_lshlrev_b64 v[114:115], 12, v[112:113]
	v_cndmask_b32_e32 v96, v182, v172, vcc
	v_cmp_gt_f32_e32 vcc, 0, v103
	v_pk_mul_f32 v[102:103], v[116:117], v[116:117]
	v_lshl_add_u64 v[114:115], s[20:21], 0, v[114:115]
	v_cndmask_b32_e32 v99, v181, v99, vcc
	v_cmp_gt_f32_e32 vcc, 0, v101
	v_pk_fma_f32 v[100:101], v[184:185], s[2:3], v[108:109] op_sel_hi:[1,0,0]
	v_pk_mul_f32 v[102:103], v[102:103], s[86:87] op_sel_hi:[1,0]
	v_pk_fma_f32 v[100:101], v[184:185], v[100:101], s[4:5] op_sel_hi:[1,1,0]
	v_exp_f32_e32 v102, v102
	v_exp_f32_e32 v103, v103
	v_pk_fma_f32 v[100:101], v[184:185], v[100:101], s[12:13] op_sel_hi:[1,1,0]
	v_cndmask_b32_e32 v98, v183, v173, vcc
	v_pk_fma_f32 v[100:101], v[184:185], v[100:101], s[88:89] op_sel_hi:[1,1,0]
	v_cmp_gt_f32_e32 vcc, 0, v122
	v_pk_mul_f32 v[100:101], v[184:185], v[100:101]
	v_lshl_add_u64 v[114:115], v[162:163], 1, v[114:115]
	v_pk_mul_f32 v[100:101], v[102:103], v[100:101]
	v_cndmask_b32_e32 v102, v170, v168, vcc
	v_pk_mul_f32 v[180:181], v[116:117], v[100:101]
	v_pk_fma_f32 v[182:183], v[116:117], v[100:101], v[116:117] neg_lo:[1,0,0] neg_hi:[1,0,0]
	v_cmp_gt_f32_e32 vcc, 0, v116
	v_cvt_pk_bf16_f32 v120, v104, v106
	v_cvt_pk_bf16_f32 v121, v105, v107
	v_pk_mul_f32 v[172:173], v[174:175], v[174:175]
	v_cndmask_b32_e64 v100, 0, 1, s[0:1]
	v_cndmask_b32_e32 v103, v182, v180, vcc
	v_cmp_gt_f32_e32 vcc, 0, v123
	s_nop 1
	v_cndmask_b32_e32 v116, v171, v169, vcc
	v_cmp_gt_f32_e32 vcc, 0, v124
	v_cvt_pk_bf16_f32 v122, v102, v116
	s_nop 1
	v_cndmask_b32_e32 v101, v126, v118, vcc
	v_and_b32_e32 v118, 0x7fffffff, v174
	v_pk_fma_f32 v[118:119], v[118:119], s[56:57], 1.0 op_sel_hi:[1,0,0]
	v_cvt_pk_bf16_f32 v123, v101, v110
	global_store_dwordx4 v[114:115], v[120:123], off nt
	v_rcp_f32_e32 v124, v118
	v_rcp_f32_e32 v125, v119
	v_pk_mul_f32 v[120:121], v[172:173], s[86:87] op_sel_hi:[1,0]
	v_cmp_gt_f32_e32 vcc, 0, v117
	v_exp_f32_e32 v120, v120
	v_pk_fma_f32 v[108:109], v[124:125], s[2:3], v[108:109] op_sel_hi:[1,0,0]
	v_exp_f32_e32 v121, v121
	v_pk_fma_f32 v[108:109], v[124:125], v[108:109], s[4:5] op_sel_hi:[1,1,0]
	v_cndmask_b32_e32 v118, v183, v181, vcc
	v_pk_fma_f32 v[108:109], v[124:125], v[108:109], s[12:13] op_sel_hi:[1,1,0]
	v_cmp_gt_f32_e32 vcc, 0, v175
	v_pk_fma_f32 v[108:109], v[124:125], v[108:109], s[88:89] op_sel_hi:[1,1,0]
	v_cmp_ne_u32_e64 s[12:13], 1, v100
	v_pk_mul_f32 v[108:109], v[124:125], v[108:109]
	s_nop 0
	v_pk_mul_f32 v[108:109], v[120:121], v[108:109]
	s_nop 0
	v_pk_mul_f32 v[120:121], v[174:175], v[108:109]
	v_pk_fma_f32 v[108:109], v[174:175], v[108:109], v[174:175] neg_lo:[1,0,0] neg_hi:[1,0,0]
	s_nop 0
	v_cndmask_b32_e32 v109, v109, v121, vcc
	v_cmp_gt_f32_e32 vcc, 0, v174
	s_nop 1
	v_cndmask_b32_e32 v108, v108, v120, vcc
	s_andn2_b64 vcc, exec, s[0:1]
	v_cvt_pk_bf16_f32 v120, v96, v98
	v_cvt_pk_bf16_f32 v121, v97, v99
	v_cvt_pk_bf16_f32 v122, v103, v118
	v_cvt_pk_bf16_f32 v123, v108, v109
	global_store_dwordx4 v[114:115], v[120:123], off offset:256 nt
	s_cbranch_vccnz .LBB0_760
	v_mov_b32_e32 v100, v103
	v_mov_b32_e32 v119, v101
	v_pk_add_f32 v[114:115], v[100:101], v[118:119]
	v_pk_mul_f32 v[120:121], v[100:101], v[118:119]
	v_mov_b32_e32 v122, v102
	v_mov_b32_e32 v123, v116
	v_mul_f32_e32 v100, v102, v102
	v_mov_b32_e32 v117, v103
	v_pk_fma_f32 v[122:123], v[122:123], v[122:123], v[100:101] op_sel_hi:[1,1,0]
	v_mul_f32_e32 v100, v108, v108
	v_pk_fma_f32 v[124:125], v[108:109], v[108:109], v[100:101] op_sel_hi:[1,1,0]
	v_mov_b32_e32 v126, v96
	v_mov_b32_e32 v127, v98
	v_mul_f32_e32 v100, v96, v96
	v_pk_add_f32 v[170:171], v[102:103], v[116:117]
	v_pk_mul_f32 v[102:103], v[102:103], v[116:117]
	v_mov_b32_e32 v115, v121
	v_pk_mul_f32 v[120:121], v[106:107], v[106:107]
	v_pk_fma_f32 v[126:127], v[126:127], v[126:127], v[100:101] op_sel_hi:[1,1,0]
	v_mov_b32_e32 v168, v97
	v_mov_b32_e32 v169, v99
	v_mul_f32_e32 v100, v97, v97
	v_mov_b32_e32 v171, v103
	v_pk_mul_f32 v[102:103], v[118:119], v[118:119]
	v_pk_add_f32 v[96:97], v[96:97], v[98:99]
	v_and_b32_e32 v99, 64, v192
	v_pk_fma_f32 v[120:121], v[104:105], v[104:105], v[120:121]
	v_pk_add_f32 v[104:105], v[104:105], v[106:107]
	v_xor_b32_e32 v98, 16, v192
	v_add_u32_e32 v103, 64, v99
	v_pk_fma_f32 v[168:169], v[168:169], v[168:169], v[100:101] op_sel_hi:[1,1,0]
	v_pk_add_f32 v[104:105], v[104:105], v[104:105] op_sel:[0,1] op_sel_hi:[1,0]
	v_cmp_lt_i32_e32 vcc, v98, v103
	v_mul_f32_e32 v141, v110, v110
	v_pk_add_f32 v[120:121], v[120:121], v[120:121] op_sel_hi:[0,1]
	v_cndmask_b32_e32 v98, v192, v98, vcc
	v_mov_b32_e32 v126, v101
	v_mov_b32_e32 v111, v169
	v_mov_b32_e32 v105, v102
	v_pk_add_f32 v[96:97], v[96:97], v[96:97] op_sel:[0,1] op_sel_hi:[1,0]
	v_lshlrev_b32_e32 v106, 2, v98
	v_pk_add_f32 v[98:99], v[126:127], v[110:111]
	v_pk_add_f32 v[100:101], v[170:171], v[104:105]
	v_mov_b32_e32 v122, v108
	v_mov_b32_e32 v120, v109
	v_mov_b32_e32 v97, v141
	v_pk_add_f32 v[98:99], v[100:101], v[98:99]
	v_mov_b32_e32 v147, v125
	v_pk_add_f32 v[100:101], v[122:123], v[120:121]
	v_pk_add_f32 v[96:97], v[114:115], v[96:97]
	v_pk_add_f32 v[98:99], v[98:99], v[146:147]
	v_pk_add_f32 v[96:97], v[96:97], v[100:101]
	v_xor_b32_e32 v100, 32, v192
	v_pk_add_f32 v[96:97], v[96:97], v[98:99]
	ds_bpermute_b32 v98, v106, v96
	ds_bpermute_b32 v99, v106, v97
	v_cmp_lt_i32_e32 vcc, v100, v103
	s_waitcnt lgkmcnt(0)
	v_pk_add_f32 v[96:97], v[96:97], v[98:99]
	v_cndmask_b32_e32 v100, v192, v100, vcc
	v_lshlrev_b32_e32 v100, 2, v100
	ds_bpermute_b32 v98, v100, v96
	ds_bpermute_b32 v99, v100, v97
	s_and_saveexec_b64 s[0:1], s[10:11]
	s_cbranch_execz .LBB0_759
	s_waitcnt lgkmcnt(0)
	v_pk_add_f32 v[96:97], v[96:97], v[98:99]
	v_lshlrev_b64 v[98:99], 7, v[112:113]
	v_lshl_add_u64 v[98:99], s[16:17], 0, v[98:99]
	v_lshl_add_u64 v[98:99], s[38:39], 3, v[98:99]
	s_lshl_b32 s88, s44, 3
	v_lshl_add_u64 v[98:99], v[98:99], 0, s[88:89]
	global_store_dwordx2 v[98:99], v[96:97], off

; __device__ __forceinline__ f32x2 gelu_pk(f32x2 v) {
;     const f32x2 av = __builtin_elementwise_abs(v), d = av * 0.2316418882f + 1.0f;
;     f32x2 t; t.x = __builtin_amdgcn_rcpf(d.x); t.y = __builtin_amdgcn_rcpf(d.y);
;     f32x2 q = t * 0.5307027145f + (-0.7265760135f); q = q * t + 0.7107068705f; q = q * t + (-0.142248368f); q = q * t + 0.127414796f; q = q * t;
;     const f32x2 s = (v * v) * (-0.72134752044f);
;     f32x2 e; e.x = __builtin_amdgcn_exp2f(s.x); e.y = __builtin_amdgcn_exp2f(s.y);
;     const f32x2 m = v * (q * e), r = v - m;
;     f32x2 o; o.x = v.x < 0.f ? m.x : r.x; o.y = v.y < 0.f ? m.y : r.y; return o;
;     __device__ __forceinline__ void operator()(const f32x4 (&acc)[2][2][4][2], const Unit& u, int ui, int wr, int wc, int fr, int fq) const {
;     ...
;             for (int m = 0; m < 4; ++m) { const float r = rs[ai][m]; const int row = row0 + ai * HALF + m * 16; bf16_t* rowp = Z + (size_t)row * 2048 + col0; float s1 = 0.f, s2 = 0.f;
; #pragma unroll
;                 for (int bj = 0; bj < 2; ++bj) { const f32x4 v0 = acc[ai][bj][m][0] * r, v1 = acc[ai][bj][m][1] * r;
;                     const f32x2 a = gelu_pk((f32x2){v0[0], v0[1]}), b = gelu_pk((f32x2){v0[2], v0[3]}), c = gelu_pk((f32x2){v1[0], v1[1]}), d = gelu_pk((f32x2){v1[2], v1[3]});
.LBB0_760:
	v_pk_mul_f32 v[100:101], v[92:93], v[166:167] op_sel_hi:[1,0]
	s_mov_b32 s0, 0xbf3a00e3
	v_and_b32_e32 v93, 0x7fffffff, v101
	v_and_b32_e32 v92, 0x7fffffff, v100
	v_pk_fma_f32 v[92:93], v[92:93], s[56:57], 1.0 op_sel_hi:[1,0,0]
	v_pk_mul_f32 v[106:107], v[88:89], v[166:167] op_sel_hi:[1,0]
	v_rcp_f32_e32 v102, v92
	v_rcp_f32_e32 v103, v93
	v_mov_b64_e32 v[92:93], s[0:1]
	s_mov_b32 s0, 0x3f07dc22
	s_mov_b32 s2, 0x3f35f0e3
	v_pk_fma_f32 v[88:89], v[102:103], s[0:1], v[92:93] op_sel_hi:[1,0,0]
	s_mov_b32 s4, 0xbe11a98e
	v_pk_fma_f32 v[88:89], v[102:103], v[88:89], s[2:3] op_sel_hi:[1,1,0]
	s_mov_b32 s88, 0x3e027906
	v_pk_fma_f32 v[88:89], v[102:103], v[88:89], s[4:5] op_sel_hi:[1,1,0]
	v_pk_mul_f32 v[94:95], v[94:95], v[166:167] op_sel_hi:[1,0]
	v_pk_fma_f32 v[88:89], v[102:103], v[88:89], s[88:89] op_sel_hi:[1,1,0]
	v_and_b32_e32 v105, 0x7fffffff, v95
	v_pk_mul_f32 v[88:89], v[102:103], v[88:89]
	v_pk_mul_f32 v[102:103], v[100:101], v[100:101]
	v_and_b32_e32 v104, 0x7fffffff, v94
	v_pk_mul_f32 v[102:103], v[102:103], s[86:87] op_sel_hi:[1,0]
	v_pk_fma_f32 v[104:105], v[104:105], s[56:57], 1.0 op_sel_hi:[1,0,0]
	v_exp_f32_e32 v102, v102
	v_exp_f32_e32 v103, v103
	v_rcp_f32_e32 v104, v104
	v_rcp_f32_e32 v105, v105
	v_pk_mul_f32 v[108:109], v[90:91], v[166:167] op_sel_hi:[1,0]
	v_pk_mul_f32 v[90:91], v[94:95], v[94:95]
	v_pk_mul_f32 v[88:89], v[102:103], v[88:89]
	v_pk_mul_f32 v[90:91], v[90:91], s[86:87] op_sel_hi:[1,0]
	v_pk_mul_f32 v[102:103], v[100:101], v[88:89]
	v_pk_fma_f32 v[110:111], v[100:101], v[88:89], v[100:101] neg_lo:[1,0,0] neg_hi:[1,0,0]
	v_pk_fma_f32 v[88:89], v[104:105], s[0:1], v[92:93] op_sel_hi:[1,0,0]
	v_exp_f32_e32 v90, v90
	v_pk_fma_f32 v[88:89], v[104:105], v[88:89], s[2:3] op_sel_hi:[1,1,0]
	v_exp_f32_e32 v91, v91
	v_pk_fma_f32 v[88:89], v[104:105], v[88:89], s[4:5] op_sel_hi:[1,1,0]
	v_and_b32_e32 v113, 0x7fffffff, v107
	v_pk_fma_f32 v[88:89], v[104:105], v[88:89], s[88:89] op_sel_hi:[1,1,0]
	v_and_b32_e32 v112, 0x7fffffff, v106
	v_pk_mul_f32 v[88:89], v[104:105], v[88:89]
	v_cmp_gt_f32_e32 vcc, 0, v94
	v_pk_mul_f32 v[88:89], v[90:91], v[88:89]
	v_pk_fma_f32 v[112:113], v[112:113], s[56:57], 1.0 op_sel_hi:[1,0,0]
	v_pk_mul_f32 v[90:91], v[94:95], v[88:89]
	v_pk_fma_f32 v[104:105], v[94:95], v[88:89], v[94:95] neg_lo:[1,0,0] neg_hi:[1,0,0]
	v_rcp_f32_e32 v112, v112
	v_cndmask_b32_e32 v89, v104, v90, vcc
	v_cmp_gt_f32_e32 vcc, 0, v100
	v_rcp_f32_e32 v113, v113
	v_and_b32_e32 v104, 0x7fffffff, v108
	v_cndmask_b32_e32 v88, v110, v102, vcc
	v_cmp_gt_f32_e32 vcc, 0, v95
	v_pk_fma_f32 v[94:95], v[112:113], s[0:1], v[92:93] op_sel_hi:[1,0,0]
	v_pk_mul_f32 v[84:85], v[84:85], v[166:167] op_sel_hi:[1,0]
	v_cndmask_b32_e32 v91, v105, v91, vcc
	v_cmp_gt_f32_e32 vcc, 0, v101
	v_and_b32_e32 v105, 0x7fffffff, v109
	v_pk_fma_f32 v[94:95], v[112:113], v[94:95], s[2:3] op_sel_hi:[1,1,0]
	v_cndmask_b32_e32 v90, v111, v103, vcc
	v_pk_mul_f32 v[102:103], v[106:107], v[106:107]
	v_pk_fma_f32 v[104:105], v[104:105], s[56:57], 1.0 op_sel_hi:[1,0,0]
	v_pk_mul_f32 v[102:103], v[102:103], s[86:87] op_sel_hi:[1,0]
	v_pk_fma_f32 v[94:95], v[112:113], v[94:95], s[4:5] op_sel_hi:[1,1,0]
	v_exp_f32_e32 v102, v102
	v_exp_f32_e32 v103, v103
	v_rcp_f32_e32 v104, v104
	v_rcp_f32_e32 v105, v105
	v_pk_fma_f32 v[94:95], v[112:113], v[94:95], s[88:89] op_sel_hi:[1,1,0]
	v_pk_mul_f32 v[100:101], v[108:109], v[108:109]
	v_pk_mul_f32 v[94:95], v[112:113], v[94:95]
	v_pk_mul_f32 v[100:101], v[100:101], s[86:87] op_sel_hi:[1,0]
	v_pk_mul_f32 v[94:95], v[102:103], v[94:95]
	v_exp_f32_e32 v100, v100
	v_pk_mul_f32 v[102:103], v[106:107], v[94:95]
	v_pk_fma_f32 v[110:111], v[106:107], v[94:95], v[106:107] neg_lo:[1,0,0] neg_hi:[1,0,0]
	v_pk_fma_f32 v[94:95], v[104:105], s[0:1], v[92:93] op_sel_hi:[1,0,0]
	v_exp_f32_e32 v101, v101
	v_pk_fma_f32 v[94:95], v[104:105], v[94:95], s[2:3] op_sel_hi:[1,1,0]
	v_pk_mul_f32 v[118:119], v[80:81], v[166:167] op_sel_hi:[1,0]
	v_pk_fma_f32 v[94:95], v[104:105], v[94:95], s[4:5] op_sel_hi:[1,1,0]
	v_pk_mul_f32 v[86:87], v[86:87], v[166:167] op_sel_hi:[1,0]
	v_pk_fma_f32 v[94:95], v[104:105], v[94:95], s[88:89] op_sel_hi:[1,1,0]
	v_and_b32_e32 v121, 0x7fffffff, v87
	v_pk_mul_f32 v[94:95], v[104:105], v[94:95]
	v_and_b32_e32 v120, 0x7fffffff, v86
	v_pk_mul_f32 v[94:95], v[100:101], v[94:95]
	v_and_b32_e32 v101, 0x7fffffff, v85
	v_and_b32_e32 v100, 0x7fffffff, v84
	v_pk_fma_f32 v[100:101], v[100:101], s[56:57], 1.0 op_sel_hi:[1,0,0]
	v_pk_fma_f32 v[120:121], v[120:121], s[56:57], 1.0 op_sel_hi:[1,0,0]
	v_rcp_f32_e32 v100, v100
	v_rcp_f32_e32 v101, v101
	v_rcp_f32_e32 v120, v120
	v_rcp_f32_e32 v121, v121
	v_pk_mul_f32 v[116:117], v[82:83], v[166:167] op_sel_hi:[1,0]
	v_pk_fma_f32 v[80:81], v[100:101], s[0:1], v[92:93] op_sel_hi:[1,0,0]
	v_pk_mul_f32 v[82:83], v[86:87], v[86:87]
	v_pk_fma_f32 v[80:81], v[100:101], v[80:81], s[2:3] op_sel_hi:[1,1,0]
	v_pk_mul_f32 v[82:83], v[82:83], s[86:87] op_sel_hi:[1,0]
	v_pk_fma_f32 v[80:81], v[100:101], v[80:81], s[4:5] op_sel_hi:[1,1,0]
	v_exp_f32_e32 v82, v82
	v_pk_fma_f32 v[80:81], v[100:101], v[80:81], s[88:89] op_sel_hi:[1,1,0]
	v_exp_f32_e32 v83, v83
	v_pk_mul_f32 v[80:81], v[100:101], v[80:81]
	v_pk_mul_f32 v[100:101], v[84:85], v[84:85]
	v_and_b32_e32 v125, 0x7fffffff, v119
	v_pk_mul_f32 v[100:101], v[100:101], s[86:87] op_sel_hi:[1,0]
	v_and_b32_e32 v124, 0x7fffffff, v118
	v_exp_f32_e32 v100, v100
	v_exp_f32_e32 v101, v101
	v_pk_fma_f32 v[124:125], v[124:125], s[56:57], 1.0 op_sel_hi:[1,0,0]
	v_pk_mul_f32 v[112:113], v[108:109], v[94:95]
	v_pk_fma_f32 v[114:115], v[108:109], v[94:95], v[108:109] neg_lo:[1,0,0] neg_hi:[1,0,0]
	v_pk_mul_f32 v[80:81], v[100:101], v[80:81]
	v_cmp_gt_f32_e32 vcc, 0, v109
	v_pk_mul_f32 v[100:101], v[84:85], v[80:81]
	v_pk_fma_f32 v[122:123], v[84:85], v[80:81], v[84:85] neg_lo:[1,0,0] neg_hi:[1,0,0]
	v_pk_fma_f32 v[80:81], v[120:121], s[0:1], v[92:93] op_sel_hi:[1,0,0]
	v_rcp_f32_e32 v124, v124
	v_pk_fma_f32 v[80:81], v[120:121], v[80:81], s[2:3] op_sel_hi:[1,1,0]
	v_rcp_f32_e32 v125, v125
	v_pk_fma_f32 v[80:81], v[120:121], v[80:81], s[4:5] op_sel_hi:[1,1,0]
	v_cndmask_b32_e32 v94, v115, v113, vcc
	v_pk_fma_f32 v[80:81], v[120:121], v[80:81], s[88:89] op_sel_hi:[1,1,0]
	v_cmp_gt_f32_e32 vcc, 0, v86
	v_pk_mul_f32 v[80:81], v[120:121], v[80:81]
	v_add_u32_e32 v96, 32, v140
	v_pk_mul_f32 v[80:81], v[82:83], v[80:81]
	v_ashrrev_i32_e32 v97, 31, v96
	v_pk_mul_f32 v[82:83], v[86:87], v[80:81]
	v_pk_fma_f32 v[120:121], v[86:87], v[80:81], v[86:87] neg_lo:[1,0,0] neg_hi:[1,0,0]
	s_waitcnt lgkmcnt(0)
; __device__ __forceinline__ u32x4 pack8(const f32x4& a, const f32x4& b) { u32x4 w; w.x = cvt_pk_bf16(a[0], a[1]); w.y = cvt_pk_bf16(a[2], a[3]); w.z = cvt_pk_bf16(b[0], b[1]); w.w = cvt_pk_bf16(b[2], b[3]); return w; }
; __device__ __forceinline__ f32x2 gelu_pk(f32x2 v) {
;     const f32x2 av = __builtin_elementwise_abs(v), d = av * 0.2316418882f + 1.0f;
;     f32x2 t; t.x = __builtin_amdgcn_rcpf(d.x); t.y = __builtin_amdgcn_rcpf(d.y);
;     f32x2 q = t * 0.5307027145f + (-0.7265760135f); q = q * t + 0.7107068705f; q = q * t + (-0.142248368f); q = q * t + 0.127414796f; q = q * t;
;     const f32x2 s = (v * v) * (-0.72134752044f);
;     f32x2 e; e.x = __builtin_amdgcn_exp2f(s.x); e.y = __builtin_amdgcn_exp2f(s.y);
;     const f32x2 m = v * (q * e), r = v - m;
;     f32x2 o; o.x = v.x < 0.f ? m.x : r.x; o.y = v.y < 0.f ? m.y : r.y; return o;
;     __device__ __forceinline__ void operator()(const f32x4 (&acc)[2][2][4][2], const Unit& u, int ui, int wr, int wc, int fr, int fq) const {
;     ...
;             for (int m = 0; m < 4; ++m) { const float r = rs[ai][m]; const int row = row0 + ai * HALF + m * 16; bf16_t* rowp = Z + (size_t)row * 2048 + col0; float s1 = 0.f, s2 = 0.f;
; #pragma unroll
;                 for (int bj = 0; bj < 2; ++bj) { const f32x4 v0 = acc[ai][bj][m][0] * r, v1 = acc[ai][bj][m][1] * r;
;                     const f32x2 a = gelu_pk((f32x2){v0[0], v0[1]}), b = gelu_pk((f32x2){v0[2], v0[3]}), c = gelu_pk((f32x2){v1[0], v1[1]}), d = gelu_pk((f32x2){v1[2], v1[3]});
;                     const f32x4 z0 = (f32x4){a.x, a.y, b.x, b.y}, z1 = (f32x4){c.x, c.y, d.x, d.y};
;                     *(u32x4*)(rowp + bj * HALF) = pack8(z0, z1);
;                     s1 += (z0[0] + z0[1]) + (z0[2] + z0[3]) + (z1[0] + z1[1]) + (z1[2] + z1[3]);
;                     s2 += (z0[0] * z0[0] + z0[1] * z0[1]) + (z0[2] * z0[2] + z0[3] * z0[3]) + (z1[0] * z1[0] + z1[1] * z1[1]) + (z1[2] * z1[2] + z1[3] * z1[3]); }
;                 if (u.pn >= 4) { s1 += __shfl_xor(s1, 16); s1 += __shfl_xor(s1, 32); s2 += __shfl_xor(s2, 16); s2 += __shfl_xor(s2, 32);
;                     if (fq == 0) vst[(size_t)row * 16 + (u.pn - 4) * 4 + wc] = (f32x2){s1, s2}; } }
	v_lshlrev_b64 v[98:99], 12, v[96:97]
	v_cndmask_b32_e32 v81, v120, v82, vcc
	v_cmp_gt_f32_e32 vcc, 0, v84
	v_lshl_add_u64 v[98:99], s[20:21], 0, v[98:99]
	v_lshl_add_u64 v[98:99], v[162:163], 1, v[98:99]
	v_cndmask_b32_e32 v80, v122, v100, vcc
	v_cmp_gt_f32_e32 vcc, 0, v87
	v_pk_mul_f32 v[86:87], v[118:119], v[118:119]
	v_cvt_pk_bf16_f32 v104, v88, v90
	v_cvt_pk_bf16_f32 v105, v89, v91
	s_nop 0
	v_cndmask_b32_e32 v83, v121, v83, vcc
	v_cmp_gt_f32_e32 vcc, 0, v85
	v_pk_fma_f32 v[84:85], v[124:125], s[0:1], v[92:93] op_sel_hi:[1,0,0]
	v_pk_mul_f32 v[86:87], v[86:87], s[86:87] op_sel_hi:[1,0]
	v_pk_fma_f32 v[84:85], v[124:125], v[84:85], s[2:3] op_sel_hi:[1,1,0]
	v_exp_f32_e32 v86, v86
	v_exp_f32_e32 v87, v87
	v_pk_fma_f32 v[84:85], v[124:125], v[84:85], s[4:5] op_sel_hi:[1,1,0]
	v_cndmask_b32_e32 v82, v123, v101, vcc
	v_pk_fma_f32 v[84:85], v[124:125], v[84:85], s[88:89] op_sel_hi:[1,1,0]
	v_cmp_gt_f32_e32 vcc, 0, v106
	v_pk_mul_f32 v[84:85], v[124:125], v[84:85]
	v_pk_mul_f32 v[120:121], v[116:117], v[116:117]
	v_pk_mul_f32 v[84:85], v[86:87], v[84:85]
	v_cndmask_b32_e32 v86, v110, v102, vcc
	v_pk_mul_f32 v[100:101], v[118:119], v[84:85]
	v_pk_fma_f32 v[122:123], v[118:119], v[84:85], v[118:119] neg_lo:[1,0,0] neg_hi:[1,0,0]
	v_cmp_gt_f32_e32 vcc, 0, v118
	v_and_b32_e32 v102, 0x7fffffff, v116
	s_nop 0
	v_cndmask_b32_e32 v87, v122, v100, vcc
	v_cmp_gt_f32_e32 vcc, 0, v107
	s_nop 1
	v_cndmask_b32_e32 v100, v111, v103, vcc
	v_and_b32_e32 v103, 0x7fffffff, v117
	v_pk_fma_f32 v[102:103], v[102:103], s[56:57], 1.0 op_sel_hi:[1,0,0]
	v_cmp_gt_f32_e32 vcc, 0, v108
	v_rcp_f32_e32 v108, v102
	v_rcp_f32_e32 v109, v103
	v_cvt_pk_bf16_f32 v106, v86, v100
	v_cndmask_b32_e32 v85, v114, v112, vcc
	v_cvt_pk_bf16_f32 v107, v85, v94
	global_store_dwordx4 v[98:99], v[104:107], off nt
	v_pk_fma_f32 v[92:93], v[108:109], s[0:1], v[92:93] op_sel_hi:[1,0,0]
	v_cmp_gt_f32_e32 vcc, 0, v119
	v_pk_mul_f32 v[104:105], v[120:121], s[86:87] op_sel_hi:[1,0]
	v_pk_fma_f32 v[92:93], v[108:109], v[92:93], s[2:3] op_sel_hi:[1,1,0]
	v_exp_f32_e32 v104, v104
	v_exp_f32_e32 v105, v105
	v_pk_fma_f32 v[92:93], v[108:109], v[92:93], s[4:5] op_sel_hi:[1,1,0]
	v_cndmask_b32_e32 v102, v123, v101, vcc
	v_pk_fma_f32 v[92:93], v[108:109], v[92:93], s[88:89] op_sel_hi:[1,1,0]
	v_cmp_gt_f32_e32 vcc, 0, v117
	v_pk_mul_f32 v[92:93], v[108:109], v[92:93]
	s_nop 0
	v_pk_mul_f32 v[92:93], v[104:105], v[92:93]
	s_nop 0
	v_pk_mul_f32 v[104:105], v[116:117], v[92:93]
	v_pk_fma_f32 v[92:93], v[116:117], v[92:93], v[116:117] neg_lo:[1,0,0] neg_hi:[1,0,0]
	s_nop 0
	v_cndmask_b32_e32 v93, v93, v105, vcc
	v_cmp_gt_f32_e32 vcc, 0, v116
	s_nop 1
	v_cndmask_b32_e32 v92, v92, v104, vcc
	s_and_b64 vcc, exec, s[12:13]
	v_cvt_pk_bf16_f32 v104, v80, v82
	v_cvt_pk_bf16_f32 v105, v81, v83
	v_cvt_pk_bf16_f32 v106, v87, v102
	v_cvt_pk_bf16_f32 v107, v92, v93
	global_store_dwordx4 v[98:99], v[104:107], off offset:256 nt
	s_cbranch_vccnz .LBB0_764
	v_mov_b32_e32 v84, v87
	v_mov_b32_e32 v103, v85
	v_pk_add_f32 v[98:99], v[84:85], v[102:103]
	v_pk_mul_f32 v[104:105], v[84:85], v[102:103]
	v_mov_b32_e32 v106, v86
	v_mov_b32_e32 v107, v100
	v_mul_f32_e32 v84, v86, v86
	v_mov_b32_e32 v101, v87
	v_pk_fma_f32 v[106:107], v[106:107], v[106:107], v[84:85] op_sel_hi:[1,1,0]
	v_mul_f32_e32 v84, v92, v92
	v_pk_fma_f32 v[108:109], v[92:93], v[92:93], v[84:85] op_sel_hi:[1,1,0]
	v_mov_b32_e32 v110, v80
	v_mov_b32_e32 v111, v82
	v_mul_f32_e32 v84, v80, v80
	v_pk_add_f32 v[114:115], v[86:87], v[100:101]
	v_pk_mul_f32 v[86:87], v[86:87], v[100:101]
	v_mov_b32_e32 v99, v105
	v_pk_mul_f32 v[104:105], v[90:91], v[90:91]
	v_pk_fma_f32 v[110:111], v[110:111], v[110:111], v[84:85] op_sel_hi:[1,1,0]
	v_mov_b32_e32 v112, v81
	v_mov_b32_e32 v113, v83
	v_mul_f32_e32 v84, v81, v81
	v_mov_b32_e32 v115, v87
	v_pk_mul_f32 v[86:87], v[102:103], v[102:103]
	v_pk_add_f32 v[80:81], v[80:81], v[82:83]
	v_and_b32_e32 v83, 64, v192
	v_pk_fma_f32 v[104:105], v[88:89], v[88:89], v[104:105]
	v_pk_add_f32 v[88:89], v[88:89], v[90:91]
	v_xor_b32_e32 v82, 16, v192
	v_add_u32_e32 v87, 64, v83
	v_pk_fma_f32 v[112:113], v[112:113], v[112:113], v[84:85] op_sel_hi:[1,1,0]
	v_pk_add_f32 v[88:89], v[88:89], v[88:89] op_sel:[0,1] op_sel_hi:[1,0]
	v_cmp_lt_i32_e32 vcc, v82, v87
	v_mul_f32_e32 v116, v94, v94
	v_pk_add_f32 v[104:105], v[104:105], v[104:105] op_sel_hi:[0,1]
	v_cndmask_b32_e32 v82, v192, v82, vcc
	v_mov_b32_e32 v110, v85
	v_mov_b32_e32 v95, v113
	v_mov_b32_e32 v89, v86
	v_pk_add_f32 v[80:81], v[80:81], v[80:81] op_sel:[0,1] op_sel_hi:[1,0]
	v_lshlrev_b32_e32 v90, 2, v82
	v_pk_add_f32 v[82:83], v[110:111], v[94:95]
	v_pk_add_f32 v[84:85], v[114:115], v[88:89]
	v_mov_b32_e32 v106, v92
	v_mov_b32_e32 v104, v93
	v_mov_b32_e32 v81, v116
	v_pk_add_f32 v[82:83], v[84:85], v[82:83]
	v_mov_b32_e32 v147, v109
	v_pk_add_f32 v[84:85], v[106:107], v[104:105]
	v_pk_add_f32 v[80:81], v[98:99], v[80:81]
	v_pk_add_f32 v[82:83], v[82:83], v[146:147]
	v_pk_add_f32 v[80:81], v[80:81], v[84:85]
	v_xor_b32_e32 v84, 32, v192
	v_pk_add_f32 v[80:81], v[80:81], v[82:83]
	ds_bpermute_b32 v82, v90, v80
	ds_bpermute_b32 v83, v90, v81
	v_cmp_lt_i32_e32 vcc, v84, v87
	s_waitcnt lgkmcnt(0)
	v_pk_add_f32 v[80:81], v[80:81], v[82:83]
	v_cndmask_b32_e32 v84, v192, v84, vcc
	v_lshlrev_b32_e32 v84, 2, v84
	ds_bpermute_b32 v82, v84, v80
	ds_bpermute_b32 v83, v84, v81
	s_and_saveexec_b64 s[0:1], s[10:11]
	s_cbranch_execz .LBB0_763
	s_waitcnt lgkmcnt(0)
	v_pk_add_f32 v[80:81], v[80:81], v[82:83]
	v_lshlrev_b64 v[82:83], 7, v[96:97]
	v_lshl_add_u64 v[82:83], s[16:17], 0, v[82:83]
	v_lshl_add_u64 v[82:83], s[38:39], 3, v[82:83]
	s_lshl_b32 s88, s44, 3
	v_lshl_add_u64 v[82:83], v[82:83], 0, s[88:89]
	global_store_dwordx2 v[82:83], v[80:81], off

; __device__ __forceinline__ f32x2 gelu_pk(f32x2 v) {
;     const f32x2 av = __builtin_elementwise_abs(v), d = av * 0.2316418882f + 1.0f;
;     f32x2 t; t.x = __builtin_amdgcn_rcpf(d.x); t.y = __builtin_amdgcn_rcpf(d.y);
;     f32x2 q = t * 0.5307027145f + (-0.7265760135f); q = q * t + 0.7107068705f; q = q * t + (-0.142248368f); q = q * t + 0.127414796f; q = q * t;
;     const f32x2 s = (v * v) * (-0.72134752044f);
;     f32x2 e; e.x = __builtin_amdgcn_exp2f(s.x); e.y = __builtin_amdgcn_exp2f(s.y);
;     const f32x2 m = v * (q * e), r = v - m;
;     f32x2 o; o.x = v.x < 0.f ? m.x : r.x; o.y = v.y < 0.f ? m.y : r.y; return o;
;     __device__ __forceinline__ void operator()(const f32x4 (&acc)[2][2][4][2], const Unit& u, int ui, int wr, int wc, int fr, int fq) const {
;     ...
;             for (int m = 0; m < 4; ++m) { const float r = rs[ai][m]; const int row = row0 + ai * HALF + m * 16; bf16_t* rowp = Z + (size_t)row * 2048 + col0; float s1 = 0.f, s2 = 0.f;
; #pragma unroll
;                 for (int bj = 0; bj < 2; ++bj) { const f32x4 v0 = acc[ai][bj][m][0] * r, v1 = acc[ai][bj][m][1] * r;
;                     const f32x2 a = gelu_pk((f32x2){v0[0], v0[1]}), b = gelu_pk((f32x2){v0[2], v0[3]}), c = gelu_pk((f32x2){v1[0], v1[1]}), d = gelu_pk((f32x2){v1[2], v1[3]});
.LBB0_764:
	v_mov_b32_e32 v84, v167
	v_pk_mul_f32 v[86:87], v[76:77], v[84:85] op_sel_hi:[1,0]
	s_mov_b32 s0, 0xbf3a00e3
	v_and_b32_e32 v77, 0x7fffffff, v87
	v_and_b32_e32 v76, 0x7fffffff, v86
	v_pk_fma_f32 v[76:77], v[76:77], s[56:57], 1.0 op_sel_hi:[1,0,0]
	v_pk_mul_f32 v[90:91], v[72:73], v[84:85] op_sel_hi:[1,0]
	v_rcp_f32_e32 v88, v76
	v_rcp_f32_e32 v89, v77
	v_mov_b64_e32 v[76:77], s[0:1]
	s_mov_b32 s0, 0x3f07dc22
	s_mov_b32 s88, 0x3e027906
	v_pk_fma_f32 v[72:73], v[88:89], s[0:1], v[76:77] op_sel_hi:[1,0,0]
	v_pk_mul_f32 v[78:79], v[78:79], v[84:85] op_sel_hi:[1,0]
	v_pk_fma_f32 v[72:73], v[88:89], v[72:73], s[2:3] op_sel_hi:[1,1,0]
	v_and_b32_e32 v95, 0x7fffffff, v79
	v_pk_fma_f32 v[72:73], v[88:89], v[72:73], s[4:5] op_sel_hi:[1,1,0]
	v_and_b32_e32 v94, 0x7fffffff, v78
	v_pk_fma_f32 v[72:73], v[88:89], v[72:73], s[88:89] op_sel_hi:[1,1,0]
	v_pk_fma_f32 v[94:95], v[94:95], s[56:57], 1.0 op_sel_hi:[1,0,0]
	v_pk_mul_f32 v[72:73], v[88:89], v[72:73]
	v_pk_mul_f32 v[88:89], v[86:87], v[86:87]
	v_rcp_f32_e32 v94, v94
	v_pk_mul_f32 v[88:89], v[88:89], s[86:87] op_sel_hi:[1,0]
	v_rcp_f32_e32 v95, v95
	v_exp_f32_e32 v88, v88
	v_exp_f32_e32 v89, v89
	v_pk_mul_f32 v[92:93], v[74:75], v[84:85] op_sel_hi:[1,0]
	v_pk_mul_f32 v[74:75], v[78:79], v[78:79]
	v_pk_mul_f32 v[68:69], v[68:69], v[84:85] op_sel_hi:[1,0]
	v_pk_mul_f32 v[72:73], v[88:89], v[72:73]
	v_pk_mul_f32 v[74:75], v[74:75], s[86:87] op_sel_hi:[1,0]
	v_pk_mul_f32 v[88:89], v[86:87], v[72:73]
	v_pk_fma_f32 v[96:97], v[86:87], v[72:73], v[86:87] neg_lo:[1,0,0] neg_hi:[1,0,0]
	v_pk_fma_f32 v[72:73], v[94:95], s[0:1], v[76:77] op_sel_hi:[1,0,0]
	v_exp_f32_e32 v74, v74
	v_pk_fma_f32 v[72:73], v[94:95], v[72:73], s[2:3] op_sel_hi:[1,1,0]
	v_exp_f32_e32 v75, v75
	v_and_b32_e32 v101, 0x7fffffff, v69
	v_and_b32_e32 v100, 0x7fffffff, v68
	v_pk_fma_f32 v[72:73], v[94:95], v[72:73], s[4:5] op_sel_hi:[1,1,0]
	v_pk_fma_f32 v[100:101], v[100:101], s[56:57], 1.0 op_sel_hi:[1,0,0]
	v_pk_fma_f32 v[72:73], v[94:95], v[72:73], s[88:89] op_sel_hi:[1,1,0]
	v_rcp_f32_e32 v100, v100
	v_rcp_f32_e32 v101, v101
	v_pk_mul_f32 v[72:73], v[94:95], v[72:73]
	v_and_b32_e32 v99, 0x7fffffff, v91
	v_pk_mul_f32 v[72:73], v[74:75], v[72:73]
	v_and_b32_e32 v98, 0x7fffffff, v90
	v_pk_mul_f32 v[74:75], v[78:79], v[72:73]
	v_pk_fma_f32 v[94:95], v[78:79], v[72:73], v[78:79] neg_lo:[1,0,0] neg_hi:[1,0,0]
	v_cmp_gt_f32_e32 vcc, 0, v78
	v_pk_fma_f32 v[98:99], v[98:99], s[56:57], 1.0 op_sel_hi:[1,0,0]
	v_pk_mul_f32 v[70:71], v[70:71], v[84:85] op_sel_hi:[1,0]
	v_cndmask_b32_e32 v73, v94, v74, vcc
	v_cmp_gt_f32_e32 vcc, 0, v86
	v_rcp_f32_e32 v98, v98
	v_rcp_f32_e32 v99, v99
	v_pk_mul_f32 v[102:103], v[66:67], v[84:85] op_sel_hi:[1,0]
	v_pk_mul_f32 v[84:85], v[64:65], v[84:85] op_sel_hi:[1,0]
	v_pk_fma_f32 v[64:65], v[100:101], s[0:1], v[76:77] op_sel_hi:[1,0,0]
	v_cndmask_b32_e32 v72, v96, v88, vcc
	v_cmp_gt_f32_e32 vcc, 0, v79
	v_pk_fma_f32 v[64:65], v[100:101], v[64:65], s[2:3] op_sel_hi:[1,1,0]
	v_pk_fma_f32 v[78:79], v[98:99], s[0:1], v[76:77] op_sel_hi:[1,0,0]
	v_cndmask_b32_e32 v75, v95, v75, vcc
	v_cmp_gt_f32_e32 vcc, 0, v87
	v_pk_fma_f32 v[64:65], v[100:101], v[64:65], s[4:5] op_sel_hi:[1,1,0]
	v_and_b32_e32 v95, 0x7fffffff, v93
	v_cndmask_b32_e32 v74, v97, v89, vcc
	v_pk_mul_f32 v[88:89], v[90:91], v[90:91]
	v_pk_fma_f32 v[64:65], v[100:101], v[64:65], s[88:89] op_sel_hi:[1,1,0]
	v_pk_mul_f32 v[88:89], v[88:89], s[86:87] op_sel_hi:[1,0]
	v_and_b32_e32 v94, 0x7fffffff, v92
	v_pk_mul_f32 v[64:65], v[100:101], v[64:65]
	v_pk_mul_f32 v[100:101], v[68:69], v[68:69]
	v_pk_fma_f32 v[78:79], v[98:99], v[78:79], s[2:3] op_sel_hi:[1,1,0]
	v_exp_f32_e32 v88, v88
	v_exp_f32_e32 v89, v89
	v_pk_fma_f32 v[94:95], v[94:95], s[56:57], 1.0 op_sel_hi:[1,0,0]
	v_pk_mul_f32 v[100:101], v[100:101], s[86:87] op_sel_hi:[1,0]
	v_and_b32_e32 v105, 0x7fffffff, v71
	v_and_b32_e32 v104, 0x7fffffff, v70
	v_pk_fma_f32 v[78:79], v[98:99], v[78:79], s[4:5] op_sel_hi:[1,1,0]
	v_rcp_f32_e32 v94, v94
	v_rcp_f32_e32 v95, v95
	v_exp_f32_e32 v100, v100
	v_exp_f32_e32 v101, v101
	v_pk_fma_f32 v[104:105], v[104:105], s[56:57], 1.0 op_sel_hi:[1,0,0]
	v_pk_fma_f32 v[78:79], v[98:99], v[78:79], s[88:89] op_sel_hi:[1,1,0]
	v_rcp_f32_e32 v104, v104
	v_rcp_f32_e32 v105, v105
	v_pk_mul_f32 v[78:79], v[98:99], v[78:79]
	v_pk_mul_f32 v[86:87], v[92:93], v[92:93]
	v_pk_mul_f32 v[78:79], v[88:89], v[78:79]
	v_pk_mul_f32 v[86:87], v[86:87], s[86:87] op_sel_hi:[1,0]
	v_pk_mul_f32 v[96:97], v[90:91], v[78:79]
	v_pk_fma_f32 v[98:99], v[90:91], v[78:79], v[90:91] neg_lo:[1,0,0] neg_hi:[1,0,0]
	v_pk_fma_f32 v[78:79], v[94:95], s[0:1], v[76:77] op_sel_hi:[1,0,0]
	v_pk_mul_f32 v[66:67], v[70:71], v[70:71]
	v_pk_mul_f32 v[64:65], v[100:101], v[64:65]
	v_pk_fma_f32 v[78:79], v[94:95], v[78:79], s[2:3] op_sel_hi:[1,1,0]
	v_exp_f32_e32 v86, v86
	v_exp_f32_e32 v87, v87
	v_pk_mul_f32 v[100:101], v[68:69], v[64:65]
	v_pk_fma_f32 v[106:107], v[68:69], v[64:65], v[68:69] neg_lo:[1,0,0] neg_hi:[1,0,0]
	v_pk_fma_f32 v[64:65], v[104:105], s[0:1], v[76:77] op_sel_hi:[1,0,0]
	v_pk_mul_f32 v[66:67], v[66:67], s[86:87] op_sel_hi:[1,0]
	v_pk_fma_f32 v[78:79], v[94:95], v[78:79], s[4:5] op_sel_hi:[1,1,0]
	v_pk_fma_f32 v[64:65], v[104:105], v[64:65], s[2:3] op_sel_hi:[1,1,0]
	v_exp_f32_e32 v66, v66
	v_exp_f32_e32 v67, v67
	v_pk_fma_f32 v[78:79], v[94:95], v[78:79], s[88:89] op_sel_hi:[1,1,0]
	v_pk_fma_f32 v[64:65], v[104:105], v[64:65], s[4:5] op_sel_hi:[1,1,0]
	v_pk_mul_f32 v[78:79], v[94:95], v[78:79]
	v_pk_fma_f32 v[64:65], v[104:105], v[64:65], s[88:89] op_sel_hi:[1,1,0]
	v_and_b32_e32 v109, 0x7fffffff, v85
	v_and_b32_e32 v108, 0x7fffffff, v84
	v_pk_mul_f32 v[78:79], v[86:87], v[78:79]
	v_pk_mul_f32 v[64:65], v[104:105], v[64:65]
	v_pk_fma_f32 v[108:109], v[108:109], s[56:57], 1.0 op_sel_hi:[1,0,0]
	v_pk_mul_f32 v[86:87], v[92:93], v[78:79]
	v_pk_fma_f32 v[94:95], v[92:93], v[78:79], v[92:93] neg_lo:[1,0,0] neg_hi:[1,0,0]
	v_cmp_gt_f32_e32 vcc, 0, v93
	v_pk_mul_f32 v[64:65], v[66:67], v[64:65]
	v_rcp_f32_e32 v108, v108
	v_rcp_f32_e32 v109, v109
	v_cndmask_b32_e32 v78, v95, v87, vcc
	v_pk_mul_f32 v[66:67], v[70:71], v[64:65]
	v_pk_fma_f32 v[104:105], v[70:71], v[64:65], v[70:71] neg_lo:[1,0,0] neg_hi:[1,0,0]
	v_cmp_gt_f32_e32 vcc, 0, v70
	v_and_b32_e32 v87, 0x7fffffff, v103
	v_add_u32_e32 v80, 48, v140
	v_cndmask_b32_e32 v65, v104, v66, vcc
	v_cmp_gt_f32_e32 vcc, 0, v68
	v_ashrrev_i32_e32 v81, 31, v80
	s_waitcnt lgkmcnt(0)
; __device__ __forceinline__ u32x4 pack8(const f32x4& a, const f32x4& b) { u32x4 w; w.x = cvt_pk_bf16(a[0], a[1]); w.y = cvt_pk_bf16(a[2], a[3]); w.z = cvt_pk_bf16(b[0], b[1]); w.w = cvt_pk_bf16(b[2], b[3]); return w; }
; __device__ __forceinline__ f32x2 gelu_pk(f32x2 v) {
;     const f32x2 av = __builtin_elementwise_abs(v), d = av * 0.2316418882f + 1.0f;
;     f32x2 t; t.x = __builtin_amdgcn_rcpf(d.x); t.y = __builtin_amdgcn_rcpf(d.y);
;     f32x2 q = t * 0.5307027145f + (-0.7265760135f); q = q * t + 0.7107068705f; q = q * t + (-0.142248368f); q = q * t + 0.127414796f; q = q * t;
;     const f32x2 s = (v * v) * (-0.72134752044f);
;     f32x2 e; e.x = __builtin_amdgcn_exp2f(s.x); e.y = __builtin_amdgcn_exp2f(s.y);
;     const f32x2 m = v * (q * e), r = v - m;
;     f32x2 o; o.x = v.x < 0.f ? m.x : r.x; o.y = v.y < 0.f ? m.y : r.y; return o;
;     __device__ __forceinline__ void operator()(const f32x4 (&acc)[2][2][4][2], const Unit& u, int ui, int wr, int wc, int fr, int fq) const {
;     ...
;             for (int m = 0; m < 4; ++m) { const float r = rs[ai][m]; const int row = row0 + ai * HALF + m * 16; bf16_t* rowp = Z + (size_t)row * 2048 + col0; float s1 = 0.f, s2 = 0.f;
; #pragma unroll
;                 for (int bj = 0; bj < 2; ++bj) { const f32x4 v0 = acc[ai][bj][m][0] * r, v1 = acc[ai][bj][m][1] * r;
;                     const f32x2 a = gelu_pk((f32x2){v0[0], v0[1]}), b = gelu_pk((f32x2){v0[2], v0[3]}), c = gelu_pk((f32x2){v1[0], v1[1]}), d = gelu_pk((f32x2){v1[2], v1[3]});
;                     const f32x4 z0 = (f32x4){a.x, a.y, b.x, b.y}, z1 = (f32x4){c.x, c.y, d.x, d.y};
;                     *(u32x4*)(rowp + bj * HALF) = pack8(z0, z1);
;                     s1 += (z0[0] + z0[1]) + (z0[2] + z0[3]) + (z1[0] + z1[1]) + (z1[2] + z1[3]);
;                     s2 += (z0[0] * z0[0] + z0[1] * z0[1]) + (z0[2] * z0[2] + z0[3] * z0[3]) + (z1[0] * z1[0] + z1[1] * z1[1]) + (z1[2] * z1[2] + z1[3] * z1[3]); }
;                 if (u.pn >= 4) { s1 += __shfl_xor(s1, 16); s1 += __shfl_xor(s1, 32); s2 += __shfl_xor(s2, 16); s2 += __shfl_xor(s2, 32);
;                     if (fq == 0) vst[(size_t)row * 16 + (u.pn - 4) * 4 + wc] = (f32x2){s1, s2}; } }
	v_lshlrev_b64 v[82:83], 12, v[80:81]
	v_cndmask_b32_e32 v64, v106, v100, vcc
	v_cmp_gt_f32_e32 vcc, 0, v71
	v_pk_mul_f32 v[70:71], v[84:85], v[84:85]
	v_lshl_add_u64 v[82:83], s[20:21], 0, v[82:83]
	v_cndmask_b32_e32 v67, v105, v67, vcc
	v_cmp_gt_f32_e32 vcc, 0, v69
	v_pk_fma_f32 v[68:69], v[108:109], s[0:1], v[76:77] op_sel_hi:[1,0,0]
	v_pk_mul_f32 v[70:71], v[70:71], s[86:87] op_sel_hi:[1,0]
	v_pk_fma_f32 v[68:69], v[108:109], v[68:69], s[2:3] op_sel_hi:[1,1,0]
	v_exp_f32_e32 v70, v70
	v_exp_f32_e32 v71, v71
	v_pk_fma_f32 v[68:69], v[108:109], v[68:69], s[4:5] op_sel_hi:[1,1,0]
	v_cndmask_b32_e32 v66, v107, v101, vcc
	v_pk_fma_f32 v[68:69], v[108:109], v[68:69], s[88:89] op_sel_hi:[1,1,0]
	v_cmp_gt_f32_e32 vcc, 0, v90
	v_pk_mul_f32 v[68:69], v[108:109], v[68:69]
	v_lshl_add_u64 v[82:83], v[162:163], 1, v[82:83]
	v_pk_mul_f32 v[68:69], v[70:71], v[68:69]
	v_cndmask_b32_e32 v70, v98, v96, vcc
	v_pk_mul_f32 v[104:105], v[84:85], v[68:69]
	v_pk_fma_f32 v[106:107], v[84:85], v[68:69], v[84:85] neg_lo:[1,0,0] neg_hi:[1,0,0]
	v_cmp_gt_f32_e32 vcc, 0, v84
	v_cvt_pk_bf16_f32 v88, v72, v74
	v_cvt_pk_bf16_f32 v89, v73, v75
	v_pk_mul_f32 v[100:101], v[102:103], v[102:103]
	s_nop 0
	v_cndmask_b32_e32 v71, v106, v104, vcc
	v_cmp_gt_f32_e32 vcc, 0, v91
	s_nop 1
	v_cndmask_b32_e32 v84, v99, v97, vcc
	v_cmp_gt_f32_e32 vcc, 0, v92
	v_cvt_pk_bf16_f32 v90, v70, v84
	s_nop 1
	v_cndmask_b32_e32 v69, v94, v86, vcc
	v_and_b32_e32 v86, 0x7fffffff, v102
	v_pk_fma_f32 v[86:87], v[86:87], s[56:57], 1.0 op_sel_hi:[1,0,0]
	v_cvt_pk_bf16_f32 v91, v69, v78
	global_store_dwordx4 v[82:83], v[88:91], off nt
	v_rcp_f32_e32 v92, v86
	v_rcp_f32_e32 v93, v87
	v_pk_mul_f32 v[88:89], v[100:101], s[86:87] op_sel_hi:[1,0]
	v_cmp_gt_f32_e32 vcc, 0, v85
	v_exp_f32_e32 v88, v88
	v_pk_fma_f32 v[76:77], v[92:93], s[0:1], v[76:77] op_sel_hi:[1,0,0]
	v_exp_f32_e32 v89, v89
	v_pk_fma_f32 v[76:77], v[92:93], v[76:77], s[2:3] op_sel_hi:[1,1,0]
	v_cndmask_b32_e32 v86, v107, v105, vcc
	v_pk_fma_f32 v[76:77], v[92:93], v[76:77], s[4:5] op_sel_hi:[1,1,0]
	v_cmp_gt_f32_e32 vcc, 0, v103
	v_pk_fma_f32 v[76:77], v[92:93], v[76:77], s[88:89] op_sel_hi:[1,1,0]
	s_nop 0
	v_pk_mul_f32 v[76:77], v[92:93], v[76:77]
	s_nop 0
	v_pk_mul_f32 v[76:77], v[88:89], v[76:77]
	s_nop 0
	v_pk_mul_f32 v[88:89], v[102:103], v[76:77]
	v_pk_fma_f32 v[76:77], v[102:103], v[76:77], v[102:103] neg_lo:[1,0,0] neg_hi:[1,0,0]
	s_nop 0
	v_cndmask_b32_e32 v77, v77, v89, vcc
	v_cmp_gt_f32_e32 vcc, 0, v102
	s_nop 1
	v_cndmask_b32_e32 v76, v76, v88, vcc
	s_and_b64 vcc, exec, s[12:13]
	v_cvt_pk_bf16_f32 v88, v64, v66
	v_cvt_pk_bf16_f32 v89, v65, v67
	v_cvt_pk_bf16_f32 v90, v71, v86
	v_cvt_pk_bf16_f32 v91, v76, v77
	global_store_dwordx4 v[82:83], v[88:91], off offset:256 nt
	s_cbranch_vccnz .LBB0_768
	v_mov_b32_e32 v68, v71
	v_mov_b32_e32 v87, v69
	v_pk_add_f32 v[82:83], v[68:69], v[86:87]
	v_pk_mul_f32 v[88:89], v[68:69], v[86:87]
	v_mov_b32_e32 v90, v70
	v_mov_b32_e32 v91, v84
	v_mul_f32_e32 v68, v70, v70
	v_mov_b32_e32 v85, v71
	v_pk_fma_f32 v[90:91], v[90:91], v[90:91], v[68:69] op_sel_hi:[1,1,0]
	v_mul_f32_e32 v68, v76, v76
	v_pk_fma_f32 v[92:93], v[76:77], v[76:77], v[68:69] op_sel_hi:[1,1,0]
	v_mov_b32_e32 v94, v64
	v_mov_b32_e32 v95, v66
	v_mul_f32_e32 v68, v64, v64
	v_pk_add_f32 v[98:99], v[70:71], v[84:85]
	v_pk_mul_f32 v[70:71], v[70:71], v[84:85]
	v_mov_b32_e32 v83, v89
	v_pk_mul_f32 v[88:89], v[74:75], v[74:75]
	v_pk_fma_f32 v[94:95], v[94:95], v[94:95], v[68:69] op_sel_hi:[1,1,0]
	v_mov_b32_e32 v96, v65
	v_mov_b32_e32 v97, v67
	v_mul_f32_e32 v68, v65, v65
	v_mov_b32_e32 v99, v71
	v_pk_mul_f32 v[70:71], v[86:87], v[86:87]
	v_pk_add_f32 v[64:65], v[64:65], v[66:67]
	v_and_b32_e32 v67, 64, v192
	v_pk_fma_f32 v[88:89], v[72:73], v[72:73], v[88:89]
	v_pk_add_f32 v[72:73], v[72:73], v[74:75]
	v_xor_b32_e32 v66, 16, v192
	v_add_u32_e32 v71, 64, v67
	v_pk_fma_f32 v[96:97], v[96:97], v[96:97], v[68:69] op_sel_hi:[1,1,0]
	v_pk_add_f32 v[72:73], v[72:73], v[72:73] op_sel:[0,1] op_sel_hi:[1,0]
	v_cmp_lt_i32_e32 vcc, v66, v71
	v_mul_f32_e32 v100, v78, v78
	v_pk_add_f32 v[88:89], v[88:89], v[88:89] op_sel_hi:[0,1]
	v_cndmask_b32_e32 v66, v192, v66, vcc
	v_mov_b32_e32 v94, v69
	v_mov_b32_e32 v79, v97
	v_mov_b32_e32 v73, v70
	v_pk_add_f32 v[64:65], v[64:65], v[64:65] op_sel:[0,1] op_sel_hi:[1,0]
	v_lshlrev_b32_e32 v74, 2, v66
	v_pk_add_f32 v[66:67], v[94:95], v[78:79]
	v_pk_add_f32 v[68:69], v[98:99], v[72:73]
	v_mov_b32_e32 v90, v76
	v_mov_b32_e32 v88, v77
	v_mov_b32_e32 v65, v100
	v_pk_add_f32 v[66:67], v[68:69], v[66:67]
	v_mov_b32_e32 v147, v93
	v_pk_add_f32 v[68:69], v[90:91], v[88:89]
	v_pk_add_f32 v[64:65], v[82:83], v[64:65]
	v_pk_add_f32 v[66:67], v[66:67], v[146:147]
	v_pk_add_f32 v[64:65], v[64:65], v[68:69]
	v_xor_b32_e32 v68, 32, v192
	v_pk_add_f32 v[64:65], v[64:65], v[66:67]
	ds_bpermute_b32 v66, v74, v64
	ds_bpermute_b32 v67, v74, v65
	v_cmp_lt_i32_e32 vcc, v68, v71
	s_waitcnt lgkmcnt(0)
	v_pk_add_f32 v[64:65], v[64:65], v[66:67]
	v_cndmask_b32_e32 v68, v192, v68, vcc
	v_lshlrev_b32_e32 v68, 2, v68
	ds_bpermute_b32 v66, v68, v64
	ds_bpermute_b32 v67, v68, v65
	s_and_saveexec_b64 s[0:1], s[10:11]
	s_cbranch_execz .LBB0_767
	s_waitcnt lgkmcnt(0)
	v_pk_add_f32 v[64:65], v[64:65], v[66:67]
	v_lshlrev_b64 v[66:67], 7, v[80:81]
	v_lshl_add_u64 v[66:67], s[16:17], 0, v[66:67]
	v_lshl_add_u64 v[66:67], s[38:39], 3, v[66:67]
	s_lshl_b32 s88, s44, 3
	v_lshl_add_u64 v[66:67], v[66:67], 0, s[88:89]
	global_store_dwordx2 v[66:67], v[64:65], off

; __device__ __forceinline__ f32x2 gelu_pk(f32x2 v) {
;     const f32x2 av = __builtin_elementwise_abs(v), d = av * 0.2316418882f + 1.0f;
;     f32x2 t; t.x = __builtin_amdgcn_rcpf(d.x); t.y = __builtin_amdgcn_rcpf(d.y);
;     f32x2 q = t * 0.5307027145f + (-0.7265760135f); q = q * t + 0.7107068705f; q = q * t + (-0.142248368f); q = q * t + 0.127414796f; q = q * t;
;     const f32x2 s = (v * v) * (-0.72134752044f);
;     f32x2 e; e.x = __builtin_amdgcn_exp2f(s.x); e.y = __builtin_amdgcn_exp2f(s.y);
;     const f32x2 m = v * (q * e), r = v - m;
;     f32x2 o; o.x = v.x < 0.f ? m.x : r.x; o.y = v.y < 0.f ? m.y : r.y; return o;
;     __device__ __forceinline__ void operator()(const f32x4 (&acc)[2][2][4][2], const Unit& u, int ui, int wr, int wc, int fr, int fq) const {
;     ...
;             for (int m = 0; m < 4; ++m) { const float r = rs[ai][m]; const int row = row0 + ai * HALF + m * 16; bf16_t* rowp = Z + (size_t)row * 2048 + col0; float s1 = 0.f, s2 = 0.f;
; #pragma unroll
;                 for (int bj = 0; bj < 2; ++bj) { const f32x4 v0 = acc[ai][bj][m][0] * r, v1 = acc[ai][bj][m][1] * r;
;                     const f32x2 a = gelu_pk((f32x2){v0[0], v0[1]}), b = gelu_pk((f32x2){v0[2], v0[3]}), c = gelu_pk((f32x2){v1[0], v1[1]}), d = gelu_pk((f32x2){v1[2], v1[3]});
.LBB0_768:
	v_pk_mul_f32 v[68:69], v[60:61], v[164:165] op_sel_hi:[1,0]
	s_mov_b32 s0, 0xbf3a00e3
	v_and_b32_e32 v61, 0x7fffffff, v69
	v_and_b32_e32 v60, 0x7fffffff, v68
	v_pk_fma_f32 v[60:61], v[60:61], s[56:57], 1.0 op_sel_hi:[1,0,0]
	v_pk_mul_f32 v[74:75], v[56:57], v[164:165] op_sel_hi:[1,0]
	v_rcp_f32_e32 v70, v60
	v_rcp_f32_e32 v71, v61
	v_mov_b64_e32 v[60:61], s[0:1]
	s_mov_b32 s0, 0x3f07dc22
	s_mov_b32 s88, 0x3e027906
	v_pk_fma_f32 v[56:57], v[70:71], s[0:1], v[60:61] op_sel_hi:[1,0,0]
	v_pk_mul_f32 v[62:63], v[62:63], v[164:165] op_sel_hi:[1,0]
	v_pk_fma_f32 v[56:57], v[70:71], v[56:57], s[2:3] op_sel_hi:[1,1,0]
	v_and_b32_e32 v73, 0x7fffffff, v63
	v_pk_fma_f32 v[56:57], v[70:71], v[56:57], s[4:5] op_sel_hi:[1,1,0]
	v_and_b32_e32 v72, 0x7fffffff, v62
	v_pk_fma_f32 v[56:57], v[70:71], v[56:57], s[88:89] op_sel_hi:[1,1,0]
	v_pk_fma_f32 v[72:73], v[72:73], s[56:57], 1.0 op_sel_hi:[1,0,0]
	v_pk_mul_f32 v[56:57], v[70:71], v[56:57]
	v_pk_mul_f32 v[70:71], v[68:69], v[68:69]
	v_rcp_f32_e32 v72, v72
	v_pk_mul_f32 v[70:71], v[70:71], s[86:87] op_sel_hi:[1,0]
	v_rcp_f32_e32 v73, v73
	v_exp_f32_e32 v70, v70
	v_exp_f32_e32 v71, v71
	v_pk_mul_f32 v[76:77], v[58:59], v[164:165] op_sel_hi:[1,0]
	v_pk_mul_f32 v[58:59], v[62:63], v[62:63]
	v_and_b32_e32 v81, 0x7fffffff, v75
	v_pk_mul_f32 v[56:57], v[70:71], v[56:57]
	v_pk_mul_f32 v[58:59], v[58:59], s[86:87] op_sel_hi:[1,0]
	v_pk_mul_f32 v[70:71], v[68:69], v[56:57]
	v_pk_fma_f32 v[78:79], v[68:69], v[56:57], v[68:69] neg_lo:[1,0,0] neg_hi:[1,0,0]
	v_pk_fma_f32 v[56:57], v[72:73], s[0:1], v[60:61] op_sel_hi:[1,0,0]
	v_exp_f32_e32 v58, v58
	v_pk_fma_f32 v[56:57], v[72:73], v[56:57], s[2:3] op_sel_hi:[1,1,0]
	v_exp_f32_e32 v59, v59
	v_pk_fma_f32 v[56:57], v[72:73], v[56:57], s[4:5] op_sel_hi:[1,1,0]
	v_and_b32_e32 v80, 0x7fffffff, v74
	v_pk_fma_f32 v[56:57], v[72:73], v[56:57], s[88:89] op_sel_hi:[1,1,0]
	v_cmp_gt_f32_e32 vcc, 0, v62
	v_pk_mul_f32 v[56:57], v[72:73], v[56:57]
	v_pk_fma_f32 v[80:81], v[80:81], s[56:57], 1.0 op_sel_hi:[1,0,0]
	v_pk_mul_f32 v[56:57], v[58:59], v[56:57]
	v_rcp_f32_e32 v80, v80
	v_pk_mul_f32 v[58:59], v[62:63], v[56:57]
	v_pk_fma_f32 v[72:73], v[62:63], v[56:57], v[62:63] neg_lo:[1,0,0] neg_hi:[1,0,0]
	v_rcp_f32_e32 v81, v81
	v_cndmask_b32_e32 v57, v72, v58, vcc
	v_cmp_gt_f32_e32 vcc, 0, v68
	v_and_b32_e32 v72, 0x7fffffff, v76
	v_pk_mul_f32 v[52:53], v[52:53], v[164:165] op_sel_hi:[1,0]
	v_cndmask_b32_e32 v56, v78, v70, vcc
	v_cmp_gt_f32_e32 vcc, 0, v63
	v_pk_fma_f32 v[62:63], v[80:81], s[0:1], v[60:61] op_sel_hi:[1,0,0]
	v_pk_mul_f32 v[86:87], v[48:49], v[164:165] op_sel_hi:[1,0]
	v_cndmask_b32_e32 v59, v73, v59, vcc
	v_cmp_gt_f32_e32 vcc, 0, v69
	v_and_b32_e32 v73, 0x7fffffff, v77
	v_pk_fma_f32 v[62:63], v[80:81], v[62:63], s[2:3] op_sel_hi:[1,1,0]
	v_cndmask_b32_e32 v58, v79, v71, vcc
	v_pk_mul_f32 v[70:71], v[74:75], v[74:75]
	v_pk_fma_f32 v[72:73], v[72:73], s[56:57], 1.0 op_sel_hi:[1,0,0]
	v_pk_mul_f32 v[70:71], v[70:71], s[86:87] op_sel_hi:[1,0]
	v_pk_fma_f32 v[62:63], v[80:81], v[62:63], s[4:5] op_sel_hi:[1,1,0]
	v_exp_f32_e32 v70, v70
	v_exp_f32_e32 v71, v71
	v_rcp_f32_e32 v72, v72
	v_rcp_f32_e32 v73, v73
	v_pk_fma_f32 v[62:63], v[80:81], v[62:63], s[88:89] op_sel_hi:[1,1,0]
	v_pk_mul_f32 v[68:69], v[76:77], v[76:77]
	v_pk_mul_f32 v[62:63], v[80:81], v[62:63]
	v_pk_mul_f32 v[68:69], v[68:69], s[86:87] op_sel_hi:[1,0]
	v_pk_mul_f32 v[62:63], v[70:71], v[62:63]
	v_exp_f32_e32 v68, v68
	v_pk_mul_f32 v[70:71], v[74:75], v[62:63]
	v_pk_fma_f32 v[78:79], v[74:75], v[62:63], v[74:75] neg_lo:[1,0,0] neg_hi:[1,0,0]
	v_pk_fma_f32 v[62:63], v[72:73], s[0:1], v[60:61] op_sel_hi:[1,0,0]
	v_exp_f32_e32 v69, v69
	v_pk_fma_f32 v[62:63], v[72:73], v[62:63], s[2:3] op_sel_hi:[1,1,0]
	v_pk_mul_f32 v[54:55], v[54:55], v[164:165] op_sel_hi:[1,0]
	v_pk_fma_f32 v[62:63], v[72:73], v[62:63], s[4:5] op_sel_hi:[1,1,0]
	v_and_b32_e32 v89, 0x7fffffff, v55
	v_pk_fma_f32 v[62:63], v[72:73], v[62:63], s[88:89] op_sel_hi:[1,1,0]
	v_and_b32_e32 v88, 0x7fffffff, v54
	v_pk_mul_f32 v[62:63], v[72:73], v[62:63]
	v_pk_fma_f32 v[88:89], v[88:89], s[56:57], 1.0 op_sel_hi:[1,0,0]
	v_pk_mul_f32 v[62:63], v[68:69], v[62:63]
	v_and_b32_e32 v69, 0x7fffffff, v53
	v_and_b32_e32 v68, 0x7fffffff, v52
	v_pk_fma_f32 v[68:69], v[68:69], s[56:57], 1.0 op_sel_hi:[1,0,0]
	v_rcp_f32_e32 v88, v88
	v_rcp_f32_e32 v68, v68
	v_rcp_f32_e32 v69, v69
	v_rcp_f32_e32 v89, v89
	v_pk_mul_f32 v[84:85], v[50:51], v[164:165] op_sel_hi:[1,0]
	v_pk_mul_f32 v[50:51], v[54:55], v[54:55]
	v_pk_fma_f32 v[48:49], v[68:69], s[0:1], v[60:61] op_sel_hi:[1,0,0]
	v_pk_mul_f32 v[50:51], v[50:51], s[86:87] op_sel_hi:[1,0]
	v_pk_fma_f32 v[48:49], v[68:69], v[48:49], s[2:3] op_sel_hi:[1,1,0]
	v_exp_f32_e32 v50, v50
	v_pk_fma_f32 v[48:49], v[68:69], v[48:49], s[4:5] op_sel_hi:[1,1,0]
	v_exp_f32_e32 v51, v51
	v_pk_fma_f32 v[48:49], v[68:69], v[48:49], s[88:89] op_sel_hi:[1,1,0]
	v_and_b32_e32 v93, 0x7fffffff, v87
	v_pk_mul_f32 v[48:49], v[68:69], v[48:49]
	v_pk_mul_f32 v[68:69], v[52:53], v[52:53]
	v_and_b32_e32 v92, 0x7fffffff, v86
	v_pk_mul_f32 v[68:69], v[68:69], s[86:87] op_sel_hi:[1,0]
	v_pk_fma_f32 v[92:93], v[92:93], s[56:57], 1.0 op_sel_hi:[1,0,0]
	v_exp_f32_e32 v68, v68
	v_exp_f32_e32 v69, v69
	v_pk_mul_f32 v[80:81], v[76:77], v[62:63]
	v_pk_fma_f32 v[82:83], v[76:77], v[62:63], v[76:77] neg_lo:[1,0,0] neg_hi:[1,0,0]
	v_cmp_gt_f32_e32 vcc, 0, v77
	v_pk_mul_f32 v[48:49], v[68:69], v[48:49]
	v_rcp_f32_e32 v92, v92
	v_pk_mul_f32 v[68:69], v[52:53], v[48:49]
	v_pk_fma_f32 v[90:91], v[52:53], v[48:49], v[52:53] neg_lo:[1,0,0] neg_hi:[1,0,0]
	v_pk_fma_f32 v[48:49], v[88:89], s[0:1], v[60:61] op_sel_hi:[1,0,0]
	v_rcp_f32_e32 v93, v93
	v_pk_fma_f32 v[48:49], v[88:89], v[48:49], s[2:3] op_sel_hi:[1,1,0]
	v_cndmask_b32_e32 v62, v83, v81, vcc
	v_pk_fma_f32 v[48:49], v[88:89], v[48:49], s[4:5] op_sel_hi:[1,1,0]
	v_cmp_gt_f32_e32 vcc, 0, v54
	v_pk_fma_f32 v[48:49], v[88:89], v[48:49], s[88:89] op_sel_hi:[1,1,0]
	v_add_u32_e32 v64, 0x80, v140
	v_pk_mul_f32 v[48:49], v[88:89], v[48:49]
	v_ashrrev_i32_e32 v65, 31, v64
	v_pk_mul_f32 v[48:49], v[50:51], v[48:49]
	s_waitcnt lgkmcnt(0)
; __device__ __forceinline__ u32x4 pack8(const f32x4& a, const f32x4& b) { u32x4 w; w.x = cvt_pk_bf16(a[0], a[1]); w.y = cvt_pk_bf16(a[2], a[3]); w.z = cvt_pk_bf16(b[0], b[1]); w.w = cvt_pk_bf16(b[2], b[3]); return w; }
; __device__ __forceinline__ f32x2 gelu_pk(f32x2 v) {
;     const f32x2 av = __builtin_elementwise_abs(v), d = av * 0.2316418882f + 1.0f;
;     f32x2 t; t.x = __builtin_amdgcn_rcpf(d.x); t.y = __builtin_amdgcn_rcpf(d.y);
;     f32x2 q = t * 0.5307027145f + (-0.7265760135f); q = q * t + 0.7107068705f; q = q * t + (-0.142248368f); q = q * t + 0.127414796f; q = q * t;
;     const f32x2 s = (v * v) * (-0.72134752044f);
;     f32x2 e; e.x = __builtin_amdgcn_exp2f(s.x); e.y = __builtin_amdgcn_exp2f(s.y);
;     const f32x2 m = v * (q * e), r = v - m;
;     f32x2 o; o.x = v.x < 0.f ? m.x : r.x; o.y = v.y < 0.f ? m.y : r.y; return o;
;     __device__ __forceinline__ void operator()(const f32x4 (&acc)[2][2][4][2], const Unit& u, int ui, int wr, int wc, int fr, int fq) const {
;     ...
;             for (int m = 0; m < 4; ++m) { const float r = rs[ai][m]; const int row = row0 + ai * HALF + m * 16; bf16_t* rowp = Z + (size_t)row * 2048 + col0; float s1 = 0.f, s2 = 0.f;
; #pragma unroll
;                 for (int bj = 0; bj < 2; ++bj) { const f32x4 v0 = acc[ai][bj][m][0] * r, v1 = acc[ai][bj][m][1] * r;
;                     const f32x2 a = gelu_pk((f32x2){v0[0], v0[1]}), b = gelu_pk((f32x2){v0[2], v0[3]}), c = gelu_pk((f32x2){v1[0], v1[1]}), d = gelu_pk((f32x2){v1[2], v1[3]});
;                     const f32x4 z0 = (f32x4){a.x, a.y, b.x, b.y}, z1 = (f32x4){c.x, c.y, d.x, d.y};
;                     *(u32x4*)(rowp + bj * HALF) = pack8(z0, z1);
;                     s1 += (z0[0] + z0[1]) + (z0[2] + z0[3]) + (z1[0] + z1[1]) + (z1[2] + z1[3]);
;                     s2 += (z0[0] * z0[0] + z0[1] * z0[1]) + (z0[2] * z0[2] + z0[3] * z0[3]) + (z1[0] * z1[0] + z1[1] * z1[1]) + (z1[2] * z1[2] + z1[3] * z1[3]); }
;                 if (u.pn >= 4) { s1 += __shfl_xor(s1, 16); s1 += __shfl_xor(s1, 32); s2 += __shfl_xor(s2, 16); s2 += __shfl_xor(s2, 32);
;                     if (fq == 0) vst[(size_t)row * 16 + (u.pn - 4) * 4 + wc] = (f32x2){s1, s2}; } }
	v_lshlrev_b64 v[66:67], 12, v[64:65]
	v_pk_mul_f32 v[50:51], v[54:55], v[48:49]
	v_pk_fma_f32 v[88:89], v[54:55], v[48:49], v[54:55] neg_lo:[1,0,0] neg_hi:[1,0,0]
	v_lshl_add_u64 v[66:67], s[20:21], 0, v[66:67]
	v_cndmask_b32_e32 v49, v88, v50, vcc
	v_cmp_gt_f32_e32 vcc, 0, v52
	v_lshl_add_u64 v[66:67], v[162:163], 1, v[66:67]
	v_cvt_pk_bf16_f32 v72, v56, v58
	v_cvt_pk_bf16_f32 v73, v57, v59
	s_nop 0
	v_cndmask_b32_e32 v48, v90, v68, vcc
	v_cmp_gt_f32_e32 vcc, 0, v55
	v_pk_mul_f32 v[54:55], v[86:87], v[86:87]
	s_nop 0
	v_cndmask_b32_e32 v51, v89, v51, vcc
	v_cmp_gt_f32_e32 vcc, 0, v53
	v_pk_fma_f32 v[52:53], v[92:93], s[0:1], v[60:61] op_sel_hi:[1,0,0]
	v_pk_mul_f32 v[54:55], v[54:55], s[86:87] op_sel_hi:[1,0]
	v_pk_fma_f32 v[52:53], v[92:93], v[52:53], s[2:3] op_sel_hi:[1,1,0]
	v_exp_f32_e32 v54, v54
	v_exp_f32_e32 v55, v55
	v_pk_fma_f32 v[52:53], v[92:93], v[52:53], s[4:5] op_sel_hi:[1,1,0]
	v_cndmask_b32_e32 v50, v91, v69, vcc
	v_pk_fma_f32 v[52:53], v[92:93], v[52:53], s[88:89] op_sel_hi:[1,1,0]
	v_cmp_gt_f32_e32 vcc, 0, v74
	v_pk_mul_f32 v[52:53], v[92:93], v[52:53]
	v_pk_mul_f32 v[88:89], v[84:85], v[84:85]
	v_pk_mul_f32 v[52:53], v[54:55], v[52:53]
	v_cndmask_b32_e32 v54, v78, v70, vcc
	v_pk_mul_f32 v[68:69], v[86:87], v[52:53]
	v_pk_fma_f32 v[90:91], v[86:87], v[52:53], v[86:87] neg_lo:[1,0,0] neg_hi:[1,0,0]
	v_cmp_gt_f32_e32 vcc, 0, v86
	v_and_b32_e32 v70, 0x7fffffff, v84
	s_nop 0
	v_cndmask_b32_e32 v55, v90, v68, vcc
	v_cmp_gt_f32_e32 vcc, 0, v75
	s_nop 1
	v_cndmask_b32_e32 v68, v79, v71, vcc
	v_and_b32_e32 v71, 0x7fffffff, v85
	v_pk_fma_f32 v[70:71], v[70:71], s[56:57], 1.0 op_sel_hi:[1,0,0]
	v_cmp_gt_f32_e32 vcc, 0, v76
	v_rcp_f32_e32 v76, v70
	v_rcp_f32_e32 v77, v71
	v_cvt_pk_bf16_f32 v74, v54, v68
	v_cndmask_b32_e32 v53, v82, v80, vcc
	v_cvt_pk_bf16_f32 v75, v53, v62
	global_store_dwordx4 v[66:67], v[72:75], off nt
	v_pk_fma_f32 v[60:61], v[76:77], s[0:1], v[60:61] op_sel_hi:[1,0,0]
	v_cmp_gt_f32_e32 vcc, 0, v87
	v_pk_mul_f32 v[72:73], v[88:89], s[86:87] op_sel_hi:[1,0]
	v_pk_fma_f32 v[60:61], v[76:77], v[60:61], s[2:3] op_sel_hi:[1,1,0]
	v_exp_f32_e32 v72, v72
	v_exp_f32_e32 v73, v73
	v_pk_fma_f32 v[60:61], v[76:77], v[60:61], s[4:5] op_sel_hi:[1,1,0]
	v_cndmask_b32_e32 v70, v91, v69, vcc
	v_pk_fma_f32 v[60:61], v[76:77], v[60:61], s[88:89] op_sel_hi:[1,1,0]
	v_cmp_gt_f32_e32 vcc, 0, v85
	v_pk_mul_f32 v[60:61], v[76:77], v[60:61]
	s_nop 0
	v_pk_mul_f32 v[60:61], v[72:73], v[60:61]
	s_nop 0
	v_pk_mul_f32 v[72:73], v[84:85], v[60:61]
	v_pk_fma_f32 v[60:61], v[84:85], v[60:61], v[84:85] neg_lo:[1,0,0] neg_hi:[1,0,0]
	s_nop 0
	v_cndmask_b32_e32 v61, v61, v73, vcc
	v_cmp_gt_f32_e32 vcc, 0, v84
	s_nop 1
	v_cndmask_b32_e32 v60, v60, v72, vcc
	s_and_b64 vcc, exec, s[12:13]
	v_cvt_pk_bf16_f32 v72, v48, v50
	v_cvt_pk_bf16_f32 v73, v49, v51
	v_cvt_pk_bf16_f32 v74, v55, v70
	v_cvt_pk_bf16_f32 v75, v60, v61
	global_store_dwordx4 v[66:67], v[72:75], off offset:256 nt
	s_cbranch_vccnz .LBB0_772
	v_mov_b32_e32 v52, v55
	v_mov_b32_e32 v71, v53
	v_pk_add_f32 v[66:67], v[52:53], v[70:71]
	v_pk_mul_f32 v[72:73], v[52:53], v[70:71]
	v_mov_b32_e32 v74, v54
	v_mov_b32_e32 v75, v68
	v_mul_f32_e32 v52, v54, v54
	v_mov_b32_e32 v69, v55
	v_pk_fma_f32 v[74:75], v[74:75], v[74:75], v[52:53] op_sel_hi:[1,1,0]
	v_mul_f32_e32 v52, v60, v60
	v_pk_fma_f32 v[76:77], v[60:61], v[60:61], v[52:53] op_sel_hi:[1,1,0]
	v_mov_b32_e32 v78, v48
	v_mov_b32_e32 v79, v50
	v_mul_f32_e32 v52, v48, v48
	v_pk_add_f32 v[82:83], v[54:55], v[68:69]
	v_pk_mul_f32 v[54:55], v[54:55], v[68:69]
	v_mov_b32_e32 v67, v73
	v_pk_mul_f32 v[72:73], v[58:59], v[58:59]
	v_pk_fma_f32 v[78:79], v[78:79], v[78:79], v[52:53] op_sel_hi:[1,1,0]
	v_mov_b32_e32 v80, v49
	v_mov_b32_e32 v81, v51
	v_mul_f32_e32 v52, v49, v49
	v_mov_b32_e32 v83, v55
	v_pk_mul_f32 v[54:55], v[70:71], v[70:71]
	v_pk_add_f32 v[48:49], v[48:49], v[50:51]
	v_and_b32_e32 v51, 64, v192
	v_pk_fma_f32 v[72:73], v[56:57], v[56:57], v[72:73]
	v_pk_add_f32 v[56:57], v[56:57], v[58:59]
	v_xor_b32_e32 v50, 16, v192
	v_add_u32_e32 v55, 64, v51
	v_pk_fma_f32 v[80:81], v[80:81], v[80:81], v[52:53] op_sel_hi:[1,1,0]
	v_pk_add_f32 v[56:57], v[56:57], v[56:57] op_sel:[0,1] op_sel_hi:[1,0]
	v_cmp_lt_i32_e32 vcc, v50, v55
	v_mul_f32_e32 v84, v62, v62
	v_pk_add_f32 v[72:73], v[72:73], v[72:73] op_sel_hi:[0,1]
	v_cndmask_b32_e32 v50, v192, v50, vcc
	v_mov_b32_e32 v78, v53
	v_mov_b32_e32 v63, v81
	v_mov_b32_e32 v57, v54
	v_pk_add_f32 v[48:49], v[48:49], v[48:49] op_sel:[0,1] op_sel_hi:[1,0]
	v_lshlrev_b32_e32 v58, 2, v50
	v_pk_add_f32 v[50:51], v[78:79], v[62:63]
	v_pk_add_f32 v[52:53], v[82:83], v[56:57]
	v_mov_b32_e32 v74, v60
	v_mov_b32_e32 v72, v61
	v_mov_b32_e32 v49, v84
	v_pk_add_f32 v[50:51], v[52:53], v[50:51]
	v_mov_b32_e32 v147, v77
	v_pk_add_f32 v[52:53], v[74:75], v[72:73]
	v_pk_add_f32 v[48:49], v[66:67], v[48:49]
	v_pk_add_f32 v[50:51], v[50:51], v[146:147]
	v_pk_add_f32 v[48:49], v[48:49], v[52:53]
	v_xor_b32_e32 v52, 32, v192
	v_pk_add_f32 v[48:49], v[48:49], v[50:51]
	ds_bpermute_b32 v50, v58, v48
	ds_bpermute_b32 v51, v58, v49
	v_cmp_lt_i32_e32 vcc, v52, v55
	s_waitcnt lgkmcnt(0)
	v_pk_add_f32 v[48:49], v[48:49], v[50:51]
	v_cndmask_b32_e32 v52, v192, v52, vcc
	v_lshlrev_b32_e32 v52, 2, v52
	ds_bpermute_b32 v50, v52, v48
	ds_bpermute_b32 v51, v52, v49
	s_and_saveexec_b64 s[0:1], s[10:11]
	s_cbranch_execz .LBB0_771
	s_waitcnt lgkmcnt(0)
	v_pk_add_f32 v[48:49], v[48:49], v[50:51]
	v_lshlrev_b64 v[50:51], 7, v[64:65]
	v_lshl_add_u64 v[50:51], s[16:17], 0, v[50:51]
	v_lshl_add_u64 v[50:51], s[38:39], 3, v[50:51]
	s_lshl_b32 s88, s44, 3
	v_lshl_add_u64 v[50:51], v[50:51], 0, s[88:89]
	global_store_dwordx2 v[50:51], v[48:49], off

; __device__ __forceinline__ f32x2 gelu_pk(f32x2 v) {
;     const f32x2 av = __builtin_elementwise_abs(v), d = av * 0.2316418882f + 1.0f;
;     f32x2 t; t.x = __builtin_amdgcn_rcpf(d.x); t.y = __builtin_amdgcn_rcpf(d.y);
;     f32x2 q = t * 0.5307027145f + (-0.7265760135f); q = q * t + 0.7107068705f; q = q * t + (-0.142248368f); q = q * t + 0.127414796f; q = q * t;
;     const f32x2 s = (v * v) * (-0.72134752044f);
;     f32x2 e; e.x = __builtin_amdgcn_exp2f(s.x); e.y = __builtin_amdgcn_exp2f(s.y);
;     const f32x2 m = v * (q * e), r = v - m;
;     f32x2 o; o.x = v.x < 0.f ? m.x : r.x; o.y = v.y < 0.f ? m.y : r.y; return o;
;     __device__ __forceinline__ void operator()(const f32x4 (&acc)[2][2][4][2], const Unit& u, int ui, int wr, int wc, int fr, int fq) const {
;     ...
;             for (int m = 0; m < 4; ++m) { const float r = rs[ai][m]; const int row = row0 + ai * HALF + m * 16; bf16_t* rowp = Z + (size_t)row * 2048 + col0; float s1 = 0.f, s2 = 0.f;
; #pragma unroll
;                 for (int bj = 0; bj < 2; ++bj) { const f32x4 v0 = acc[ai][bj][m][0] * r, v1 = acc[ai][bj][m][1] * r;
;                     const f32x2 a = gelu_pk((f32x2){v0[0], v0[1]}), b = gelu_pk((f32x2){v0[2], v0[3]}), c = gelu_pk((f32x2){v1[0], v1[1]}), d = gelu_pk((f32x2){v1[2], v1[3]});
.LBB0_772:
	v_mov_b32_e32 v52, v165
	v_pk_mul_f32 v[54:55], v[44:45], v[52:53] op_sel_hi:[1,0]
	s_mov_b32 s0, 0xbf3a00e3
	v_and_b32_e32 v45, 0x7fffffff, v55
	v_and_b32_e32 v44, 0x7fffffff, v54
	v_pk_fma_f32 v[44:45], v[44:45], s[56:57], 1.0 op_sel_hi:[1,0,0]
	v_pk_mul_f32 v[58:59], v[40:41], v[52:53] op_sel_hi:[1,0]
	v_rcp_f32_e32 v56, v44
	v_rcp_f32_e32 v57, v45
	v_mov_b64_e32 v[44:45], s[0:1]
	s_mov_b32 s0, 0x3f07dc22
	s_mov_b32 s88, 0x3e027906
	v_pk_fma_f32 v[40:41], v[56:57], s[0:1], v[44:45] op_sel_hi:[1,0,0]
	v_pk_mul_f32 v[46:47], v[46:47], v[52:53] op_sel_hi:[1,0]
	v_pk_fma_f32 v[40:41], v[56:57], v[40:41], s[2:3] op_sel_hi:[1,1,0]
	v_and_b32_e32 v63, 0x7fffffff, v47
	v_pk_fma_f32 v[40:41], v[56:57], v[40:41], s[4:5] op_sel_hi:[1,1,0]
	v_and_b32_e32 v62, 0x7fffffff, v46
	v_pk_fma_f32 v[40:41], v[56:57], v[40:41], s[88:89] op_sel_hi:[1,1,0]
	v_pk_fma_f32 v[62:63], v[62:63], s[56:57], 1.0 op_sel_hi:[1,0,0]
	v_pk_mul_f32 v[40:41], v[56:57], v[40:41]
	v_pk_mul_f32 v[56:57], v[54:55], v[54:55]
	v_rcp_f32_e32 v62, v62
	v_pk_mul_f32 v[56:57], v[56:57], s[86:87] op_sel_hi:[1,0]
	v_rcp_f32_e32 v63, v63
	v_exp_f32_e32 v56, v56
	v_exp_f32_e32 v57, v57
	v_pk_mul_f32 v[60:61], v[42:43], v[52:53] op_sel_hi:[1,0]
	v_pk_mul_f32 v[42:43], v[46:47], v[46:47]
	v_pk_mul_f32 v[36:37], v[36:37], v[52:53] op_sel_hi:[1,0]
	v_pk_mul_f32 v[40:41], v[56:57], v[40:41]
	v_pk_mul_f32 v[42:43], v[42:43], s[86:87] op_sel_hi:[1,0]
	v_pk_mul_f32 v[56:57], v[54:55], v[40:41]
	v_pk_fma_f32 v[64:65], v[54:55], v[40:41], v[54:55] neg_lo:[1,0,0] neg_hi:[1,0,0]
	v_pk_fma_f32 v[40:41], v[62:63], s[0:1], v[44:45] op_sel_hi:[1,0,0]
	v_exp_f32_e32 v42, v42
	v_pk_fma_f32 v[40:41], v[62:63], v[40:41], s[2:3] op_sel_hi:[1,1,0]
	v_exp_f32_e32 v43, v43
	v_and_b32_e32 v69, 0x7fffffff, v37
	v_and_b32_e32 v68, 0x7fffffff, v36
	v_pk_fma_f32 v[40:41], v[62:63], v[40:41], s[4:5] op_sel_hi:[1,1,0]
	v_pk_fma_f32 v[68:69], v[68:69], s[56:57], 1.0 op_sel_hi:[1,0,0]
	v_pk_fma_f32 v[40:41], v[62:63], v[40:41], s[88:89] op_sel_hi:[1,1,0]
	v_rcp_f32_e32 v68, v68
	v_rcp_f32_e32 v69, v69
	v_pk_mul_f32 v[40:41], v[62:63], v[40:41]
	v_and_b32_e32 v67, 0x7fffffff, v59
	v_pk_mul_f32 v[40:41], v[42:43], v[40:41]
	v_and_b32_e32 v66, 0x7fffffff, v58
	v_pk_mul_f32 v[42:43], v[46:47], v[40:41]
	v_pk_fma_f32 v[62:63], v[46:47], v[40:41], v[46:47] neg_lo:[1,0,0] neg_hi:[1,0,0]
	v_cmp_gt_f32_e32 vcc, 0, v46
	v_pk_fma_f32 v[66:67], v[66:67], s[56:57], 1.0 op_sel_hi:[1,0,0]
	v_pk_mul_f32 v[38:39], v[38:39], v[52:53] op_sel_hi:[1,0]
	v_cndmask_b32_e32 v41, v62, v42, vcc
	v_cmp_gt_f32_e32 vcc, 0, v54
	v_rcp_f32_e32 v66, v66
	v_rcp_f32_e32 v67, v67
	v_pk_mul_f32 v[70:71], v[34:35], v[52:53] op_sel_hi:[1,0]
	v_pk_mul_f32 v[52:53], v[32:33], v[52:53] op_sel_hi:[1,0]
	v_pk_fma_f32 v[32:33], v[68:69], s[0:1], v[44:45] op_sel_hi:[1,0,0]
	v_cndmask_b32_e32 v40, v64, v56, vcc
	v_cmp_gt_f32_e32 vcc, 0, v47
	v_pk_fma_f32 v[32:33], v[68:69], v[32:33], s[2:3] op_sel_hi:[1,1,0]
	v_pk_fma_f32 v[46:47], v[66:67], s[0:1], v[44:45] op_sel_hi:[1,0,0]
	v_cndmask_b32_e32 v43, v63, v43, vcc
	v_cmp_gt_f32_e32 vcc, 0, v55
	v_pk_fma_f32 v[32:33], v[68:69], v[32:33], s[4:5] op_sel_hi:[1,1,0]
	v_and_b32_e32 v63, 0x7fffffff, v61
	v_cndmask_b32_e32 v42, v65, v57, vcc
	v_pk_mul_f32 v[56:57], v[58:59], v[58:59]
	v_pk_fma_f32 v[32:33], v[68:69], v[32:33], s[88:89] op_sel_hi:[1,1,0]
	v_pk_mul_f32 v[56:57], v[56:57], s[86:87] op_sel_hi:[1,0]
	v_and_b32_e32 v62, 0x7fffffff, v60
	v_pk_mul_f32 v[32:33], v[68:69], v[32:33]
	v_pk_mul_f32 v[68:69], v[36:37], v[36:37]
	v_pk_fma_f32 v[46:47], v[66:67], v[46:47], s[2:3] op_sel_hi:[1,1,0]
	v_exp_f32_e32 v56, v56
	v_exp_f32_e32 v57, v57
	v_pk_fma_f32 v[62:63], v[62:63], s[56:57], 1.0 op_sel_hi:[1,0,0]
	v_pk_mul_f32 v[68:69], v[68:69], s[86:87] op_sel_hi:[1,0]
	v_and_b32_e32 v73, 0x7fffffff, v39
	v_and_b32_e32 v72, 0x7fffffff, v38
	v_pk_fma_f32 v[46:47], v[66:67], v[46:47], s[4:5] op_sel_hi:[1,1,0]
	v_rcp_f32_e32 v62, v62
	v_rcp_f32_e32 v63, v63
	v_exp_f32_e32 v68, v68
	v_exp_f32_e32 v69, v69
	v_pk_fma_f32 v[72:73], v[72:73], s[56:57], 1.0 op_sel_hi:[1,0,0]
	v_pk_fma_f32 v[46:47], v[66:67], v[46:47], s[88:89] op_sel_hi:[1,1,0]
	v_rcp_f32_e32 v72, v72
	v_rcp_f32_e32 v73, v73
	v_pk_mul_f32 v[46:47], v[66:67], v[46:47]
	v_pk_mul_f32 v[54:55], v[60:61], v[60:61]
	v_pk_mul_f32 v[46:47], v[56:57], v[46:47]
	v_pk_mul_f32 v[54:55], v[54:55], s[86:87] op_sel_hi:[1,0]
	v_pk_mul_f32 v[64:65], v[58:59], v[46:47]
	v_pk_fma_f32 v[66:67], v[58:59], v[46:47], v[58:59] neg_lo:[1,0,0] neg_hi:[1,0,0]
	v_pk_fma_f32 v[46:47], v[62:63], s[0:1], v[44:45] op_sel_hi:[1,0,0]
	v_pk_mul_f32 v[34:35], v[38:39], v[38:39]
	v_pk_mul_f32 v[32:33], v[68:69], v[32:33]
	v_pk_fma_f32 v[46:47], v[62:63], v[46:47], s[2:3] op_sel_hi:[1,1,0]
	v_exp_f32_e32 v54, v54
	v_exp_f32_e32 v55, v55
	v_pk_mul_f32 v[68:69], v[36:37], v[32:33]
	v_pk_fma_f32 v[74:75], v[36:37], v[32:33], v[36:37] neg_lo:[1,0,0] neg_hi:[1,0,0]
	v_pk_fma_f32 v[32:33], v[72:73], s[0:1], v[44:45] op_sel_hi:[1,0,0]
	v_pk_mul_f32 v[34:35], v[34:35], s[86:87] op_sel_hi:[1,0]
	v_pk_fma_f32 v[46:47], v[62:63], v[46:47], s[4:5] op_sel_hi:[1,1,0]
	v_pk_fma_f32 v[32:33], v[72:73], v[32:33], s[2:3] op_sel_hi:[1,1,0]
	v_exp_f32_e32 v34, v34
	v_exp_f32_e32 v35, v35
	v_pk_fma_f32 v[46:47], v[62:63], v[46:47], s[88:89] op_sel_hi:[1,1,0]
	v_pk_fma_f32 v[32:33], v[72:73], v[32:33], s[4:5] op_sel_hi:[1,1,0]
	v_pk_mul_f32 v[46:47], v[62:63], v[46:47]
	v_pk_fma_f32 v[32:33], v[72:73], v[32:33], s[88:89] op_sel_hi:[1,1,0]
	v_and_b32_e32 v77, 0x7fffffff, v53
	v_and_b32_e32 v76, 0x7fffffff, v52
	v_pk_mul_f32 v[46:47], v[54:55], v[46:47]
	v_pk_mul_f32 v[32:33], v[72:73], v[32:33]
	v_pk_fma_f32 v[76:77], v[76:77], s[56:57], 1.0 op_sel_hi:[1,0,0]
	v_pk_mul_f32 v[54:55], v[60:61], v[46:47]
	v_pk_fma_f32 v[62:63], v[60:61], v[46:47], v[60:61] neg_lo:[1,0,0] neg_hi:[1,0,0]
	v_cmp_gt_f32_e32 vcc, 0, v61
	v_pk_mul_f32 v[32:33], v[34:35], v[32:33]
	v_rcp_f32_e32 v76, v76
	v_rcp_f32_e32 v77, v77
	v_cndmask_b32_e32 v46, v63, v55, vcc
	v_pk_mul_f32 v[34:35], v[38:39], v[32:33]
	v_pk_fma_f32 v[72:73], v[38:39], v[32:33], v[38:39] neg_lo:[1,0,0] neg_hi:[1,0,0]
	v_cmp_gt_f32_e32 vcc, 0, v38
	v_and_b32_e32 v55, 0x7fffffff, v71
	v_add_u32_e32 v48, 0x90, v140
	v_cndmask_b32_e32 v33, v72, v34, vcc
	v_cmp_gt_f32_e32 vcc, 0, v36
	v_ashrrev_i32_e32 v49, 31, v48
	s_waitcnt lgkmcnt(0)
; __device__ __forceinline__ u32x4 pack8(const f32x4& a, const f32x4& b) { u32x4 w; w.x = cvt_pk_bf16(a[0], a[1]); w.y = cvt_pk_bf16(a[2], a[3]); w.z = cvt_pk_bf16(b[0], b[1]); w.w = cvt_pk_bf16(b[2], b[3]); return w; }
; __device__ __forceinline__ f32x2 gelu_pk(f32x2 v) {
;     const f32x2 av = __builtin_elementwise_abs(v), d = av * 0.2316418882f + 1.0f;
;     f32x2 t; t.x = __builtin_amdgcn_rcpf(d.x); t.y = __builtin_amdgcn_rcpf(d.y);
;     f32x2 q = t * 0.5307027145f + (-0.7265760135f); q = q * t + 0.7107068705f; q = q * t + (-0.142248368f); q = q * t + 0.127414796f; q = q * t;
;     const f32x2 s = (v * v) * (-0.72134752044f);
;     f32x2 e; e.x = __builtin_amdgcn_exp2f(s.x); e.y = __builtin_amdgcn_exp2f(s.y);
;     const f32x2 m = v * (q * e), r = v - m;
;     f32x2 o; o.x = v.x < 0.f ? m.x : r.x; o.y = v.y < 0.f ? m.y : r.y; return o;
;     __device__ __forceinline__ void operator()(const f32x4 (&acc)[2][2][4][2], const Unit& u, int ui, int wr, int wc, int fr, int fq) const {
;     ...
;             for (int m = 0; m < 4; ++m) { const float r = rs[ai][m]; const int row = row0 + ai * HALF + m * 16; bf16_t* rowp = Z + (size_t)row * 2048 + col0; float s1 = 0.f, s2 = 0.f;
; #pragma unroll
;                 for (int bj = 0; bj < 2; ++bj) { const f32x4 v0 = acc[ai][bj][m][0] * r, v1 = acc[ai][bj][m][1] * r;
;                     const f32x2 a = gelu_pk((f32x2){v0[0], v0[1]}), b = gelu_pk((f32x2){v0[2], v0[3]}), c = gelu_pk((f32x2){v1[0], v1[1]}), d = gelu_pk((f32x2){v1[2], v1[3]});
;                     const f32x4 z0 = (f32x4){a.x, a.y, b.x, b.y}, z1 = (f32x4){c.x, c.y, d.x, d.y};
;                     *(u32x4*)(rowp + bj * HALF) = pack8(z0, z1);
;                     s1 += (z0[0] + z0[1]) + (z0[2] + z0[3]) + (z1[0] + z1[1]) + (z1[2] + z1[3]);
;                     s2 += (z0[0] * z0[0] + z0[1] * z0[1]) + (z0[2] * z0[2] + z0[3] * z0[3]) + (z1[0] * z1[0] + z1[1] * z1[1]) + (z1[2] * z1[2] + z1[3] * z1[3]); }
;                 if (u.pn >= 4) { s1 += __shfl_xor(s1, 16); s1 += __shfl_xor(s1, 32); s2 += __shfl_xor(s2, 16); s2 += __shfl_xor(s2, 32);
;                     if (fq == 0) vst[(size_t)row * 16 + (u.pn - 4) * 4 + wc] = (f32x2){s1, s2}; } }
	v_lshlrev_b64 v[50:51], 12, v[48:49]
	v_cndmask_b32_e32 v32, v74, v68, vcc
	v_cmp_gt_f32_e32 vcc, 0, v39
	v_pk_mul_f32 v[38:39], v[52:53], v[52:53]
	v_lshl_add_u64 v[50:51], s[20:21], 0, v[50:51]
	v_cndmask_b32_e32 v35, v73, v35, vcc
	v_cmp_gt_f32_e32 vcc, 0, v37
	v_pk_fma_f32 v[36:37], v[76:77], s[0:1], v[44:45] op_sel_hi:[1,0,0]
	v_pk_mul_f32 v[38:39], v[38:39], s[86:87] op_sel_hi:[1,0]
	v_pk_fma_f32 v[36:37], v[76:77], v[36:37], s[2:3] op_sel_hi:[1,1,0]
	v_exp_f32_e32 v38, v38
	v_exp_f32_e32 v39, v39
	v_pk_fma_f32 v[36:37], v[76:77], v[36:37], s[4:5] op_sel_hi:[1,1,0]
	v_cndmask_b32_e32 v34, v75, v69, vcc
	v_pk_fma_f32 v[36:37], v[76:77], v[36:37], s[88:89] op_sel_hi:[1,1,0]
	v_cmp_gt_f32_e32 vcc, 0, v58
	v_pk_mul_f32 v[36:37], v[76:77], v[36:37]
	v_lshl_add_u64 v[50:51], v[162:163], 1, v[50:51]
	v_pk_mul_f32 v[36:37], v[38:39], v[36:37]
	v_cndmask_b32_e32 v38, v66, v64, vcc
	v_pk_mul_f32 v[72:73], v[52:53], v[36:37]
	v_pk_fma_f32 v[74:75], v[52:53], v[36:37], v[52:53] neg_lo:[1,0,0] neg_hi:[1,0,0]
	v_cmp_gt_f32_e32 vcc, 0, v52
	v_cvt_pk_bf16_f32 v56, v40, v42
	v_cvt_pk_bf16_f32 v57, v41, v43
	v_pk_mul_f32 v[68:69], v[70:71], v[70:71]
	s_nop 0
	v_cndmask_b32_e32 v39, v74, v72, vcc
	v_cmp_gt_f32_e32 vcc, 0, v59
	s_nop 1
	v_cndmask_b32_e32 v52, v67, v65, vcc
	v_cmp_gt_f32_e32 vcc, 0, v60
	v_cvt_pk_bf16_f32 v58, v38, v52
	s_nop 1
	v_cndmask_b32_e32 v37, v62, v54, vcc
	v_and_b32_e32 v54, 0x7fffffff, v70
	v_pk_fma_f32 v[54:55], v[54:55], s[56:57], 1.0 op_sel_hi:[1,0,0]
	v_cvt_pk_bf16_f32 v59, v37, v46
	global_store_dwordx4 v[50:51], v[56:59], off nt
	v_rcp_f32_e32 v60, v54
	v_rcp_f32_e32 v61, v55
	v_pk_mul_f32 v[56:57], v[68:69], s[86:87] op_sel_hi:[1,0]
	v_cmp_gt_f32_e32 vcc, 0, v53
	v_exp_f32_e32 v56, v56
	v_pk_fma_f32 v[44:45], v[60:61], s[0:1], v[44:45] op_sel_hi:[1,0,0]
	v_exp_f32_e32 v57, v57
	v_pk_fma_f32 v[44:45], v[60:61], v[44:45], s[2:3] op_sel_hi:[1,1,0]
	v_cndmask_b32_e32 v54, v75, v73, vcc
	v_pk_fma_f32 v[44:45], v[60:61], v[44:45], s[4:5] op_sel_hi:[1,1,0]
	v_cmp_gt_f32_e32 vcc, 0, v71
	v_pk_fma_f32 v[44:45], v[60:61], v[44:45], s[88:89] op_sel_hi:[1,1,0]
	s_nop 0
	v_pk_mul_f32 v[44:45], v[60:61], v[44:45]
	s_nop 0
	v_pk_mul_f32 v[44:45], v[56:57], v[44:45]
	s_nop 0
	v_pk_mul_f32 v[56:57], v[70:71], v[44:45]
	v_pk_fma_f32 v[44:45], v[70:71], v[44:45], v[70:71] neg_lo:[1,0,0] neg_hi:[1,0,0]
	s_nop 0
	v_cndmask_b32_e32 v45, v45, v57, vcc
	v_cmp_gt_f32_e32 vcc, 0, v70
	s_nop 1
	v_cndmask_b32_e32 v44, v44, v56, vcc
	s_and_b64 vcc, exec, s[12:13]
	v_cvt_pk_bf16_f32 v56, v32, v34
	v_cvt_pk_bf16_f32 v57, v33, v35
	v_cvt_pk_bf16_f32 v58, v39, v54
	v_cvt_pk_bf16_f32 v59, v44, v45
	global_store_dwordx4 v[50:51], v[56:59], off offset:256 nt
	s_cbranch_vccnz .LBB0_776
	v_mov_b32_e32 v36, v39
	v_mov_b32_e32 v55, v37
	v_pk_add_f32 v[50:51], v[36:37], v[54:55]
	v_pk_mul_f32 v[56:57], v[36:37], v[54:55]
	v_mov_b32_e32 v58, v38
	v_mov_b32_e32 v59, v52
	v_mul_f32_e32 v36, v38, v38
	v_mov_b32_e32 v53, v39
	v_pk_fma_f32 v[58:59], v[58:59], v[58:59], v[36:37] op_sel_hi:[1,1,0]
	v_mul_f32_e32 v36, v44, v44
	v_pk_fma_f32 v[60:61], v[44:45], v[44:45], v[36:37] op_sel_hi:[1,1,0]
	v_mov_b32_e32 v62, v32
	v_mov_b32_e32 v63, v34
	v_mul_f32_e32 v36, v32, v32
	v_pk_add_f32 v[66:67], v[38:39], v[52:53]
	v_pk_mul_f32 v[38:39], v[38:39], v[52:53]
	v_mov_b32_e32 v51, v57
	v_pk_mul_f32 v[56:57], v[42:43], v[42:43]
	v_pk_fma_f32 v[62:63], v[62:63], v[62:63], v[36:37] op_sel_hi:[1,1,0]
	v_mov_b32_e32 v64, v33
	v_mov_b32_e32 v65, v35
	v_mul_f32_e32 v36, v33, v33
	v_mov_b32_e32 v67, v39
	v_pk_mul_f32 v[38:39], v[54:55], v[54:55]
	v_pk_add_f32 v[32:33], v[32:33], v[34:35]
	v_and_b32_e32 v35, 64, v192
	v_pk_fma_f32 v[56:57], v[40:41], v[40:41], v[56:57]
	v_pk_add_f32 v[40:41], v[40:41], v[42:43]
	v_xor_b32_e32 v34, 16, v192
	v_add_u32_e32 v39, 64, v35
	v_pk_fma_f32 v[64:65], v[64:65], v[64:65], v[36:37] op_sel_hi:[1,1,0]
	v_pk_add_f32 v[40:41], v[40:41], v[40:41] op_sel:[0,1] op_sel_hi:[1,0]
	v_cmp_lt_i32_e32 vcc, v34, v39
	v_mul_f32_e32 v68, v46, v46
	v_pk_add_f32 v[56:57], v[56:57], v[56:57] op_sel_hi:[0,1]
	v_cndmask_b32_e32 v34, v192, v34, vcc
	v_mov_b32_e32 v62, v37
	v_mov_b32_e32 v47, v65
	v_mov_b32_e32 v41, v38
	v_pk_add_f32 v[32:33], v[32:33], v[32:33] op_sel:[0,1] op_sel_hi:[1,0]
	v_lshlrev_b32_e32 v42, 2, v34
	v_pk_add_f32 v[34:35], v[62:63], v[46:47]
	v_pk_add_f32 v[36:37], v[66:67], v[40:41]
	v_mov_b32_e32 v58, v44
	v_mov_b32_e32 v56, v45
	v_mov_b32_e32 v33, v68
	v_pk_add_f32 v[34:35], v[36:37], v[34:35]
	v_mov_b32_e32 v147, v61
	v_pk_add_f32 v[36:37], v[58:59], v[56:57]
	v_pk_add_f32 v[32:33], v[50:51], v[32:33]
	v_pk_add_f32 v[34:35], v[34:35], v[146:147]
	v_pk_add_f32 v[32:33], v[32:33], v[36:37]
	v_xor_b32_e32 v36, 32, v192
	v_pk_add_f32 v[32:33], v[32:33], v[34:35]
	ds_bpermute_b32 v34, v42, v32
	ds_bpermute_b32 v35, v42, v33
	v_cmp_lt_i32_e32 vcc, v36, v39
	s_waitcnt lgkmcnt(0)
	v_pk_add_f32 v[32:33], v[32:33], v[34:35]
	v_cndmask_b32_e32 v36, v192, v36, vcc
	v_lshlrev_b32_e32 v36, 2, v36
	ds_bpermute_b32 v34, v36, v32
	ds_bpermute_b32 v35, v36, v33
	s_and_saveexec_b64 s[0:1], s[10:11]
	s_cbranch_execz .LBB0_775
	s_waitcnt lgkmcnt(0)
	v_pk_add_f32 v[32:33], v[32:33], v[34:35]
	v_lshlrev_b64 v[34:35], 7, v[48:49]
	v_lshl_add_u64 v[34:35], s[16:17], 0, v[34:35]
	v_lshl_add_u64 v[34:35], s[38:39], 3, v[34:35]
	s_lshl_b32 s88, s44, 3
	v_lshl_add_u64 v[34:35], v[34:35], 0, s[88:89]
	global_store_dwordx2 v[34:35], v[32:33], off

; __device__ __forceinline__ f32x2 gelu_pk(f32x2 v) {
;     const f32x2 av = __builtin_elementwise_abs(v), d = av * 0.2316418882f + 1.0f;
;     f32x2 t; t.x = __builtin_amdgcn_rcpf(d.x); t.y = __builtin_amdgcn_rcpf(d.y);
;     f32x2 q = t * 0.5307027145f + (-0.7265760135f); q = q * t + 0.7107068705f; q = q * t + (-0.142248368f); q = q * t + 0.127414796f; q = q * t;
;     const f32x2 s = (v * v) * (-0.72134752044f);
;     f32x2 e; e.x = __builtin_amdgcn_exp2f(s.x); e.y = __builtin_amdgcn_exp2f(s.y);
;     const f32x2 m = v * (q * e), r = v - m;
;     f32x2 o; o.x = v.x < 0.f ? m.x : r.x; o.y = v.y < 0.f ? m.y : r.y; return o;
;     __device__ __forceinline__ void operator()(const f32x4 (&acc)[2][2][4][2], const Unit& u, int ui, int wr, int wc, int fr, int fq) const {
;     ...
;             for (int m = 0; m < 4; ++m) { const float r = rs[ai][m]; const int row = row0 + ai * HALF + m * 16; bf16_t* rowp = Z + (size_t)row * 2048 + col0; float s1 = 0.f, s2 = 0.f;
; #pragma unroll
;                 for (int bj = 0; bj < 2; ++bj) { const f32x4 v0 = acc[ai][bj][m][0] * r, v1 = acc[ai][bj][m][1] * r;
;                     const f32x2 a = gelu_pk((f32x2){v0[0], v0[1]}), b = gelu_pk((f32x2){v0[2], v0[3]}), c = gelu_pk((f32x2){v1[0], v1[1]}), d = gelu_pk((f32x2){v1[2], v1[3]});
.LBB0_776:
	v_pk_mul_f32 v[36:37], v[28:29], v[142:143] op_sel_hi:[1,0]
	s_mov_b32 s0, 0xbf3a00e3
	v_and_b32_e32 v29, 0x7fffffff, v37
	v_and_b32_e32 v28, 0x7fffffff, v36
	v_pk_fma_f32 v[28:29], v[28:29], s[56:57], 1.0 op_sel_hi:[1,0,0]
	v_pk_mul_f32 v[42:43], v[24:25], v[142:143] op_sel_hi:[1,0]
	v_rcp_f32_e32 v38, v28
	v_rcp_f32_e32 v39, v29
	v_mov_b64_e32 v[28:29], s[0:1]
	s_mov_b32 s0, 0x3f07dc22
	s_mov_b32 s88, 0x3e027906
	v_pk_fma_f32 v[24:25], v[38:39], s[0:1], v[28:29] op_sel_hi:[1,0,0]
	v_pk_mul_f32 v[30:31], v[30:31], v[142:143] op_sel_hi:[1,0]
	v_pk_fma_f32 v[24:25], v[38:39], v[24:25], s[2:3] op_sel_hi:[1,1,0]
	v_and_b32_e32 v41, 0x7fffffff, v31
	v_pk_fma_f32 v[24:25], v[38:39], v[24:25], s[4:5] op_sel_hi:[1,1,0]
	v_and_b32_e32 v40, 0x7fffffff, v30
	v_pk_fma_f32 v[24:25], v[38:39], v[24:25], s[88:89] op_sel_hi:[1,1,0]
	v_pk_fma_f32 v[40:41], v[40:41], s[56:57], 1.0 op_sel_hi:[1,0,0]
	v_pk_mul_f32 v[24:25], v[38:39], v[24:25]
	v_pk_mul_f32 v[38:39], v[36:37], v[36:37]
	v_rcp_f32_e32 v40, v40
	v_pk_mul_f32 v[38:39], v[38:39], s[86:87] op_sel_hi:[1,0]
	v_rcp_f32_e32 v41, v41
	v_exp_f32_e32 v38, v38
	v_exp_f32_e32 v39, v39
	v_pk_mul_f32 v[44:45], v[26:27], v[142:143] op_sel_hi:[1,0]
	v_pk_mul_f32 v[26:27], v[30:31], v[30:31]
	v_and_b32_e32 v49, 0x7fffffff, v43
	v_pk_mul_f32 v[24:25], v[38:39], v[24:25]
	v_pk_mul_f32 v[26:27], v[26:27], s[86:87] op_sel_hi:[1,0]
	v_pk_mul_f32 v[38:39], v[36:37], v[24:25]
	v_pk_fma_f32 v[46:47], v[36:37], v[24:25], v[36:37] neg_lo:[1,0,0] neg_hi:[1,0,0]
	v_pk_fma_f32 v[24:25], v[40:41], s[0:1], v[28:29] op_sel_hi:[1,0,0]
	v_exp_f32_e32 v26, v26
	v_pk_fma_f32 v[24:25], v[40:41], v[24:25], s[2:3] op_sel_hi:[1,1,0]
	v_exp_f32_e32 v27, v27
	v_pk_fma_f32 v[24:25], v[40:41], v[24:25], s[4:5] op_sel_hi:[1,1,0]
	v_and_b32_e32 v48, 0x7fffffff, v42
	v_pk_fma_f32 v[24:25], v[40:41], v[24:25], s[88:89] op_sel_hi:[1,1,0]
	v_cmp_gt_f32_e32 vcc, 0, v30
	v_pk_mul_f32 v[24:25], v[40:41], v[24:25]
	v_pk_fma_f32 v[48:49], v[48:49], s[56:57], 1.0 op_sel_hi:[1,0,0]
	v_pk_mul_f32 v[24:25], v[26:27], v[24:25]
	v_rcp_f32_e32 v48, v48
	v_pk_mul_f32 v[26:27], v[30:31], v[24:25]
	v_pk_fma_f32 v[40:41], v[30:31], v[24:25], v[30:31] neg_lo:[1,0,0] neg_hi:[1,0,0]
	v_rcp_f32_e32 v49, v49
	v_cndmask_b32_e32 v25, v40, v26, vcc
	v_cmp_gt_f32_e32 vcc, 0, v36
	v_and_b32_e32 v40, 0x7fffffff, v44
	v_pk_mul_f32 v[20:21], v[20:21], v[142:143] op_sel_hi:[1,0]
	v_cndmask_b32_e32 v24, v46, v38, vcc
	v_cmp_gt_f32_e32 vcc, 0, v31
	v_pk_fma_f32 v[30:31], v[48:49], s[0:1], v[28:29] op_sel_hi:[1,0,0]
	v_pk_mul_f32 v[54:55], v[16:17], v[142:143] op_sel_hi:[1,0]
	v_cndmask_b32_e32 v27, v41, v27, vcc
	v_cmp_gt_f32_e32 vcc, 0, v37
	v_and_b32_e32 v41, 0x7fffffff, v45
	v_pk_fma_f32 v[30:31], v[48:49], v[30:31], s[2:3] op_sel_hi:[1,1,0]
	v_cndmask_b32_e32 v26, v47, v39, vcc
	v_pk_mul_f32 v[38:39], v[42:43], v[42:43]
	v_pk_fma_f32 v[40:41], v[40:41], s[56:57], 1.0 op_sel_hi:[1,0,0]
	v_pk_mul_f32 v[38:39], v[38:39], s[86:87] op_sel_hi:[1,0]
	v_pk_fma_f32 v[30:31], v[48:49], v[30:31], s[4:5] op_sel_hi:[1,1,0]
	v_exp_f32_e32 v38, v38
	v_exp_f32_e32 v39, v39
	v_rcp_f32_e32 v40, v40
	v_rcp_f32_e32 v41, v41
	v_pk_fma_f32 v[30:31], v[48:49], v[30:31], s[88:89] op_sel_hi:[1,1,0]
	v_pk_mul_f32 v[36:37], v[44:45], v[44:45]
	v_pk_mul_f32 v[30:31], v[48:49], v[30:31]
	v_pk_mul_f32 v[36:37], v[36:37], s[86:87] op_sel_hi:[1,0]
	v_pk_mul_f32 v[30:31], v[38:39], v[30:31]
	v_exp_f32_e32 v36, v36
	v_pk_mul_f32 v[38:39], v[42:43], v[30:31]
	v_pk_fma_f32 v[46:47], v[42:43], v[30:31], v[42:43] neg_lo:[1,0,0] neg_hi:[1,0,0]
	v_pk_fma_f32 v[30:31], v[40:41], s[0:1], v[28:29] op_sel_hi:[1,0,0]
	v_exp_f32_e32 v37, v37
	v_pk_fma_f32 v[30:31], v[40:41], v[30:31], s[2:3] op_sel_hi:[1,1,0]
	v_pk_mul_f32 v[22:23], v[22:23], v[142:143] op_sel_hi:[1,0]
	v_pk_fma_f32 v[30:31], v[40:41], v[30:31], s[4:5] op_sel_hi:[1,1,0]
	v_and_b32_e32 v57, 0x7fffffff, v23
	v_pk_fma_f32 v[30:31], v[40:41], v[30:31], s[88:89] op_sel_hi:[1,1,0]
	v_and_b32_e32 v56, 0x7fffffff, v22
	v_pk_mul_f32 v[30:31], v[40:41], v[30:31]
	v_pk_fma_f32 v[56:57], v[56:57], s[56:57], 1.0 op_sel_hi:[1,0,0]
	v_pk_mul_f32 v[30:31], v[36:37], v[30:31]
	v_and_b32_e32 v37, 0x7fffffff, v21
	v_and_b32_e32 v36, 0x7fffffff, v20
	v_pk_fma_f32 v[36:37], v[36:37], s[56:57], 1.0 op_sel_hi:[1,0,0]
	v_rcp_f32_e32 v56, v56
	v_rcp_f32_e32 v36, v36
	v_rcp_f32_e32 v37, v37
	v_rcp_f32_e32 v57, v57
	v_pk_mul_f32 v[52:53], v[18:19], v[142:143] op_sel_hi:[1,0]
	v_pk_mul_f32 v[18:19], v[22:23], v[22:23]
	v_pk_fma_f32 v[16:17], v[36:37], s[0:1], v[28:29] op_sel_hi:[1,0,0]
	v_pk_mul_f32 v[18:19], v[18:19], s[86:87] op_sel_hi:[1,0]
	v_pk_fma_f32 v[16:17], v[36:37], v[16:17], s[2:3] op_sel_hi:[1,1,0]
	v_exp_f32_e32 v18, v18
	v_pk_fma_f32 v[16:17], v[36:37], v[16:17], s[4:5] op_sel_hi:[1,1,0]
	v_exp_f32_e32 v19, v19
	v_pk_fma_f32 v[16:17], v[36:37], v[16:17], s[88:89] op_sel_hi:[1,1,0]
	v_and_b32_e32 v61, 0x7fffffff, v55
	v_pk_mul_f32 v[16:17], v[36:37], v[16:17]
	v_pk_mul_f32 v[36:37], v[20:21], v[20:21]
	v_and_b32_e32 v60, 0x7fffffff, v54
	v_pk_mul_f32 v[36:37], v[36:37], s[86:87] op_sel_hi:[1,0]
	v_pk_fma_f32 v[60:61], v[60:61], s[56:57], 1.0 op_sel_hi:[1,0,0]
	v_exp_f32_e32 v36, v36
	v_exp_f32_e32 v37, v37
	v_pk_mul_f32 v[48:49], v[44:45], v[30:31]
	v_pk_fma_f32 v[50:51], v[44:45], v[30:31], v[44:45] neg_lo:[1,0,0] neg_hi:[1,0,0]
	v_cmp_gt_f32_e32 vcc, 0, v45
	v_pk_mul_f32 v[16:17], v[36:37], v[16:17]
	v_rcp_f32_e32 v60, v60
	v_pk_mul_f32 v[36:37], v[20:21], v[16:17]
	v_pk_fma_f32 v[58:59], v[20:21], v[16:17], v[20:21] neg_lo:[1,0,0] neg_hi:[1,0,0]
	v_pk_fma_f32 v[16:17], v[56:57], s[0:1], v[28:29] op_sel_hi:[1,0,0]
	v_rcp_f32_e32 v61, v61
	v_pk_fma_f32 v[16:17], v[56:57], v[16:17], s[2:3] op_sel_hi:[1,1,0]
	v_cndmask_b32_e32 v30, v51, v49, vcc
	v_pk_fma_f32 v[16:17], v[56:57], v[16:17], s[4:5] op_sel_hi:[1,1,0]
	v_cmp_gt_f32_e32 vcc, 0, v22
	v_pk_fma_f32 v[16:17], v[56:57], v[16:17], s[88:89] op_sel_hi:[1,1,0]
	v_add_u32_e32 v32, 0xa0, v140
	v_pk_mul_f32 v[16:17], v[56:57], v[16:17]
	v_ashrrev_i32_e32 v33, 31, v32
	v_pk_mul_f32 v[16:17], v[18:19], v[16:17]
	s_waitcnt lgkmcnt(0)
; __device__ __forceinline__ u32x4 pack8(const f32x4& a, const f32x4& b) { u32x4 w; w.x = cvt_pk_bf16(a[0], a[1]); w.y = cvt_pk_bf16(a[2], a[3]); w.z = cvt_pk_bf16(b[0], b[1]); w.w = cvt_pk_bf16(b[2], b[3]); return w; }
; __device__ __forceinline__ f32x2 gelu_pk(f32x2 v) {
;     const f32x2 av = __builtin_elementwise_abs(v), d = av * 0.2316418882f + 1.0f;
;     f32x2 t; t.x = __builtin_amdgcn_rcpf(d.x); t.y = __builtin_amdgcn_rcpf(d.y);
;     f32x2 q = t * 0.5307027145f + (-0.7265760135f); q = q * t + 0.7107068705f; q = q * t + (-0.142248368f); q = q * t + 0.127414796f; q = q * t;
;     const f32x2 s = (v * v) * (-0.72134752044f);
;     f32x2 e; e.x = __builtin_amdgcn_exp2f(s.x); e.y = __builtin_amdgcn_exp2f(s.y);
;     const f32x2 m = v * (q * e), r = v - m;
;     f32x2 o; o.x = v.x < 0.f ? m.x : r.x; o.y = v.y < 0.f ? m.y : r.y; return o;
; }
;     __device__ __forceinline__ void operator()(const f32x4 (&acc)[2][2][4][2], const Unit& u, int ui, int wr, int wc, int fr, int fq) const {
;     ...
;             for (int m = 0; m < 4; ++m) { const float r = rs[ai][m]; const int row = row0 + ai * HALF + m * 16; bf16_t* rowp = Z + (size_t)row * 2048 + col0; float s1 = 0.f, s2 = 0.f;
; #pragma unroll
;                 for (int bj = 0; bj < 2; ++bj) { const f32x4 v0 = acc[ai][bj][m][0] * r, v1 = acc[ai][bj][m][1] * r;
;                     const f32x2 a = gelu_pk((f32x2){v0[0], v0[1]}), b = gelu_pk((f32x2){v0[2], v0[3]}), c = gelu_pk((f32x2){v1[0], v1[1]}), d = gelu_pk((f32x2){v1[2], v1[3]});
;                     const f32x4 z0 = (f32x4){a.x, a.y, b.x, b.y}, z1 = (f32x4){c.x, c.y, d.x, d.y};
;                     *(u32x4*)(rowp + bj * HALF) = pack8(z0, z1);
;                     s1 += (z0[0] + z0[1]) + (z0[2] + z0[3]) + (z1[0] + z1[1]) + (z1[2] + z1[3]);
;                     s2 += (z0[0] * z0[0] + z0[1] * z0[1]) + (z0[2] * z0[2] + z0[3] * z0[3]) + (z1[0] * z1[0] + z1[1] * z1[1]) + (z1[2] * z1[2] + z1[3] * z1[3]); }
;                 if (u.pn >= 4) { s1 += __shfl_xor(s1, 16); s1 += __shfl_xor(s1, 32); s2 += __shfl_xor(s2, 16); s2 += __shfl_xor(s2, 32);
;                     if (fq == 0) vst[(size_t)row * 16 + (u.pn - 4) * 4 + wc] = (f32x2){s1, s2}; } }
	v_lshlrev_b64 v[34:35], 12, v[32:33]
	v_pk_mul_f32 v[18:19], v[22:23], v[16:17]
	v_pk_fma_f32 v[56:57], v[22:23], v[16:17], v[22:23] neg_lo:[1,0,0] neg_hi:[1,0,0]
	v_lshl_add_u64 v[34:35], s[20:21], 0, v[34:35]
	v_cndmask_b32_e32 v17, v56, v18, vcc
	v_cmp_gt_f32_e32 vcc, 0, v20
	v_lshl_add_u64 v[34:35], v[162:163], 1, v[34:35]
	v_cvt_pk_bf16_f32 v40, v24, v26
	v_cvt_pk_bf16_f32 v41, v25, v27
	s_nop 0
	v_cndmask_b32_e32 v16, v58, v36, vcc
	v_cmp_gt_f32_e32 vcc, 0, v23
	v_pk_mul_f32 v[22:23], v[54:55], v[54:55]
	s_nop 0
	v_cndmask_b32_e32 v19, v57, v19, vcc
	v_cmp_gt_f32_e32 vcc, 0, v21
	v_pk_fma_f32 v[20:21], v[60:61], s[0:1], v[28:29] op_sel_hi:[1,0,0]
	v_pk_mul_f32 v[22:23], v[22:23], s[86:87] op_sel_hi:[1,0]
	v_pk_fma_f32 v[20:21], v[60:61], v[20:21], s[2:3] op_sel_hi:[1,1,0]
	v_exp_f32_e32 v22, v22
	v_exp_f32_e32 v23, v23
	v_pk_fma_f32 v[20:21], v[60:61], v[20:21], s[4:5] op_sel_hi:[1,1,0]
	v_cndmask_b32_e32 v18, v59, v37, vcc
	v_pk_fma_f32 v[20:21], v[60:61], v[20:21], s[88:89] op_sel_hi:[1,1,0]
	v_cmp_gt_f32_e32 vcc, 0, v42
	v_pk_mul_f32 v[20:21], v[60:61], v[20:21]
	v_pk_mul_f32 v[56:57], v[52:53], v[52:53]
	v_pk_mul_f32 v[20:21], v[22:23], v[20:21]
	v_cndmask_b32_e32 v22, v46, v38, vcc
	v_pk_mul_f32 v[36:37], v[54:55], v[20:21]
	v_pk_fma_f32 v[58:59], v[54:55], v[20:21], v[54:55] neg_lo:[1,0,0] neg_hi:[1,0,0]
	v_cmp_gt_f32_e32 vcc, 0, v54
	v_and_b32_e32 v38, 0x7fffffff, v52
	s_nop 0
	v_cndmask_b32_e32 v23, v58, v36, vcc
	v_cmp_gt_f32_e32 vcc, 0, v43
	s_nop 1
	v_cndmask_b32_e32 v36, v47, v39, vcc
	v_and_b32_e32 v39, 0x7fffffff, v53
	v_pk_fma_f32 v[38:39], v[38:39], s[56:57], 1.0 op_sel_hi:[1,0,0]
	v_cmp_gt_f32_e32 vcc, 0, v44
	v_rcp_f32_e32 v44, v38
	v_rcp_f32_e32 v45, v39
	v_cvt_pk_bf16_f32 v42, v22, v36
	v_cndmask_b32_e32 v21, v50, v48, vcc
	v_cvt_pk_bf16_f32 v43, v21, v30
	global_store_dwordx4 v[34:35], v[40:43], off nt
	v_pk_fma_f32 v[28:29], v[44:45], s[0:1], v[28:29] op_sel_hi:[1,0,0]
	v_cmp_gt_f32_e32 vcc, 0, v55
	v_pk_mul_f32 v[40:41], v[56:57], s[86:87] op_sel_hi:[1,0]
	v_pk_fma_f32 v[28:29], v[44:45], v[28:29], s[2:3] op_sel_hi:[1,1,0]
	v_exp_f32_e32 v40, v40
	v_exp_f32_e32 v41, v41
	v_pk_fma_f32 v[28:29], v[44:45], v[28:29], s[4:5] op_sel_hi:[1,1,0]
	v_cndmask_b32_e32 v38, v59, v37, vcc
	v_pk_fma_f32 v[28:29], v[44:45], v[28:29], s[88:89] op_sel_hi:[1,1,0]
	v_cmp_gt_f32_e32 vcc, 0, v53
	v_pk_mul_f32 v[28:29], v[44:45], v[28:29]
	s_nop 0
	v_pk_mul_f32 v[28:29], v[40:41], v[28:29]
	s_nop 0
	v_pk_mul_f32 v[40:41], v[52:53], v[28:29]
	v_pk_fma_f32 v[28:29], v[52:53], v[28:29], v[52:53] neg_lo:[1,0,0] neg_hi:[1,0,0]
	s_nop 0
	v_cndmask_b32_e32 v29, v29, v41, vcc
	v_cmp_gt_f32_e32 vcc, 0, v52
	s_nop 1
	v_cndmask_b32_e32 v28, v28, v40, vcc
	s_and_b64 vcc, exec, s[12:13]
	v_cvt_pk_bf16_f32 v40, v16, v18
	v_cvt_pk_bf16_f32 v41, v17, v19
	v_cvt_pk_bf16_f32 v42, v23, v38
	v_cvt_pk_bf16_f32 v43, v28, v29
	global_store_dwordx4 v[34:35], v[40:43], off offset:256 nt
	s_cbranch_vccnz .LBB0_780
	v_mov_b32_e32 v20, v23
	v_mov_b32_e32 v39, v21
	v_pk_add_f32 v[34:35], v[20:21], v[38:39]
	v_pk_mul_f32 v[40:41], v[20:21], v[38:39]
	v_mov_b32_e32 v42, v22
	v_mov_b32_e32 v43, v36
	v_mul_f32_e32 v20, v22, v22
	v_mov_b32_e32 v37, v23
	v_pk_fma_f32 v[42:43], v[42:43], v[42:43], v[20:21] op_sel_hi:[1,1,0]
	v_mul_f32_e32 v20, v28, v28
	v_pk_fma_f32 v[44:45], v[28:29], v[28:29], v[20:21] op_sel_hi:[1,1,0]
	v_mov_b32_e32 v46, v16
	v_mov_b32_e32 v47, v18
	v_mul_f32_e32 v20, v16, v16
	v_pk_add_f32 v[50:51], v[22:23], v[36:37]
	v_pk_mul_f32 v[22:23], v[22:23], v[36:37]
	v_mov_b32_e32 v35, v41
	v_pk_mul_f32 v[40:41], v[26:27], v[26:27]
	v_pk_fma_f32 v[46:47], v[46:47], v[46:47], v[20:21] op_sel_hi:[1,1,0]
	v_mov_b32_e32 v48, v17
	v_mov_b32_e32 v49, v19
	v_mul_f32_e32 v20, v17, v17
	v_mov_b32_e32 v51, v23
	v_pk_mul_f32 v[22:23], v[38:39], v[38:39]
	v_pk_add_f32 v[16:17], v[16:17], v[18:19]
	v_and_b32_e32 v19, 64, v192
	v_pk_fma_f32 v[40:41], v[24:25], v[24:25], v[40:41]
	v_pk_add_f32 v[24:25], v[24:25], v[26:27]
	v_xor_b32_e32 v18, 16, v192
	v_add_u32_e32 v23, 64, v19
	v_pk_fma_f32 v[48:49], v[48:49], v[48:49], v[20:21] op_sel_hi:[1,1,0]
	v_pk_add_f32 v[24:25], v[24:25], v[24:25] op_sel:[0,1] op_sel_hi:[1,0]
	v_cmp_lt_i32_e32 vcc, v18, v23
	v_mul_f32_e32 v52, v30, v30
	v_pk_add_f32 v[40:41], v[40:41], v[40:41] op_sel_hi:[0,1]
	v_cndmask_b32_e32 v18, v192, v18, vcc
	v_mov_b32_e32 v46, v21
	v_mov_b32_e32 v31, v49
	v_mov_b32_e32 v25, v22
	v_pk_add_f32 v[16:17], v[16:17], v[16:17] op_sel:[0,1] op_sel_hi:[1,0]
	v_lshlrev_b32_e32 v26, 2, v18
	v_pk_add_f32 v[18:19], v[46:47], v[30:31]
	v_pk_add_f32 v[20:21], v[50:51], v[24:25]
	v_mov_b32_e32 v42, v28
	v_mov_b32_e32 v40, v29
	v_mov_b32_e32 v17, v52
	v_pk_add_f32 v[18:19], v[20:21], v[18:19]
	v_mov_b32_e32 v147, v45
	v_pk_add_f32 v[20:21], v[42:43], v[40:41]
	v_pk_add_f32 v[16:17], v[34:35], v[16:17]
	v_pk_add_f32 v[18:19], v[18:19], v[146:147]
	v_pk_add_f32 v[16:17], v[16:17], v[20:21]
	v_xor_b32_e32 v20, 32, v192
	v_pk_add_f32 v[16:17], v[16:17], v[18:19]
	ds_bpermute_b32 v18, v26, v16
	ds_bpermute_b32 v19, v26, v17
	v_cmp_lt_i32_e32 vcc, v20, v23
	s_waitcnt lgkmcnt(0)
	v_pk_add_f32 v[16:17], v[16:17], v[18:19]
	v_cndmask_b32_e32 v20, v192, v20, vcc
	v_lshlrev_b32_e32 v20, 2, v20
	ds_bpermute_b32 v18, v20, v16
	ds_bpermute_b32 v19, v20, v17
	s_and_saveexec_b64 s[0:1], s[10:11]
	s_cbranch_execz .LBB0_779
	s_waitcnt lgkmcnt(0)
	v_pk_add_f32 v[16:17], v[16:17], v[18:19]
	v_lshlrev_b64 v[18:19], 7, v[32:33]
	v_lshl_add_u64 v[18:19], s[16:17], 0, v[18:19]
	v_lshl_add_u64 v[18:19], s[38:39], 3, v[18:19]
	s_lshl_b32 s88, s44, 3
	v_lshl_add_u64 v[18:19], v[18:19], 0, s[88:89]
	global_store_dwordx2 v[18:19], v[16:17], off

; __device__ __forceinline__ f32x2 gelu_pk(f32x2 v) {
;     const f32x2 av = __builtin_elementwise_abs(v), d = av * 0.2316418882f + 1.0f;
;     f32x2 t; t.x = __builtin_amdgcn_rcpf(d.x); t.y = __builtin_amdgcn_rcpf(d.y);
;     f32x2 q = t * 0.5307027145f + (-0.7265760135f); q = q * t + 0.7107068705f; q = q * t + (-0.142248368f); q = q * t + 0.127414796f; q = q * t;
;     const f32x2 s = (v * v) * (-0.72134752044f);
;     f32x2 e; e.x = __builtin_amdgcn_exp2f(s.x); e.y = __builtin_amdgcn_exp2f(s.y);
;     const f32x2 m = v * (q * e), r = v - m;
;     f32x2 o; o.x = v.x < 0.f ? m.x : r.x; o.y = v.y < 0.f ? m.y : r.y; return o;
; }
;     __device__ __forceinline__ void operator()(const f32x4 (&acc)[2][2][4][2], const Unit& u, int ui, int wr, int wc, int fr, int fq) const {
;     ...
;                 for (int bj = 0; bj < 2; ++bj) { const f32x4 v0 = acc[ai][bj][m][0] * r, v1 = acc[ai][bj][m][1] * r;
;                     const f32x2 a = gelu_pk((f32x2){v0[0], v0[1]}), b = gelu_pk((f32x2){v0[2], v0[3]}), c = gelu_pk((f32x2){v1[0], v1[1]}), d = gelu_pk((f32x2){v1[2], v1[3]});
.LBB0_780:
	v_mov_b32_e32 v20, v143
	v_pk_mul_f32 v[22:23], v[12:13], v[20:21] op_sel_hi:[1,0]
	s_mov_b32 s0, 0xbf3a00e3
	v_and_b32_e32 v13, 0x7fffffff, v23
	v_and_b32_e32 v12, 0x7fffffff, v22
	v_pk_fma_f32 v[12:13], v[12:13], s[56:57], 1.0 op_sel_hi:[1,0,0]
	v_pk_mul_f32 v[26:27], v[8:9], v[20:21] op_sel_hi:[1,0]
	v_rcp_f32_e32 v24, v12
	v_rcp_f32_e32 v25, v13
	v_mov_b64_e32 v[12:13], s[0:1]
	s_mov_b32 s0, 0x3f07dc22
	s_mov_b32 s88, 0x3e027906
	v_pk_fma_f32 v[8:9], v[24:25], s[0:1], v[12:13] op_sel_hi:[1,0,0]
	v_pk_mul_f32 v[14:15], v[14:15], v[20:21] op_sel_hi:[1,0]
	v_pk_fma_f32 v[8:9], v[24:25], v[8:9], s[2:3] op_sel_hi:[1,1,0]
	v_and_b32_e32 v31, 0x7fffffff, v15
	v_pk_fma_f32 v[8:9], v[24:25], v[8:9], s[4:5] op_sel_hi:[1,1,0]
	v_and_b32_e32 v30, 0x7fffffff, v14
	v_pk_fma_f32 v[8:9], v[24:25], v[8:9], s[88:89] op_sel_hi:[1,1,0]
	v_pk_fma_f32 v[30:31], v[30:31], s[56:57], 1.0 op_sel_hi:[1,0,0]
	v_pk_mul_f32 v[8:9], v[24:25], v[8:9]
	v_pk_mul_f32 v[24:25], v[22:23], v[22:23]
	v_rcp_f32_e32 v30, v30
	v_pk_mul_f32 v[24:25], v[24:25], s[86:87] op_sel_hi:[1,0]
	v_rcp_f32_e32 v31, v31
	v_exp_f32_e32 v24, v24
	v_exp_f32_e32 v25, v25
	v_pk_mul_f32 v[28:29], v[10:11], v[20:21] op_sel_hi:[1,0]
	v_pk_mul_f32 v[10:11], v[14:15], v[14:15]
	v_pk_mul_f32 v[4:5], v[4:5], v[20:21] op_sel_hi:[1,0]
	v_pk_mul_f32 v[8:9], v[24:25], v[8:9]
	v_pk_mul_f32 v[10:11], v[10:11], s[86:87] op_sel_hi:[1,0]
	v_pk_mul_f32 v[24:25], v[22:23], v[8:9]
	v_pk_fma_f32 v[32:33], v[22:23], v[8:9], v[22:23] neg_lo:[1,0,0] neg_hi:[1,0,0]
	v_pk_fma_f32 v[8:9], v[30:31], s[0:1], v[12:13] op_sel_hi:[1,0,0]
	v_exp_f32_e32 v10, v10
	v_pk_fma_f32 v[8:9], v[30:31], v[8:9], s[2:3] op_sel_hi:[1,1,0]
	v_exp_f32_e32 v11, v11
	v_and_b32_e32 v37, 0x7fffffff, v5
	v_and_b32_e32 v36, 0x7fffffff, v4
	v_pk_fma_f32 v[8:9], v[30:31], v[8:9], s[4:5] op_sel_hi:[1,1,0]
	v_pk_fma_f32 v[36:37], v[36:37], s[56:57], 1.0 op_sel_hi:[1,0,0]
	v_pk_fma_f32 v[8:9], v[30:31], v[8:9], s[88:89] op_sel_hi:[1,1,0]
	v_rcp_f32_e32 v36, v36
	v_rcp_f32_e32 v37, v37
	v_pk_mul_f32 v[8:9], v[30:31], v[8:9]
	v_and_b32_e32 v35, 0x7fffffff, v27
	v_pk_mul_f32 v[8:9], v[10:11], v[8:9]
	v_and_b32_e32 v34, 0x7fffffff, v26
	v_pk_mul_f32 v[10:11], v[14:15], v[8:9]
	v_pk_fma_f32 v[30:31], v[14:15], v[8:9], v[14:15] neg_lo:[1,0,0] neg_hi:[1,0,0]
	v_cmp_gt_f32_e32 vcc, 0, v14
	v_pk_fma_f32 v[34:35], v[34:35], s[56:57], 1.0 op_sel_hi:[1,0,0]
	v_pk_mul_f32 v[6:7], v[6:7], v[20:21] op_sel_hi:[1,0]
	v_cndmask_b32_e32 v9, v30, v10, vcc
	v_cmp_gt_f32_e32 vcc, 0, v22
	v_rcp_f32_e32 v34, v34
	v_rcp_f32_e32 v35, v35
	v_pk_mul_f32 v[38:39], v[2:3], v[20:21] op_sel_hi:[1,0]
	v_pk_mul_f32 v[20:21], v[0:1], v[20:21] op_sel_hi:[1,0]
	v_pk_fma_f32 v[0:1], v[36:37], s[0:1], v[12:13] op_sel_hi:[1,0,0]
	v_cndmask_b32_e32 v8, v32, v24, vcc
	v_cmp_gt_f32_e32 vcc, 0, v15
	v_pk_fma_f32 v[0:1], v[36:37], v[0:1], s[2:3] op_sel_hi:[1,1,0]
	v_pk_fma_f32 v[14:15], v[34:35], s[0:1], v[12:13] op_sel_hi:[1,0,0]
	v_cndmask_b32_e32 v11, v31, v11, vcc
	v_cmp_gt_f32_e32 vcc, 0, v23
	v_pk_fma_f32 v[0:1], v[36:37], v[0:1], s[4:5] op_sel_hi:[1,1,0]
	v_and_b32_e32 v31, 0x7fffffff, v29
	v_cndmask_b32_e32 v10, v33, v25, vcc
	v_pk_mul_f32 v[24:25], v[26:27], v[26:27]
	v_pk_fma_f32 v[0:1], v[36:37], v[0:1], s[88:89] op_sel_hi:[1,1,0]
	v_pk_mul_f32 v[24:25], v[24:25], s[86:87] op_sel_hi:[1,0]
	v_and_b32_e32 v30, 0x7fffffff, v28
	v_pk_mul_f32 v[0:1], v[36:37], v[0:1]
	v_pk_mul_f32 v[36:37], v[4:5], v[4:5]
	v_pk_fma_f32 v[14:15], v[34:35], v[14:15], s[2:3] op_sel_hi:[1,1,0]
	v_exp_f32_e32 v24, v24
	v_exp_f32_e32 v25, v25
	v_pk_fma_f32 v[30:31], v[30:31], s[56:57], 1.0 op_sel_hi:[1,0,0]
	v_pk_mul_f32 v[36:37], v[36:37], s[86:87] op_sel_hi:[1,0]
	v_and_b32_e32 v41, 0x7fffffff, v7
	v_and_b32_e32 v40, 0x7fffffff, v6
	v_pk_fma_f32 v[14:15], v[34:35], v[14:15], s[4:5] op_sel_hi:[1,1,0]
	v_rcp_f32_e32 v30, v30
	v_rcp_f32_e32 v31, v31
	v_exp_f32_e32 v36, v36
	v_exp_f32_e32 v37, v37
	v_pk_fma_f32 v[40:41], v[40:41], s[56:57], 1.0 op_sel_hi:[1,0,0]
	v_pk_fma_f32 v[14:15], v[34:35], v[14:15], s[88:89] op_sel_hi:[1,1,0]
	v_rcp_f32_e32 v40, v40
	v_rcp_f32_e32 v41, v41
	v_pk_mul_f32 v[14:15], v[34:35], v[14:15]
	v_pk_mul_f32 v[22:23], v[28:29], v[28:29]
	v_pk_mul_f32 v[14:15], v[24:25], v[14:15]
	v_pk_mul_f32 v[22:23], v[22:23], s[86:87] op_sel_hi:[1,0]
	v_pk_mul_f32 v[32:33], v[26:27], v[14:15]
	v_pk_fma_f32 v[34:35], v[26:27], v[14:15], v[26:27] neg_lo:[1,0,0] neg_hi:[1,0,0]
	v_pk_fma_f32 v[14:15], v[30:31], s[0:1], v[12:13] op_sel_hi:[1,0,0]
	v_pk_mul_f32 v[2:3], v[6:7], v[6:7]
	v_pk_mul_f32 v[0:1], v[36:37], v[0:1]
	v_pk_fma_f32 v[14:15], v[30:31], v[14:15], s[2:3] op_sel_hi:[1,1,0]
	v_exp_f32_e32 v22, v22
	v_exp_f32_e32 v23, v23
	v_pk_mul_f32 v[36:37], v[4:5], v[0:1]
	v_pk_fma_f32 v[42:43], v[4:5], v[0:1], v[4:5] neg_lo:[1,0,0] neg_hi:[1,0,0]
	v_pk_fma_f32 v[0:1], v[40:41], s[0:1], v[12:13] op_sel_hi:[1,0,0]
	v_pk_mul_f32 v[2:3], v[2:3], s[86:87] op_sel_hi:[1,0]
	v_pk_fma_f32 v[14:15], v[30:31], v[14:15], s[4:5] op_sel_hi:[1,1,0]
	v_pk_fma_f32 v[0:1], v[40:41], v[0:1], s[2:3] op_sel_hi:[1,1,0]
	v_exp_f32_e32 v2, v2
	v_exp_f32_e32 v3, v3
	v_pk_fma_f32 v[14:15], v[30:31], v[14:15], s[88:89] op_sel_hi:[1,1,0]
	v_pk_fma_f32 v[0:1], v[40:41], v[0:1], s[4:5] op_sel_hi:[1,1,0]
	v_pk_mul_f32 v[14:15], v[30:31], v[14:15]
	v_pk_fma_f32 v[0:1], v[40:41], v[0:1], s[88:89] op_sel_hi:[1,1,0]
	v_and_b32_e32 v45, 0x7fffffff, v21
	v_and_b32_e32 v44, 0x7fffffff, v20
	v_pk_mul_f32 v[14:15], v[22:23], v[14:15]
	v_pk_mul_f32 v[0:1], v[40:41], v[0:1]
	v_pk_fma_f32 v[44:45], v[44:45], s[56:57], 1.0 op_sel_hi:[1,0,0]
	v_pk_mul_f32 v[22:23], v[28:29], v[14:15]
	v_pk_fma_f32 v[30:31], v[28:29], v[14:15], v[28:29] neg_lo:[1,0,0] neg_hi:[1,0,0]
	v_cmp_gt_f32_e32 vcc, 0, v29
	v_pk_mul_f32 v[0:1], v[2:3], v[0:1]
	v_rcp_f32_e32 v44, v44
	v_rcp_f32_e32 v45, v45
	v_cndmask_b32_e32 v14, v31, v23, vcc
	v_pk_mul_f32 v[2:3], v[6:7], v[0:1]
	v_pk_fma_f32 v[40:41], v[6:7], v[0:1], v[6:7] neg_lo:[1,0,0] neg_hi:[1,0,0]
	v_cmp_gt_f32_e32 vcc, 0, v6
	v_and_b32_e32 v23, 0x7fffffff, v39
	v_add_u32_e32 v16, 0xb0, v140
	v_cndmask_b32_e32 v1, v40, v2, vcc
	v_cmp_gt_f32_e32 vcc, 0, v4
	v_ashrrev_i32_e32 v17, 31, v16
	s_waitcnt lgkmcnt(0)
; __device__ __forceinline__ u32x4 pack8(const f32x4& a, const f32x4& b) { u32x4 w; w.x = cvt_pk_bf16(a[0], a[1]); w.y = cvt_pk_bf16(a[2], a[3]); w.z = cvt_pk_bf16(b[0], b[1]); w.w = cvt_pk_bf16(b[2], b[3]); return w; }
;     __device__ __forceinline__ void operator()(const f32x4 (&acc)[2][2][4][2], const Unit& u, int ui, int wr, int wc, int fr, int fq) const {
;     ...
;             for (int m = 0; m < 4; ++m) { const float r = rs[ai][m]; const int row = row0 + ai * HALF + m * 16; bf16_t* rowp = Z + (size_t)row * 2048 + col0; float s1 = 0.f, s2 = 0.f;
; #pragma unroll
;                 for (int bj = 0; bj < 2; ++bj) { const f32x4 v0 = acc[ai][bj][m][0] * r, v1 = acc[ai][bj][m][1] * r;
;                     const f32x2 a = gelu_pk((f32x2){v0[0], v0[1]}), b = gelu_pk((f32x2){v0[2], v0[3]}), c = gelu_pk((f32x2){v1[0], v1[1]}), d = gelu_pk((f32x2){v1[2], v1[3]});
;                     const f32x4 z0 = (f32x4){a.x, a.y, b.x, b.y}, z1 = (f32x4){c.x, c.y, d.x, d.y};
;                     *(u32x4*)(rowp + bj * HALF) = pack8(z0, z1);
;                     s1 += (z0[0] + z0[1]) + (z0[2] + z0[3]) + (z1[0] + z1[1]) + (z1[2] + z1[3]);
;                     s2 += (z0[0] * z0[0] + z0[1] * z0[1]) + (z0[2] * z0[2] + z0[3] * z0[3]) + (z1[0] * z1[0] + z1[1] * z1[1]) + (z1[2] * z1[2] + z1[3] * z1[3]); }
;                 if (u.pn >= 4) { s1 += __shfl_xor(s1, 16); s1 += __shfl_xor(s1, 32); s2 += __shfl_xor(s2, 16); s2 += __shfl_xor(s2, 32);
;                     if (fq == 0) vst[(size_t)row * 16 + (u.pn - 4) * 4 + wc] = (f32x2){s1, s2}; } }
	v_lshlrev_b64 v[18:19], 12, v[16:17]
	v_cndmask_b32_e32 v0, v42, v36, vcc
	v_cmp_gt_f32_e32 vcc, 0, v7
	v_pk_mul_f32 v[6:7], v[20:21], v[20:21]
	v_lshl_add_u64 v[18:19], s[20:21], 0, v[18:19]
	v_cndmask_b32_e32 v3, v41, v3, vcc
	v_cmp_gt_f32_e32 vcc, 0, v5
	v_pk_fma_f32 v[4:5], v[44:45], s[0:1], v[12:13] op_sel_hi:[1,0,0]
	v_pk_mul_f32 v[6:7], v[6:7], s[86:87] op_sel_hi:[1,0]
	v_pk_fma_f32 v[4:5], v[44:45], v[4:5], s[2:3] op_sel_hi:[1,1,0]
	v_exp_f32_e32 v6, v6
	v_exp_f32_e32 v7, v7
	v_pk_fma_f32 v[4:5], v[44:45], v[4:5], s[4:5] op_sel_hi:[1,1,0]
	v_cndmask_b32_e32 v2, v43, v37, vcc
	v_pk_fma_f32 v[4:5], v[44:45], v[4:5], s[88:89] op_sel_hi:[1,1,0]
	v_cmp_gt_f32_e32 vcc, 0, v26
	v_pk_mul_f32 v[4:5], v[44:45], v[4:5]
	v_lshl_add_u64 v[18:19], v[162:163], 1, v[18:19]
	v_pk_mul_f32 v[4:5], v[6:7], v[4:5]
	v_cndmask_b32_e32 v6, v34, v32, vcc
	v_pk_mul_f32 v[40:41], v[20:21], v[4:5]
	v_pk_fma_f32 v[42:43], v[20:21], v[4:5], v[20:21] neg_lo:[1,0,0] neg_hi:[1,0,0]
	v_cmp_gt_f32_e32 vcc, 0, v20
	v_cvt_pk_bf16_f32 v24, v8, v10
	v_cvt_pk_bf16_f32 v25, v9, v11
	v_pk_mul_f32 v[36:37], v[38:39], v[38:39]
	s_nop 0
	v_cndmask_b32_e32 v7, v42, v40, vcc
	v_cmp_gt_f32_e32 vcc, 0, v27
	s_nop 1
	v_cndmask_b32_e32 v20, v35, v33, vcc
	v_cmp_gt_f32_e32 vcc, 0, v28
	v_cvt_pk_bf16_f32 v26, v6, v20
	s_nop 1
	v_cndmask_b32_e32 v5, v30, v22, vcc
	v_and_b32_e32 v22, 0x7fffffff, v38
	v_pk_fma_f32 v[22:23], v[22:23], s[56:57], 1.0 op_sel_hi:[1,0,0]
	v_cvt_pk_bf16_f32 v27, v5, v14
	global_store_dwordx4 v[18:19], v[24:27], off nt
	v_rcp_f32_e32 v28, v22
	v_rcp_f32_e32 v29, v23
	v_pk_mul_f32 v[24:25], v[36:37], s[86:87] op_sel_hi:[1,0]
	v_cmp_gt_f32_e32 vcc, 0, v21
	v_exp_f32_e32 v24, v24
	v_pk_fma_f32 v[12:13], v[28:29], s[0:1], v[12:13] op_sel_hi:[1,0,0]
	v_exp_f32_e32 v25, v25
	v_pk_fma_f32 v[12:13], v[28:29], v[12:13], s[2:3] op_sel_hi:[1,1,0]
	v_cndmask_b32_e32 v22, v43, v41, vcc
	v_pk_fma_f32 v[12:13], v[28:29], v[12:13], s[4:5] op_sel_hi:[1,1,0]
	v_cmp_gt_f32_e32 vcc, 0, v39
	v_pk_fma_f32 v[12:13], v[28:29], v[12:13], s[88:89] op_sel_hi:[1,1,0]
	s_nop 0
	v_pk_mul_f32 v[12:13], v[28:29], v[12:13]
	s_nop 0
	v_pk_mul_f32 v[12:13], v[24:25], v[12:13]
	s_nop 0
	v_pk_mul_f32 v[24:25], v[38:39], v[12:13]
	v_pk_fma_f32 v[12:13], v[38:39], v[12:13], v[38:39] neg_lo:[1,0,0] neg_hi:[1,0,0]
	s_nop 0
	v_cndmask_b32_e32 v13, v13, v25, vcc
	v_cmp_gt_f32_e32 vcc, 0, v38
	s_nop 1
	v_cndmask_b32_e32 v12, v12, v24, vcc
	s_and_b64 vcc, exec, s[12:13]
	v_cvt_pk_bf16_f32 v24, v0, v2
	v_cvt_pk_bf16_f32 v25, v1, v3
	v_cvt_pk_bf16_f32 v26, v7, v22
	v_cvt_pk_bf16_f32 v27, v12, v13
	global_store_dwordx4 v[18:19], v[24:27], off offset:256 nt
	s_cbranch_vccnz .LBB0_784
	v_mov_b32_e32 v4, v7
	v_mov_b32_e32 v23, v5
	v_pk_add_f32 v[18:19], v[4:5], v[22:23]
	v_pk_mul_f32 v[24:25], v[4:5], v[22:23]
	v_mov_b32_e32 v26, v6
	v_mov_b32_e32 v27, v20
	v_mul_f32_e32 v4, v6, v6
	v_mov_b32_e32 v21, v7
	v_pk_fma_f32 v[26:27], v[26:27], v[26:27], v[4:5] op_sel_hi:[1,1,0]
	v_mul_f32_e32 v4, v12, v12
	v_pk_fma_f32 v[28:29], v[12:13], v[12:13], v[4:5] op_sel_hi:[1,1,0]
	v_mov_b32_e32 v30, v0
	v_mov_b32_e32 v31, v2
	v_mul_f32_e32 v4, v0, v0
	v_pk_add_f32 v[34:35], v[6:7], v[20:21]
	v_pk_mul_f32 v[6:7], v[6:7], v[20:21]
	v_mov_b32_e32 v19, v25
	v_pk_mul_f32 v[24:25], v[10:11], v[10:11]
	v_pk_fma_f32 v[30:31], v[30:31], v[30:31], v[4:5] op_sel_hi:[1,1,0]
	v_mov_b32_e32 v32, v1
	v_mov_b32_e32 v33, v3
	v_mul_f32_e32 v4, v1, v1
	v_mov_b32_e32 v35, v7
	v_pk_mul_f32 v[6:7], v[22:23], v[22:23]
	v_pk_add_f32 v[0:1], v[0:1], v[2:3]
	v_and_b32_e32 v3, 64, v192
	v_pk_fma_f32 v[24:25], v[8:9], v[8:9], v[24:25]
	v_pk_add_f32 v[8:9], v[8:9], v[10:11]
	v_xor_b32_e32 v2, 16, v192
	v_add_u32_e32 v7, 64, v3
	v_pk_fma_f32 v[32:33], v[32:33], v[32:33], v[4:5] op_sel_hi:[1,1,0]
	v_pk_add_f32 v[8:9], v[8:9], v[8:9] op_sel:[0,1] op_sel_hi:[1,0]
	v_cmp_lt_i32_e32 vcc, v2, v7
	v_mul_f32_e32 v36, v14, v14
	v_pk_add_f32 v[24:25], v[24:25], v[24:25] op_sel_hi:[0,1]
	v_cndmask_b32_e32 v2, v192, v2, vcc
	v_mov_b32_e32 v30, v5
	v_mov_b32_e32 v15, v33
	v_mov_b32_e32 v9, v6
	v_pk_add_f32 v[0:1], v[0:1], v[0:1] op_sel:[0,1] op_sel_hi:[1,0]
	v_lshlrev_b32_e32 v10, 2, v2
	v_pk_add_f32 v[2:3], v[30:31], v[14:15]
	v_pk_add_f32 v[4:5], v[34:35], v[8:9]
	v_mov_b32_e32 v26, v12
	v_mov_b32_e32 v24, v13
	v_mov_b32_e32 v1, v36
	v_pk_add_f32 v[2:3], v[4:5], v[2:3]
	v_mov_b32_e32 v147, v29
	v_pk_add_f32 v[4:5], v[26:27], v[24:25]
	v_pk_add_f32 v[0:1], v[18:19], v[0:1]
	v_pk_add_f32 v[2:3], v[2:3], v[146:147]
	v_pk_add_f32 v[0:1], v[0:1], v[4:5]
	v_xor_b32_e32 v4, 32, v192
	v_pk_add_f32 v[0:1], v[0:1], v[2:3]
	ds_bpermute_b32 v2, v10, v0
	ds_bpermute_b32 v3, v10, v1
	v_cmp_lt_i32_e32 vcc, v4, v7
	s_waitcnt lgkmcnt(0)
	v_pk_add_f32 v[0:1], v[0:1], v[2:3]
	v_cndmask_b32_e32 v4, v192, v4, vcc
	v_lshlrev_b32_e32 v4, 2, v4
	ds_bpermute_b32 v2, v4, v0
	ds_bpermute_b32 v3, v4, v1
	s_and_saveexec_b64 s[0:1], s[10:11]
	s_cbranch_execz .LBB0_783
	s_waitcnt lgkmcnt(0)
	v_pk_add_f32 v[0:1], v[0:1], v[2:3]
	v_lshlrev_b64 v[2:3], 7, v[16:17]
	v_lshl_add_u64 v[2:3], s[16:17], 0, v[2:3]
	v_lshl_add_u64 v[2:3], s[38:39], 3, v[2:3]
	s_lshl_b32 s88, s44, 3
	v_lshl_add_u64 v[2:3], v[2:3], 0, s[88:89]
	global_store_dwordx2 v[2:3], v[0:1], off

; __device__ __forceinline__ unsigned cvt_pk_bf16(float lo, float hi) { unsigned r; asm volatile("v_cvt_pk_bf16_f32 %0, %1, %2" : "=v"(r) : "v"(lo), "v"(hi)); return r; }
;     __device__ __forceinline__ void operator()(const f32x4 (&acc)[2][2][4][2], const Unit& u, int ui, int wr, int wc, int fr, int fq) const {
;     ...
;         for (int ai = 0; ai < 2; ++ai)
; #pragma unroll
;             for (int m = 0; m < 4; ++m) rs[ai][m] = row_rstd(lds, ui, ai * HALF + wr * 64 + m * 16 + fr);
;         if (u.pn < 2) {
;     ...
;                 for (int m = 0; m < 4; ++m) { const float r = rs[ai][m]; bf16_t* rowp = UG + (size_t)(row0 + ai * HALF + m * 16) * 1024 + 512 + (u.pn - 2) * HALF + cw;
;                     const float c1 = r * -1.44269504089f; u32x4 w;
; #pragma unroll
;                     for (int n = 0; n < 2; ++n)
; #pragma unroll
;                         for (int p = 0; p < 2; ++p) { const f32x2 av = (f32x2){acc[ai][0][m][n][2 * p], acc[ai][0][m][n][2 * p + 1]}, gt = (f32x2){acc[ai][1][m][n][2 * p], acc[ai][1][m][n][2 * p + 1]};
;                             const f32x2 t = gt * c1; f32x2 d; d.x = __builtin_amdgcn_exp2f(t.x); d.y = __builtin_amdgcn_exp2f(t.y); d = d + 1.0f;
;                             f32x2 q; q.x = __builtin_amdgcn_rcpf(d.x); q.y = __builtin_amdgcn_rcpf(d.y);
;                             const f32x2 hh = av * (q * r); w[2 * n + p] = cvt_pk_bf16(hh.x, hh.y); }
;                     *(u32x4*)rowp = w; }
.LBB0_795:
	v_mov_b32_e32 v140, v147
	v_mov_b32_e32 v167, v172
	s_mov_b64 s[0:1], -1
	v_add_u32_e32 v140, s35, v140
	v_lshl_add_u32 v166, s45, 8, v140
	v_lshlrev_b32_e32 v140, 2, v140
	v_lshl_add_u32 v140, s47, 10, v140
	v_add_u32_e32 v140, 0x20400, v140
	ds_read2_b32 v[164:165], v140 offset1:16
	ds_read2_b32 v[162:163], v140 offset0:32 offset1:48
	ds_read2_b32 v[142:143], v140 offset0:128 offset1:144
	ds_read2_b32 v[140:141], v140 offset0:160 offset1:176
	v_lshl_add_u32 v168, v167, 3, s36
	s_cmp_lt_i32 s44, 2
	v_ashrrev_i32_e32 v169, 31, v168
	v_ashrrev_i32_e32 v167, 31, v166
	s_cbranch_scc1 .LBB0_798
	s_waitcnt lgkmcnt(0)
	v_mul_f32_e32 v180, 0xbfb8aa3b, v164
	v_pk_mul_f32 v[176:177], v[116:117], v[180:181] op_sel_hi:[1,0]
	v_pk_mul_f32 v[178:179], v[118:119], v[180:181] op_sel_hi:[1,0]
	v_exp_f32_e32 v176, v176
	v_exp_f32_e32 v177, v177
	v_exp_f32_e32 v178, v178
	v_exp_f32_e32 v179, v179
	s_lshl_b32 s0, s44, 7
	v_pk_add_f32 v[176:177], v[176:177], 1.0 op_sel_hi:[1,0]
	v_lshlrev_b64 v[170:171], 11, v[166:167]
	v_pk_add_f32 v[178:179], v[178:179], 1.0 op_sel_hi:[1,0]
	v_rcp_f32_e32 v176, v176
	v_rcp_f32_e32 v177, v177
	v_rcp_f32_e32 v178, v178
	v_rcp_f32_e32 v179, v179
	s_add_i32 s88, s0, 0xffffff00
	v_pk_mul_f32 v[176:177], v[164:165], v[176:177] op_sel_hi:[0,1]
	v_pk_mul_f32 v[176:177], v[124:125], v[176:177]
	v_pk_mul_f32 v[178:179], v[164:165], v[178:179] op_sel_hi:[0,1]
	v_pk_mul_f32 v[178:179], v[126:127], v[178:179]
	v_cvt_pk_bf16_f32 v176, v176, v177
	v_lshl_add_u64 v[170:171], s[20:21], 0, v[170:171]
	v_cvt_pk_bf16_f32 v177, v178, v179
	v_pk_mul_f32 v[178:179], v[108:109], v[180:181] op_sel_hi:[1,0]
	v_pk_mul_f32 v[180:181], v[110:111], v[180:181] op_sel_hi:[1,0]
	v_exp_f32_e32 v178, v178
	v_exp_f32_e32 v179, v179
	v_exp_f32_e32 v180, v180
	v_exp_f32_e32 v181, v181
	v_lshl_add_u64 v[170:171], s[88:89], 1, v[170:171]
	v_pk_add_f32 v[178:179], v[178:179], 1.0 op_sel_hi:[1,0]
	v_lshl_add_u64 v[170:171], v[168:169], 1, v[170:171]
	v_pk_add_f32 v[180:181], v[180:181], 1.0 op_sel_hi:[1,0]
	v_rcp_f32_e32 v178, v178
	v_rcp_f32_e32 v179, v179
	v_rcp_f32_e32 v180, v180
	v_rcp_f32_e32 v181, v181
	v_mov_b32_e32 v182, v165
	v_pk_mul_f32 v[178:179], v[164:165], v[178:179] op_sel_hi:[0,1]
	v_pk_mul_f32 v[178:179], v[120:121], v[178:179]
	v_pk_mul_f32 v[180:181], v[164:165], v[180:181] op_sel_hi:[0,1]
	v_pk_mul_f32 v[180:181], v[122:123], v[180:181]
	v_cvt_pk_bf16_f32 v178, v178, v179
	s_mov_b32 s0, 0x8000
	v_cvt_pk_bf16_f32 v179, v180, v181
	v_mul_f32_e32 v180, 0xbfb8aa3b, v165
	global_store_dwordx4 v[170:171], v[176:179], off offset:1024 nt
	s_nop 1
	v_pk_mul_f32 v[176:177], v[100:101], v[180:181] op_sel_hi:[1,0]
	v_pk_mul_f32 v[178:179], v[102:103], v[180:181] op_sel_hi:[1,0]
	v_exp_f32_e32 v176, v176
	v_exp_f32_e32 v177, v177
	v_exp_f32_e32 v178, v178
	v_exp_f32_e32 v179, v179
	v_pk_add_f32 v[176:177], v[176:177], 1.0 op_sel_hi:[1,0]
	s_nop 0
	v_rcp_f32_e32 v176, v176
	v_pk_add_f32 v[178:179], v[178:179], 1.0 op_sel_hi:[1,0]
	v_rcp_f32_e32 v177, v177
	v_rcp_f32_e32 v178, v178
	v_rcp_f32_e32 v179, v179
	v_pk_mul_f32 v[176:177], v[182:183], v[176:177] op_sel_hi:[0,1]
	v_pk_mul_f32 v[176:177], v[112:113], v[176:177]
	v_pk_mul_f32 v[178:179], v[182:183], v[178:179] op_sel_hi:[0,1]
	v_pk_mul_f32 v[178:179], v[114:115], v[178:179]
	v_cvt_pk_bf16_f32 v176, v176, v177
	s_nop 0
	v_cvt_pk_bf16_f32 v177, v178, v179
	v_pk_mul_f32 v[178:179], v[92:93], v[180:181] op_sel_hi:[1,0]
	v_pk_mul_f32 v[180:181], v[94:95], v[180:181] op_sel_hi:[1,0]
	v_exp_f32_e32 v178, v178
	v_exp_f32_e32 v179, v179
	v_exp_f32_e32 v180, v180
	v_exp_f32_e32 v181, v181
	v_pk_add_f32 v[178:179], v[178:179], 1.0 op_sel_hi:[1,0]
	s_nop 0
	v_rcp_f32_e32 v178, v178
	v_pk_add_f32 v[180:181], v[180:181], 1.0 op_sel_hi:[1,0]
	v_rcp_f32_e32 v179, v179
	v_rcp_f32_e32 v180, v180
	v_rcp_f32_e32 v181, v181
	v_pk_mul_f32 v[178:179], v[182:183], v[178:179] op_sel_hi:[0,1]
	v_pk_mul_f32 v[178:179], v[104:105], v[178:179]
	v_pk_mul_f32 v[180:181], v[182:183], v[180:181] op_sel_hi:[0,1]
	v_pk_mul_f32 v[180:181], v[106:107], v[180:181]
	v_cvt_pk_bf16_f32 v178, v178, v179
	v_mov_b32_e32 v182, v163
	v_cvt_pk_bf16_f32 v179, v180, v181
	v_add_co_u32_e32 v180, vcc, s0, v170
	s_mov_b32 s0, 0x10000
	s_nop 0
	v_addc_co_u32_e32 v181, vcc, 0, v171, vcc
	global_store_dwordx4 v[180:181], v[176:179], off offset:1024 nt
	v_mul_f32_e32 v180, 0xbfb8aa3b, v162
	s_nop 0
	v_pk_mul_f32 v[176:177], v[84:85], v[180:181] op_sel_hi:[1,0]
	v_pk_mul_f32 v[178:179], v[86:87], v[180:181] op_sel_hi:[1,0]
	v_exp_f32_e32 v176, v176
	v_exp_f32_e32 v177, v177
	v_exp_f32_e32 v178, v178
	v_exp_f32_e32 v179, v179
	v_pk_add_f32 v[176:177], v[176:177], 1.0 op_sel_hi:[1,0]
	s_nop 0
	v_rcp_f32_e32 v176, v176
	v_pk_add_f32 v[178:179], v[178:179], 1.0 op_sel_hi:[1,0]
	v_rcp_f32_e32 v177, v177
	v_rcp_f32_e32 v178, v178
	v_rcp_f32_e32 v179, v179
	v_pk_mul_f32 v[176:177], v[162:163], v[176:177] op_sel_hi:[0,1]
	v_pk_mul_f32 v[176:177], v[96:97], v[176:177]
	v_pk_mul_f32 v[178:179], v[162:163], v[178:179] op_sel_hi:[0,1]
	v_pk_mul_f32 v[178:179], v[98:99], v[178:179]
	v_cvt_pk_bf16_f32 v176, v176, v177
	s_nop 0
	v_cvt_pk_bf16_f32 v177, v178, v179
	v_pk_mul_f32 v[178:179], v[76:77], v[180:181] op_sel_hi:[1,0]
	v_pk_mul_f32 v[180:181], v[78:79], v[180:181] op_sel_hi:[1,0]
	v_exp_f32_e32 v178, v178
	v_exp_f32_e32 v179, v179
	v_exp_f32_e32 v180, v180
	v_exp_f32_e32 v181, v181
	v_pk_add_f32 v[178:179], v[178:179], 1.0 op_sel_hi:[1,0]
	s_nop 0
	v_rcp_f32_e32 v178, v178
	v_pk_add_f32 v[180:181], v[180:181], 1.0 op_sel_hi:[1,0]
	v_rcp_f32_e32 v179, v179
	v_rcp_f32_e32 v180, v180
	v_rcp_f32_e32 v181, v181
	v_pk_mul_f32 v[178:179], v[162:163], v[178:179] op_sel_hi:[0,1]
; __device__ __forceinline__ unsigned cvt_pk_bf16(float lo, float hi) { unsigned r; asm volatile("v_cvt_pk_bf16_f32 %0, %1, %2" : "=v"(r) : "v"(lo), "v"(hi)); return r; }
;     __device__ __forceinline__ void operator()(const f32x4 (&acc)[2][2][4][2], const Unit& u, int ui, int wr, int wc, int fr, int fq) const {
;     ...
;                 for (int m = 0; m < 4; ++m) { const float r = rs[ai][m]; bf16_t* rowp = UG + (size_t)(row0 + ai * HALF + m * 16) * 1024 + 512 + (u.pn - 2) * HALF + cw;
;                     const float c1 = r * -1.44269504089f; u32x4 w;
; #pragma unroll
;                     for (int n = 0; n < 2; ++n)
; #pragma unroll
;                         for (int p = 0; p < 2; ++p) { const f32x2 av = (f32x2){acc[ai][0][m][n][2 * p], acc[ai][0][m][n][2 * p + 1]}, gt = (f32x2){acc[ai][1][m][n][2 * p], acc[ai][1][m][n][2 * p + 1]};
;                             const f32x2 t = gt * c1; f32x2 d; d.x = __builtin_amdgcn_exp2f(t.x); d.y = __builtin_amdgcn_exp2f(t.y); d = d + 1.0f;
;                             f32x2 q; q.x = __builtin_amdgcn_rcpf(d.x); q.y = __builtin_amdgcn_rcpf(d.y);
;                             const f32x2 hh = av * (q * r); w[2 * n + p] = cvt_pk_bf16(hh.x, hh.y); }
;                     *(u32x4*)rowp = w; }
	v_pk_mul_f32 v[178:179], v[88:89], v[178:179]
	v_pk_mul_f32 v[180:181], v[162:163], v[180:181] op_sel_hi:[0,1]
	v_pk_mul_f32 v[180:181], v[90:91], v[180:181]
	v_cvt_pk_bf16_f32 v178, v178, v179
	s_nop 0
	v_cvt_pk_bf16_f32 v179, v180, v181
	v_add_co_u32_e32 v180, vcc, s0, v170
	s_mov_b32 s0, 0x18000
	s_nop 0
	v_addc_co_u32_e32 v181, vcc, 0, v171, vcc
	global_store_dwordx4 v[180:181], v[176:179], off offset:1024 nt
	v_mul_f32_e32 v180, 0xbfb8aa3b, v163
	s_nop 0
	v_pk_mul_f32 v[176:177], v[68:69], v[180:181] op_sel_hi:[1,0]
	v_pk_mul_f32 v[178:179], v[70:71], v[180:181] op_sel_hi:[1,0]
	v_exp_f32_e32 v176, v176
	v_exp_f32_e32 v177, v177
	v_exp_f32_e32 v178, v178
	v_exp_f32_e32 v179, v179
	v_pk_add_f32 v[176:177], v[176:177], 1.0 op_sel_hi:[1,0]
	s_nop 0
	v_rcp_f32_e32 v176, v176
	v_pk_add_f32 v[178:179], v[178:179], 1.0 op_sel_hi:[1,0]
	v_rcp_f32_e32 v177, v177
	v_rcp_f32_e32 v178, v178
	v_rcp_f32_e32 v179, v179
	v_pk_mul_f32 v[176:177], v[182:183], v[176:177] op_sel_hi:[0,1]
	v_pk_mul_f32 v[176:177], v[80:81], v[176:177]
	v_pk_mul_f32 v[178:179], v[182:183], v[178:179] op_sel_hi:[0,1]
	v_pk_mul_f32 v[178:179], v[82:83], v[178:179]
	v_cvt_pk_bf16_f32 v176, v176, v177
	s_nop 0
	v_cvt_pk_bf16_f32 v177, v178, v179
	v_pk_mul_f32 v[178:179], v[64:65], v[180:181] op_sel_hi:[1,0]
	v_pk_mul_f32 v[180:181], v[66:67], v[180:181] op_sel_hi:[1,0]
	v_exp_f32_e32 v178, v178
	v_exp_f32_e32 v179, v179
	v_exp_f32_e32 v180, v180
	v_exp_f32_e32 v181, v181
	v_pk_add_f32 v[178:179], v[178:179], 1.0 op_sel_hi:[1,0]
	s_nop 0
	v_rcp_f32_e32 v178, v178
	v_pk_add_f32 v[180:181], v[180:181], 1.0 op_sel_hi:[1,0]
	v_rcp_f32_e32 v179, v179
	v_rcp_f32_e32 v180, v180
	v_rcp_f32_e32 v181, v181
	v_pk_mul_f32 v[178:179], v[182:183], v[178:179] op_sel_hi:[0,1]
	v_pk_mul_f32 v[178:179], v[72:73], v[178:179]
	v_pk_mul_f32 v[180:181], v[182:183], v[180:181] op_sel_hi:[0,1]
	v_pk_mul_f32 v[180:181], v[74:75], v[180:181]
	v_cvt_pk_bf16_f32 v178, v178, v179
	v_mov_b32_e32 v182, v143
	v_cvt_pk_bf16_f32 v179, v180, v181
	v_add_co_u32_e32 v180, vcc, s0, v170
	s_mov_b32 s0, 0x48000
	s_nop 0
	v_addc_co_u32_e32 v181, vcc, 0, v171, vcc
	global_store_dwordx4 v[180:181], v[176:179], off offset:1024 nt
	v_mul_f32_e32 v180, 0xbfb8aa3b, v142
	s_nop 0
	v_pk_mul_f32 v[176:177], v[52:53], v[180:181] op_sel_hi:[1,0]
	v_pk_mul_f32 v[178:179], v[54:55], v[180:181] op_sel_hi:[1,0]
	v_exp_f32_e32 v176, v176
	v_exp_f32_e32 v177, v177
	v_exp_f32_e32 v178, v178
	v_exp_f32_e32 v179, v179
	v_pk_add_f32 v[176:177], v[176:177], 1.0 op_sel_hi:[1,0]
	s_nop 0
	v_rcp_f32_e32 v176, v176
	v_pk_add_f32 v[178:179], v[178:179], 1.0 op_sel_hi:[1,0]
	v_rcp_f32_e32 v177, v177
	v_rcp_f32_e32 v178, v178
	v_rcp_f32_e32 v179, v179
	v_pk_mul_f32 v[176:177], v[142:143], v[176:177] op_sel_hi:[0,1]
	v_pk_mul_f32 v[176:177], v[60:61], v[176:177]
	v_pk_mul_f32 v[178:179], v[142:143], v[178:179] op_sel_hi:[0,1]
	v_pk_mul_f32 v[178:179], v[62:63], v[178:179]
	v_cvt_pk_bf16_f32 v176, v176, v177
	s_nop 0
	v_cvt_pk_bf16_f32 v177, v178, v179
	v_pk_mul_f32 v[178:179], v[44:45], v[180:181] op_sel_hi:[1,0]
	v_pk_mul_f32 v[180:181], v[46:47], v[180:181] op_sel_hi:[1,0]
	v_exp_f32_e32 v178, v178
	v_exp_f32_e32 v179, v179
	v_exp_f32_e32 v180, v180
	v_exp_f32_e32 v181, v181
	v_pk_add_f32 v[178:179], v[178:179], 1.0 op_sel_hi:[1,0]
	s_nop 0
	v_rcp_f32_e32 v178, v178
	v_pk_add_f32 v[180:181], v[180:181], 1.0 op_sel_hi:[1,0]
	v_rcp_f32_e32 v179, v179
	v_rcp_f32_e32 v180, v180
	v_rcp_f32_e32 v181, v181
	v_pk_mul_f32 v[178:179], v[142:143], v[178:179] op_sel_hi:[0,1]
	v_pk_mul_f32 v[178:179], v[56:57], v[178:179]
	v_pk_mul_f32 v[180:181], v[142:143], v[180:181] op_sel_hi:[0,1]
	v_pk_mul_f32 v[180:181], v[58:59], v[180:181]
	v_cvt_pk_bf16_f32 v178, v178, v179
	s_nop 0
	v_cvt_pk_bf16_f32 v179, v180, v181
	v_add_co_u32_e32 v180, vcc, s87, v170
	s_nop 1
	v_addc_co_u32_e32 v181, vcc, 0, v171, vcc
	global_store_dwordx4 v[180:181], v[176:179], off offset:1024 nt
	v_mul_f32_e32 v180, 0xbfb8aa3b, v143
	s_nop 0
	v_pk_mul_f32 v[176:177], v[36:37], v[180:181] op_sel_hi:[1,0]
	v_pk_mul_f32 v[178:179], v[38:39], v[180:181] op_sel_hi:[1,0]
	v_exp_f32_e32 v176, v176
	v_exp_f32_e32 v177, v177
	v_exp_f32_e32 v178, v178
	v_exp_f32_e32 v179, v179
	v_pk_add_f32 v[176:177], v[176:177], 1.0 op_sel_hi:[1,0]
	s_nop 0
	v_rcp_f32_e32 v176, v176
	v_pk_add_f32 v[178:179], v[178:179], 1.0 op_sel_hi:[1,0]
	v_rcp_f32_e32 v177, v177
	v_rcp_f32_e32 v178, v178
	v_rcp_f32_e32 v179, v179
	v_pk_mul_f32 v[176:177], v[182:183], v[176:177] op_sel_hi:[0,1]
	v_pk_mul_f32 v[176:177], v[48:49], v[176:177]
	v_pk_mul_f32 v[178:179], v[182:183], v[178:179] op_sel_hi:[0,1]
; __device__ __forceinline__ unsigned cvt_pk_bf16(float lo, float hi) { unsigned r; asm volatile("v_cvt_pk_bf16_f32 %0, %1, %2" : "=v"(r) : "v"(lo), "v"(hi)); return r; }
;     __device__ __forceinline__ void operator()(const f32x4 (&acc)[2][2][4][2], const Unit& u, int ui, int wr, int wc, int fr, int fq) const {
;     ...
;                 for (int m = 0; m < 4; ++m) { const float r = rs[ai][m]; bf16_t* rowp = UG + (size_t)(row0 + ai * HALF + m * 16) * 1024 + 512 + (u.pn - 2) * HALF + cw;
;                     const float c1 = r * -1.44269504089f; u32x4 w;
; #pragma unroll
;                     for (int n = 0; n < 2; ++n)
; #pragma unroll
;                         for (int p = 0; p < 2; ++p) { const f32x2 av = (f32x2){acc[ai][0][m][n][2 * p], acc[ai][0][m][n][2 * p + 1]}, gt = (f32x2){acc[ai][1][m][n][2 * p], acc[ai][1][m][n][2 * p + 1]};
;                             const f32x2 t = gt * c1; f32x2 d; d.x = __builtin_amdgcn_exp2f(t.x); d.y = __builtin_amdgcn_exp2f(t.y); d = d + 1.0f;
;                             f32x2 q; q.x = __builtin_amdgcn_rcpf(d.x); q.y = __builtin_amdgcn_rcpf(d.y);
;                             const f32x2 hh = av * (q * r); w[2 * n + p] = cvt_pk_bf16(hh.x, hh.y); }
;                     *(u32x4*)rowp = w; }
	v_pk_mul_f32 v[178:179], v[50:51], v[178:179]
	v_cvt_pk_bf16_f32 v176, v176, v177
	s_nop 0
	v_cvt_pk_bf16_f32 v177, v178, v179
	v_pk_mul_f32 v[178:179], v[28:29], v[180:181] op_sel_hi:[1,0]
	v_pk_mul_f32 v[180:181], v[30:31], v[180:181] op_sel_hi:[1,0]
	v_exp_f32_e32 v178, v178
	v_exp_f32_e32 v179, v179
	v_exp_f32_e32 v180, v180
	v_exp_f32_e32 v181, v181
	v_pk_add_f32 v[178:179], v[178:179], 1.0 op_sel_hi:[1,0]
	s_nop 0
	v_rcp_f32_e32 v178, v178
	v_pk_add_f32 v[180:181], v[180:181], 1.0 op_sel_hi:[1,0]
	v_rcp_f32_e32 v179, v179
	v_rcp_f32_e32 v180, v180
	v_rcp_f32_e32 v181, v181
	v_pk_mul_f32 v[178:179], v[182:183], v[178:179] op_sel_hi:[0,1]
	v_pk_mul_f32 v[178:179], v[40:41], v[178:179]
	v_pk_mul_f32 v[180:181], v[182:183], v[180:181] op_sel_hi:[0,1]
	v_pk_mul_f32 v[180:181], v[42:43], v[180:181]
	v_cvt_pk_bf16_f32 v178, v178, v179
	v_mov_b32_e32 v182, v141
	v_cvt_pk_bf16_f32 v179, v180, v181
	v_add_co_u32_e32 v180, vcc, s0, v170
	s_mov_b32 s0, 0x50000
	s_nop 0
	v_addc_co_u32_e32 v181, vcc, 0, v171, vcc
	global_store_dwordx4 v[180:181], v[176:179], off offset:1024 nt
	v_mul_f32_e32 v180, 0xbfb8aa3b, v140
	s_nop 0
	v_pk_mul_f32 v[176:177], v[20:21], v[180:181] op_sel_hi:[1,0]
	v_pk_mul_f32 v[178:179], v[22:23], v[180:181] op_sel_hi:[1,0]
	v_exp_f32_e32 v176, v176
	v_exp_f32_e32 v177, v177
	v_exp_f32_e32 v178, v178
	v_exp_f32_e32 v179, v179
	v_pk_add_f32 v[176:177], v[176:177], 1.0 op_sel_hi:[1,0]
	s_nop 0
	v_rcp_f32_e32 v176, v176
	v_pk_add_f32 v[178:179], v[178:179], 1.0 op_sel_hi:[1,0]
	v_rcp_f32_e32 v177, v177
	v_rcp_f32_e32 v178, v178
	v_rcp_f32_e32 v179, v179
	v_pk_mul_f32 v[176:177], v[140:141], v[176:177] op_sel_hi:[0,1]
	v_pk_mul_f32 v[176:177], v[32:33], v[176:177]
	v_pk_mul_f32 v[178:179], v[140:141], v[178:179] op_sel_hi:[0,1]
	v_pk_mul_f32 v[178:179], v[34:35], v[178:179]
	v_cvt_pk_bf16_f32 v176, v176, v177
	s_nop 0
	v_cvt_pk_bf16_f32 v177, v178, v179
	v_pk_mul_f32 v[178:179], v[12:13], v[180:181] op_sel_hi:[1,0]
	v_pk_mul_f32 v[180:181], v[14:15], v[180:181] op_sel_hi:[1,0]
	v_exp_f32_e32 v178, v178
	v_exp_f32_e32 v179, v179
	v_exp_f32_e32 v180, v180
	v_exp_f32_e32 v181, v181
	v_pk_add_f32 v[178:179], v[178:179], 1.0 op_sel_hi:[1,0]
	s_nop 0
	v_rcp_f32_e32 v178, v178
	v_pk_add_f32 v[180:181], v[180:181], 1.0 op_sel_hi:[1,0]
	v_rcp_f32_e32 v179, v179
	v_rcp_f32_e32 v180, v180
	v_rcp_f32_e32 v181, v181
	v_pk_mul_f32 v[178:179], v[140:141], v[178:179] op_sel_hi:[0,1]
	v_pk_mul_f32 v[178:179], v[24:25], v[178:179]
	v_pk_mul_f32 v[180:181], v[140:141], v[180:181] op_sel_hi:[0,1]
	v_pk_mul_f32 v[180:181], v[26:27], v[180:181]
	v_cvt_pk_bf16_f32 v178, v178, v179
	s_nop 0
	v_cvt_pk_bf16_f32 v179, v180, v181
	v_add_co_u32_e32 v180, vcc, s0, v170
	s_nop 1
	v_addc_co_u32_e32 v181, vcc, 0, v171, vcc
	global_store_dwordx4 v[180:181], v[176:179], off offset:1024 nt
	v_mul_f32_e32 v180, 0xbfb8aa3b, v141
	v_add_co_u32_e32 v170, vcc, 0x58000, v170
	v_pk_mul_f32 v[176:177], v[4:5], v[180:181] op_sel_hi:[1,0]
	v_pk_mul_f32 v[178:179], v[6:7], v[180:181] op_sel_hi:[1,0]
	v_exp_f32_e32 v176, v176
	v_exp_f32_e32 v177, v177
	v_exp_f32_e32 v178, v178
	v_exp_f32_e32 v179, v179
	v_addc_co_u32_e32 v171, vcc, 0, v171, vcc
	v_pk_add_f32 v[176:177], v[176:177], 1.0 op_sel_hi:[1,0]
	v_pk_add_f32 v[178:179], v[178:179], 1.0 op_sel_hi:[1,0]
	v_rcp_f32_e32 v176, v176
	v_rcp_f32_e32 v177, v177
	v_rcp_f32_e32 v178, v178
	v_rcp_f32_e32 v179, v179
	v_pk_mul_f32 v[176:177], v[182:183], v[176:177] op_sel_hi:[0,1]
	v_pk_mul_f32 v[176:177], v[16:17], v[176:177]
	v_pk_mul_f32 v[178:179], v[182:183], v[178:179] op_sel_hi:[0,1]
	v_pk_mul_f32 v[178:179], v[18:19], v[178:179]
	v_cvt_pk_bf16_f32 v176, v176, v177
	s_nop 0
	v_cvt_pk_bf16_f32 v177, v178, v179
	v_pk_mul_f32 v[178:179], v[0:1], v[180:181] op_sel_hi:[1,0]
	v_pk_mul_f32 v[180:181], v[2:3], v[180:181] op_sel_hi:[1,0]
	v_exp_f32_e32 v178, v178
	v_exp_f32_e32 v179, v179
	v_exp_f32_e32 v180, v180
	v_exp_f32_e32 v181, v181
	v_pk_add_f32 v[178:179], v[178:179], 1.0 op_sel_hi:[1,0]
	s_nop 0
	v_rcp_f32_e32 v178, v178
	v_rcp_f32_e32 v179, v179
	v_pk_add_f32 v[180:181], v[180:181], 1.0 op_sel_hi:[1,0]
	v_pk_mul_f32 v[178:179], v[182:183], v[178:179] op_sel_hi:[0,1]
	v_rcp_f32_e32 v180, v180
	v_rcp_f32_e32 v181, v181
	v_pk_mul_f32 v[178:179], v[8:9], v[178:179]
	v_pk_mul_f32 v[180:181], v[182:183], v[180:181] op_sel_hi:[0,1]
	v_cvt_pk_bf16_f32 v178, v178, v179
	v_pk_mul_f32 v[180:181], v[10:11], v[180:181]
	s_nop 0
	v_cvt_pk_bf16_f32 v179, v180, v181
	global_store_dwordx4 v[170:171], v[176:179], off offset:1024 nt
	s_cbranch_execz .LBB0_799

; __device__ __forceinline__ u32x4 pack8(const f32x4& a, const f32x4& b) { u32x4 w; w.x = cvt_pk_bf16(a[0], a[1]); w.y = cvt_pk_bf16(a[2], a[3]); w.z = cvt_pk_bf16(b[0], b[1]); w.w = cvt_pk_bf16(b[2], b[3]); return w; }
;     __device__ __forceinline__ void operator()(const f32x4 (&acc)[2][2][4][2], const Unit& u, int ui, int wr, int wc, int fr, int fq) const {
;     ...
;                 for (int m = 0; m < 4; ++m) { const float r = rs[ai][m]; bf16_t* rowp = UG + (size_t)(row0 + ai * HALF + m * 16) * 1024 + u.pn * BM + cw;
; #pragma unroll
;                     for (int bj = 0; bj < 2; ++bj) *(u32x4*)(rowp + bj * HALF) = pack8(acc[ai][bj][m][0] * r, acc[ai][bj][m][1] * r); }
.LBB0_799:
	s_lshl_b32 s0, s44, 8
	v_lshlrev_b64 v[166:167], 11, v[166:167]
	s_ashr_i32 s1, s0, 31
	v_lshl_add_u64 v[166:167], s[20:21], 0, v[166:167]
	v_lshl_add_u64 v[166:167], s[0:1], 1, v[166:167]
	v_lshl_add_u64 v[166:167], v[168:169], 1, v[166:167]
	s_waitcnt lgkmcnt(0)
	v_pk_mul_f32 v[126:127], v[126:127], v[164:165] op_sel_hi:[1,0]
	v_pk_mul_f32 v[124:125], v[124:125], v[164:165] op_sel_hi:[1,0]
	v_pk_mul_f32 v[168:169], v[122:123], v[164:165] op_sel_hi:[1,0]
	v_pk_mul_f32 v[122:123], v[120:121], v[164:165] op_sel_hi:[1,0]
	v_cvt_pk_bf16_f32 v120, v124, v125
	v_cvt_pk_bf16_f32 v121, v126, v127
	v_pk_mul_f32 v[118:119], v[118:119], v[164:165] op_sel_hi:[1,0]
	v_cvt_pk_bf16_f32 v122, v122, v123
	v_cvt_pk_bf16_f32 v123, v168, v169
	global_store_dwordx4 v[166:167], v[120:123], off nt
	v_pk_mul_f32 v[116:117], v[116:117], v[164:165] op_sel_hi:[1,0]
	s_mov_b32 s0, 0x8000
	v_pk_mul_f32 v[120:121], v[110:111], v[164:165] op_sel_hi:[1,0]
	v_pk_mul_f32 v[110:111], v[108:109], v[164:165] op_sel_hi:[1,0]
	v_cvt_pk_bf16_f32 v108, v116, v117
	v_cvt_pk_bf16_f32 v109, v118, v119
	v_pk_mul_f32 v[96:97], v[96:97], v[162:163] op_sel_hi:[1,0]
	v_cvt_pk_bf16_f32 v110, v110, v111
	v_cvt_pk_bf16_f32 v111, v120, v121
	global_store_dwordx4 v[166:167], v[108:111], off offset:256 nt
	v_pk_mul_f32 v[86:87], v[86:87], v[162:163] op_sel_hi:[1,0]
	v_pk_mul_f32 v[84:85], v[84:85], v[162:163] op_sel_hi:[1,0]
	v_mov_b32_e32 v110, v165
	v_pk_mul_f32 v[112:113], v[112:113], v[110:111] op_sel_hi:[1,0]
	v_pk_mul_f32 v[116:117], v[106:107], v[110:111] op_sel_hi:[1,0]
	v_pk_mul_f32 v[106:107], v[104:105], v[110:111] op_sel_hi:[1,0]
	v_cvt_pk_bf16_f32 v104, v112, v113
	v_add_co_u32_e32 v112, vcc, s0, v166
	v_pk_mul_f32 v[114:115], v[114:115], v[110:111] op_sel_hi:[1,0]
	s_nop 0
	v_addc_co_u32_e32 v113, vcc, 0, v167, vcc
	v_cvt_pk_bf16_f32 v105, v114, v115
	v_cvt_pk_bf16_f32 v106, v106, v107
	v_cvt_pk_bf16_f32 v107, v116, v117
	global_store_dwordx4 v[112:113], v[104:107], off nt
	v_lshl_add_u64 v[108:109], v[166:167], 0, s[56:57]
	v_pk_mul_f32 v[102:103], v[102:103], v[110:111] op_sel_hi:[1,0]
	v_pk_mul_f32 v[104:105], v[94:95], v[110:111] op_sel_hi:[1,0]
	v_pk_mul_f32 v[94:95], v[92:93], v[110:111] op_sel_hi:[1,0]
	v_pk_mul_f32 v[100:101], v[100:101], v[110:111] op_sel_hi:[1,0]
	s_mov_b64 s[0:1], 0x10000
	v_cvt_pk_bf16_f32 v92, v100, v101
	v_cvt_pk_bf16_f32 v93, v102, v103
	v_cvt_pk_bf16_f32 v94, v94, v95
	v_cvt_pk_bf16_f32 v95, v104, v105
	global_store_dwordx4 v[108:109], v[92:95], off offset:256 nt
	v_pk_mul_f32 v[60:61], v[60:61], v[142:143] op_sel_hi:[1,0]
	v_pk_mul_f32 v[62:63], v[62:63], v[142:143] op_sel_hi:[1,0]
	v_lshl_add_u64 v[92:93], v[166:167], 0, s[0:1]
	v_pk_mul_f32 v[94:95], v[98:99], v[162:163] op_sel_hi:[1,0]
	s_mov_b32 s0, 0x10000
	v_pk_mul_f32 v[98:99], v[90:91], v[162:163] op_sel_hi:[1,0]
	v_pk_mul_f32 v[90:91], v[88:89], v[162:163] op_sel_hi:[1,0]
	v_cvt_pk_bf16_f32 v88, v96, v97
	v_cvt_pk_bf16_f32 v89, v94, v95
	v_add_co_u32_e32 v94, vcc, s0, v166
	v_cvt_pk_bf16_f32 v90, v90, v91
	v_cvt_pk_bf16_f32 v91, v98, v99
	s_mov_b64 s[0:1], 0x18000
	s_nop 0
	v_addc_co_u32_e32 v95, vcc, 0, v167, vcc
	global_store_dwordx4 v[94:95], v[88:91], off nt
	v_pk_mul_f32 v[54:55], v[54:55], v[142:143] op_sel_hi:[1,0]
	v_pk_mul_f32 v[52:53], v[52:53], v[142:143] op_sel_hi:[1,0]
	v_pk_mul_f32 v[88:89], v[78:79], v[162:163] op_sel_hi:[1,0]
	v_pk_mul_f32 v[78:79], v[76:77], v[162:163] op_sel_hi:[1,0]
	v_cvt_pk_bf16_f32 v76, v84, v85
	v_cvt_pk_bf16_f32 v77, v86, v87
	v_pk_mul_f32 v[32:33], v[32:33], v[140:141] op_sel_hi:[1,0]
	v_cvt_pk_bf16_f32 v78, v78, v79
	v_cvt_pk_bf16_f32 v79, v88, v89
	global_store_dwordx4 v[92:93], v[76:79], off offset:256 nt
	v_pk_mul_f32 v[22:23], v[22:23], v[140:141] op_sel_hi:[1,0]
	v_pk_mul_f32 v[20:21], v[20:21], v[140:141] op_sel_hi:[1,0]
	v_mov_b32_e32 v78, v163
	v_lshl_add_u64 v[76:77], v[166:167], 0, s[0:1]
	v_pk_mul_f32 v[80:81], v[80:81], v[78:79] op_sel_hi:[1,0]
	s_mov_b32 s0, 0x18000
	v_pk_mul_f32 v[84:85], v[74:75], v[78:79] op_sel_hi:[1,0]
	v_pk_mul_f32 v[74:75], v[72:73], v[78:79] op_sel_hi:[1,0]
	v_cvt_pk_bf16_f32 v72, v80, v81
	v_add_co_u32_e32 v80, vcc, s0, v166
	v_pk_mul_f32 v[82:83], v[82:83], v[78:79] op_sel_hi:[1,0]
	s_nop 0
	v_addc_co_u32_e32 v81, vcc, 0, v167, vcc
	v_cvt_pk_bf16_f32 v73, v82, v83
	v_cvt_pk_bf16_f32 v74, v74, v75
	v_cvt_pk_bf16_f32 v75, v84, v85
; __device__ __forceinline__ u32x4 pack8(const f32x4& a, const f32x4& b) { u32x4 w; w.x = cvt_pk_bf16(a[0], a[1]); w.y = cvt_pk_bf16(a[2], a[3]); w.z = cvt_pk_bf16(b[0], b[1]); w.w = cvt_pk_bf16(b[2], b[3]); return w; }
;     __device__ __forceinline__ void operator()(const f32x4 (&acc)[2][2][4][2], const Unit& u, int ui, int wr, int wc, int fr, int fq) const {
;     ...
;                 for (int m = 0; m < 4; ++m) { const float r = rs[ai][m]; bf16_t* rowp = UG + (size_t)(row0 + ai * HALF + m * 16) * 1024 + u.pn * BM + cw;
; #pragma unroll
;                     for (int bj = 0; bj < 2; ++bj) *(u32x4*)(rowp + bj * HALF) = pack8(acc[ai][bj][m][0] * r, acc[ai][bj][m][1] * r); }
	global_store_dwordx4 v[80:81], v[72:75], off nt
	v_pk_mul_f32 v[70:71], v[70:71], v[78:79] op_sel_hi:[1,0]
	v_pk_mul_f32 v[68:69], v[68:69], v[78:79] op_sel_hi:[1,0]
	v_pk_mul_f32 v[72:73], v[66:67], v[78:79] op_sel_hi:[1,0]
	v_pk_mul_f32 v[66:67], v[64:65], v[78:79] op_sel_hi:[1,0]
	v_cvt_pk_bf16_f32 v64, v68, v69
	v_cvt_pk_bf16_f32 v65, v70, v71
	s_mov_b64 s[0:1], 0x40000
	v_cvt_pk_bf16_f32 v66, v66, v67
	v_cvt_pk_bf16_f32 v67, v72, v73
	global_store_dwordx4 v[76:77], v[64:67], off offset:256 nt
	s_nop 1
	v_pk_mul_f32 v[66:67], v[58:59], v[142:143] op_sel_hi:[1,0]
	v_pk_mul_f32 v[58:59], v[56:57], v[142:143] op_sel_hi:[1,0]
	v_cvt_pk_bf16_f32 v56, v60, v61
	v_add_co_u32_e32 v60, vcc, s87, v166
	v_cvt_pk_bf16_f32 v57, v62, v63
	v_cvt_pk_bf16_f32 v58, v58, v59
	v_cvt_pk_bf16_f32 v59, v66, v67
	v_lshl_add_u64 v[64:65], v[166:167], 0, s[0:1]
	s_nop 0
	v_addc_co_u32_e32 v61, vcc, 0, v167, vcc
	global_store_dwordx4 v[60:61], v[56:59], off nt
	s_mov_b64 s[0:1], 0x48000
	s_nop 0
	v_pk_mul_f32 v[56:57], v[46:47], v[142:143] op_sel_hi:[1,0]
	v_pk_mul_f32 v[46:47], v[44:45], v[142:143] op_sel_hi:[1,0]
	v_cvt_pk_bf16_f32 v44, v52, v53
	v_cvt_pk_bf16_f32 v45, v54, v55
	s_nop 0
	v_cvt_pk_bf16_f32 v46, v46, v47
	v_cvt_pk_bf16_f32 v47, v56, v57
	global_store_dwordx4 v[64:65], v[44:47], off offset:256 nt
	s_nop 1
	v_mov_b32_e32 v46, v143
	v_lshl_add_u64 v[44:45], v[166:167], 0, s[0:1]
	v_pk_mul_f32 v[48:49], v[48:49], v[46:47] op_sel_hi:[1,0]
	s_mov_b32 s0, 0x48000
	v_pk_mul_f32 v[52:53], v[42:43], v[46:47] op_sel_hi:[1,0]
	v_pk_mul_f32 v[42:43], v[40:41], v[46:47] op_sel_hi:[1,0]
	v_cvt_pk_bf16_f32 v40, v48, v49
	v_add_co_u32_e32 v48, vcc, s0, v166
	v_pk_mul_f32 v[50:51], v[50:51], v[46:47] op_sel_hi:[1,0]
	s_nop 0
	v_addc_co_u32_e32 v49, vcc, 0, v167, vcc
	v_cvt_pk_bf16_f32 v41, v50, v51
	v_cvt_pk_bf16_f32 v42, v42, v43
	v_cvt_pk_bf16_f32 v43, v52, v53
	global_store_dwordx4 v[48:49], v[40:43], off nt
	v_pk_mul_f32 v[38:39], v[38:39], v[46:47] op_sel_hi:[1,0]
	v_pk_mul_f32 v[36:37], v[36:37], v[46:47] op_sel_hi:[1,0]
	v_pk_mul_f32 v[40:41], v[30:31], v[46:47] op_sel_hi:[1,0]
	v_pk_mul_f32 v[30:31], v[28:29], v[46:47] op_sel_hi:[1,0]
	v_cvt_pk_bf16_f32 v28, v36, v37
	v_cvt_pk_bf16_f32 v29, v38, v39
	s_mov_b64 s[0:1], 0x50000
	v_cvt_pk_bf16_f32 v30, v30, v31
	v_cvt_pk_bf16_f32 v31, v40, v41
	global_store_dwordx4 v[44:45], v[28:31], off offset:256 nt
	s_nop 1
	v_lshl_add_u64 v[28:29], v[166:167], 0, s[0:1]
	v_pk_mul_f32 v[30:31], v[34:35], v[140:141] op_sel_hi:[1,0]
	s_mov_b32 s0, 0x50000
	v_pk_mul_f32 v[34:35], v[26:27], v[140:141] op_sel_hi:[1,0]
	v_pk_mul_f32 v[26:27], v[24:25], v[140:141] op_sel_hi:[1,0]
	v_cvt_pk_bf16_f32 v24, v32, v33
	v_cvt_pk_bf16_f32 v25, v30, v31
	v_add_co_u32_e32 v30, vcc, s0, v166
	v_cvt_pk_bf16_f32 v26, v26, v27
	v_cvt_pk_bf16_f32 v27, v34, v35
	s_mov_b64 s[0:1], 0x58000
	s_nop 0
	v_addc_co_u32_e32 v31, vcc, 0, v167, vcc
	global_store_dwordx4 v[30:31], v[24:27], off nt
	s_nop 1
	v_pk_mul_f32 v[24:25], v[14:15], v[140:141] op_sel_hi:[1,0]
	v_pk_mul_f32 v[14:15], v[12:13], v[140:141] op_sel_hi:[1,0]
	v_cvt_pk_bf16_f32 v12, v20, v21
	v_cvt_pk_bf16_f32 v13, v22, v23
	s_nop 0
	v_cvt_pk_bf16_f32 v14, v14, v15
	v_cvt_pk_bf16_f32 v15, v24, v25
	global_store_dwordx4 v[28:29], v[12:15], off offset:256 nt
	s_nop 1
	v_mov_b32_e32 v14, v141
	v_lshl_add_u64 v[12:13], v[166:167], 0, s[0:1]
	v_pk_mul_f32 v[16:17], v[16:17], v[14:15] op_sel_hi:[1,0]
	s_mov_b32 s0, 0x58000
	v_pk_mul_f32 v[20:21], v[10:11], v[14:15] op_sel_hi:[1,0]
	v_pk_mul_f32 v[10:11], v[8:9], v[14:15] op_sel_hi:[1,0]
	v_cvt_pk_bf16_f32 v8, v16, v17
	v_add_co_u32_e32 v16, vcc, s0, v166
	v_pk_mul_f32 v[18:19], v[18:19], v[14:15] op_sel_hi:[1,0]
	s_nop 0
	v_addc_co_u32_e32 v17, vcc, 0, v167, vcc
	v_cvt_pk_bf16_f32 v9, v18, v19
	v_cvt_pk_bf16_f32 v10, v10, v11
	v_cvt_pk_bf16_f32 v11, v20, v21
	global_store_dwordx4 v[16:17], v[8:11], off nt
	v_pk_mul_f32 v[6:7], v[6:7], v[14:15] op_sel_hi:[1,0]
	v_pk_mul_f32 v[4:5], v[4:5], v[14:15] op_sel_hi:[1,0]
	v_pk_mul_f32 v[8:9], v[2:3], v[14:15] op_sel_hi:[1,0]
	v_pk_mul_f32 v[2:3], v[0:1], v[14:15] op_sel_hi:[1,0]
	v_cvt_pk_bf16_f32 v0, v4, v5
	v_cvt_pk_bf16_f32 v1, v6, v7
	s_nop 0
	v_cvt_pk_bf16_f32 v2, v2, v3
	v_cvt_pk_bf16_f32 v3, v8, v9
	global_store_dwordx4 v[12:13], v[0:3], off offset:256 nt
	s_andn2_b64 vcc, exec, s[8:9]
	s_mov_b64 s[0:1], -1
	s_cbranch_vccnz .LBB0_788
